# per-cluster s_setprio flips removed from the GEMM main loops; attention V prefetch depth 5; phase-1 wave halves run shiftw/normmod in opposite order
# speedup vs baseline: 1.0623x; 1.0012x over previous
.LBB0_135:
	s_cmp_lt_i32 s58, 2
	s_waitcnt lgkmcnt(0)
	s_cselect_b64 s[24:25], -1, 0
	s_add_u32 s22, s56, 0x28b0000
	s_addc_u32 s23, s57, 0
	s_and_b64 s[0:1], s[24:25], s[0:1]
	s_andn2_b64 vcc, exec, s[0:1]
	s_cbranch_vccnz .LBB0_169
	s_mov_b32 s98, 0
.Lph1_P:
	v_and_b32_e32 v1, 0x3ff, v0
	v_lshlrev_b32_e32 v2, 2, v1
	v_and_b32_e32 v18, 0xfc, v2
	v_lshlrev_b32_e32 v50, 2, v18
	global_load_dwordx4 v[2:5], v50, s[48:49]
	global_load_dwordx4 v[6:9], v50, s[48:49] offset:1024
	global_load_dwordx4 v[10:13], v50, s[48:49] offset:2048
	global_load_dwordx4 v[14:17], v50, s[48:49] offset:3072
	v_bfe_u32 v19, v0, 6, 4
	s_add_u32 s4, s56, 0x2840000
	v_lshl_or_b32 v130, s2, 3, v19
	s_mov_b32 s3, 0x8000
	s_addc_u32 s5, s57, 0
	v_mov_b32_e32 v51, 0
	s_lshl_b32 s28, s33, 3
	v_cmp_gt_i32_e32 vcc, s3, v130
	v_lshlrev_b32_e32 v52, 1, v18
	s_cmp_lg_u32 s98, 0
	s_cbranch_scc1 .Lph1_N
	v_readfirstlane_b32 s99, v0
	s_bfe_u32 s99, s99, 0x40006
	s_cmp_lt_u32 s99, 4
	s_cbranch_scc1 .Lph1_N
	s_mov_b32 s98, 1
	s_mov_b32 s100, s40
	s_mov_b32 s101, s41
	s_waitcnt vmcnt(0)
	s_branch .Lph1_S
.Lph1_again:
	s_mov_b32 s40, s100
	s_mov_b32 s41, s101
	s_branch .Lph1_P
.Lph1_N:
	s_and_saveexec_b64 s[6:7], vcc
	s_cbranch_execz .LBB0_148
	v_mbcnt_lo_u32_b32 v18, -1, 0
	v_mbcnt_hi_u32_b32 v18, -1, v18
	v_and_b32_e32 v20, 64, v18
	v_xor_b32_e32 v19, 1, v18
	v_add_u32_e32 v20, 64, v20
	v_cmp_lt_i32_e32 vcc, v19, v20
	v_mov_b32_e32 v53, v51
	v_lshl_add_u64 v[54:55], s[48:49], 0, v[50:51]
	v_cndmask_b32_e32 v19, v18, v19, vcc
	v_lshlrev_b32_e32 v76, 2, v19
	v_xor_b32_e32 v19, 2, v18
	v_cmp_lt_i32_e32 vcc, v19, v20
	v_lshl_add_u64 v[56:57], s[36:37], 0, v[50:51]
	v_lshl_add_u64 v[58:59], s[4:5], 0, v[50:51]
	v_cndmask_b32_e32 v19, v18, v19, vcc
	v_lshlrev_b32_e32 v77, 2, v19
	v_xor_b32_e32 v19, 4, v18
	v_cmp_lt_i32_e32 vcc, v19, v20
	v_lshl_add_u64 v[60:61], s[22:23], 0, v[52:53]
	s_mov_b64 s[8:9], 0
	v_cndmask_b32_e32 v19, v18, v19, vcc
	v_lshlrev_b32_e32 v78, 2, v19
	v_xor_b32_e32 v19, 8, v18
	v_cmp_lt_i32_e32 vcc, v19, v20
	v_mov_b32_e32 v51, 0x358637bd
	s_movk_i32 s12, 0x1000
	v_cndmask_b32_e32 v19, v18, v19, vcc
	v_lshlrev_b32_e32 v79, 2, v19
	v_xor_b32_e32 v19, 16, v18
	v_cmp_lt_i32_e32 vcc, v19, v20
	s_movk_i32 s13, 0x7fff
	v_mov_b32_e32 v66, v130
	v_cndmask_b32_e32 v19, v18, v19, vcc
	v_lshlrev_b32_e32 v80, 2, v19
	v_xor_b32_e32 v19, 32, v18
	v_cmp_lt_i32_e32 vcc, v19, v20
	s_nop 1
	v_cndmask_b32_e32 v18, v18, v19, vcc
	v_lshlrev_b32_e32 v81, 2, v18
	s_branch .LBB0_139

.LBB0_159:
	s_or_b64 exec, exec, s[6:7]
	s_cmp_eq_u32 s98, 1
	s_cbranch_scc1 .LBB0_169
.Lph1_S:
	s_movk_i32 s0, 0x1600
	v_cmp_gt_i32_e32 vcc, s0, v130
	s_and_saveexec_b64 s[30:31], vcc
	s_cbranch_execz .LBB0_168
	v_and_b32_e32 v1, 63, v1
	v_mov_b32_e32 v133, 0
	v_lshlrev_b32_e32 v132, 5, v1
	v_lshl_add_u64 v[106:107], s[56:57], 0, v[132:133]
	v_add_co_u32_e32 v20, vcc, 0x286d000, v106
	s_mov_b64 s[0:1], 0x286d000
	s_nop 0
	v_addc_co_u32_e32 v21, vcc, 0, v107, vcc
	v_add_co_u32_e32 v36, vcc, 0x2867000, v106
	v_lshl_add_u64 v[18:19], v[106:107], 0, s[0:1]
	s_nop 0
	v_addc_co_u32_e32 v37, vcc, 0, v107, vcc
	v_add_co_u32_e32 v52, vcc, 0x2861000, v106
	s_mov_b64 s[0:1], 0x2867000
	s_nop 0
	v_addc_co_u32_e32 v53, vcc, 0, v107, vcc
	v_add_co_u32_e32 v68, vcc, 0x285b000, v106
	v_lshl_add_u64 v[34:35], v[106:107], 0, s[0:1]
	s_nop 0
	v_addc_co_u32_e32 v69, vcc, 0, v107, vcc
	v_add_co_u32_e32 v84, vcc, 0x2855000, v106
	s_mov_b64 s[0:1], 0x2861000
	s_nop 0
	v_addc_co_u32_e32 v85, vcc, 0, v107, vcc
	v_lshl_add_u64 v[50:51], v[106:107], 0, s[0:1]
	s_mov_b64 s[0:1], 0x285b000
	v_add_co_u32_e32 v100, vcc, 0x284f000, v106
	v_lshl_add_u64 v[66:67], v[106:107], 0, s[0:1]
	s_mov_b64 s[0:1], 0x2855000
	v_addc_co_u32_e32 v101, vcc, 0, v107, vcc
	v_lshl_add_u64 v[82:83], v[106:107], 0, s[0:1]
	s_mov_b64 s[0:1], 0x284f000
	v_add_co_u32_e32 v108, vcc, 0x2849000, v106
	v_lshl_add_u64 v[98:99], v[106:107], 0, s[0:1]
	s_mov_b64 s[0:1], 0x2849000
	v_addc_co_u32_e32 v109, vcc, 0, v107, vcc
	v_lshl_add_u64 v[118:119], v[106:107], 0, s[0:1]
	s_mov_b64 s[0:1], 0x2843000
	v_add_co_u32_e32 v120, vcc, 0x2843000, v106
	v_lshl_add_u64 v[126:127], v[106:107], 0, s[0:1]
	s_nop 0
	v_addc_co_u32_e32 v121, vcc, 0, v107, vcc
	global_load_dwordx4 v[2:5], v[18:19], off offset:2064
	global_load_dwordx4 v[6:9], v[20:21], off
	global_load_dwordx4 v[10:13], v[18:19], off offset:2048
	global_load_dwordx4 v[14:17], v[18:19], off offset:16
	s_nop 0
	global_load_dwordx4 v[18:21], v[34:35], off offset:2064
	global_load_dwordx4 v[22:25], v[36:37], off
	global_load_dwordx4 v[26:29], v[34:35], off offset:2048
	global_load_dwordx4 v[30:33], v[34:35], off offset:16
	s_nop 0
	global_load_dwordx4 v[34:37], v[50:51], off offset:2064
	global_load_dwordx4 v[38:41], v[52:53], off
	global_load_dwordx4 v[42:45], v[50:51], off offset:2048
	global_load_dwordx4 v[46:49], v[50:51], off offset:16
	s_nop 0
	global_load_dwordx4 v[50:53], v[66:67], off offset:2064
	global_load_dwordx4 v[54:57], v[68:69], off
	global_load_dwordx4 v[58:61], v[66:67], off offset:2048
	global_load_dwordx4 v[62:65], v[66:67], off offset:16
	s_nop 0
	global_load_dwordx4 v[66:69], v[82:83], off offset:2064
	global_load_dwordx4 v[70:73], v[84:85], off
	global_load_dwordx4 v[74:77], v[82:83], off offset:2048
	global_load_dwordx4 v[78:81], v[82:83], off offset:16
	s_nop 0
	global_load_dwordx4 v[82:85], v[98:99], off offset:2064
	global_load_dwordx4 v[86:89], v[100:101], off
	global_load_dwordx4 v[90:93], v[98:99], off offset:2048
	global_load_dwordx4 v[94:97], v[98:99], off offset:16
	s_nop 0
	global_load_dwordx4 v[98:101], v[118:119], off offset:2064
	global_load_dwordx4 v[102:105], v[108:109], off
	s_nop 0
	global_load_dwordx4 v[106:109], v[118:119], off offset:2048
	global_load_dwordx4 v[110:113], v[118:119], off offset:16
	global_load_dwordx4 v[114:117], v[120:121], off
	s_nop 0
	global_load_dwordx4 v[118:121], v[126:127], off offset:2064
	global_load_dwordx4 v[122:125], v[126:127], off offset:2048
	s_nop 0
	global_load_dwordx4 v[126:129], v[126:127], off offset:16
	v_mbcnt_lo_u32_b32 v131, -1, 0
	v_mbcnt_hi_u32_b32 v131, -1, v131
	v_and_b32_e32 v134, 64, v131
	v_xor_b32_e32 v132, 1, v131
	v_add_u32_e32 v134, 64, v134
	v_cmp_lt_i32_e32 vcc, v132, v134
	s_mov_b64 s[44:45], 0x1eeb4000
	s_ashr_i32 s29, s28, 31
	v_cndmask_b32_e32 v137, v131, v132, vcc
	v_xor_b32_e32 v132, 2, v131
	v_cmp_lt_i32_e32 vcc, v132, v134
	s_mov_b64 s[46:47], 0x700000
	v_lshlrev_b32_e32 v136, 3, v1
	v_cndmask_b32_e32 v138, v131, v132, vcc
	v_xor_b32_e32 v132, 4, v131
	v_cmp_lt_i32_e32 vcc, v132, v134
	v_cmp_gt_u32_e64 s[0:1], 8, v1
	v_cmp_eq_u32_e64 s[4:5], 1, v1
	v_cndmask_b32_e32 v139, v131, v132, vcc
	v_xor_b32_e32 v132, 8, v131
	v_cmp_lt_i32_e32 vcc, v132, v134
	v_cmp_eq_u32_e64 s[6:7], 2, v1
	v_cmp_eq_u32_e64 s[8:9], 3, v1
	v_cndmask_b32_e32 v140, v131, v132, vcc
	v_xor_b32_e32 v132, 16, v131
	v_cmp_lt_i32_e32 vcc, v132, v134
	v_cmp_eq_u32_e64 s[10:11], 4, v1
	v_cmp_eq_u32_e64 s[12:13], 5, v1
	v_cndmask_b32_e32 v141, v131, v132, vcc
	v_xor_b32_e32 v132, 32, v131
	v_cmp_lt_i32_e32 vcc, v132, v134
	v_cmp_eq_u32_e64 s[14:15], 6, v1
	v_cmp_eq_u32_e64 s[16:17], 7, v1
	v_cndmask_b32_e32 v145, v131, v132, vcc
	v_ashrrev_i32_e32 v131, 31, v130
	v_mul_u32_u24_e32 v132, 0x5800, v1
	v_lshlrev_b64 v[134:135], 11, v[130:131]
	v_lshl_or_b32 v134, v1, 4, v134
	v_lshl_add_u64 v[132:133], v[130:131], 2, v[132:133]
	v_lshl_add_u64 v[132:133], s[56:57], 0, v[132:133]
	v_lshl_add_u64 v[134:135], s[56:57], 0, v[134:135]
	v_lshlrev_b32_e32 v1, 2, v137
	v_lshlrev_b32_e32 v137, 2, v138
	v_lshlrev_b32_e32 v142, 2, v139
	v_lshlrev_b32_e32 v143, 2, v140
	v_lshlrev_b32_e32 v144, 2, v141
	v_lshlrev_b32_e32 v145, 2, v145
	s_lshl_b64 s[38:39], s[28:29], 2
	s_lshl_b64 s[40:41], s[28:29], 11
	s_mov_b64 s[42:43], 0
	s_movk_i32 s3, 0x15ff
	v_mov_b32_e32 v131, v130
	v_lshl_add_u64 v[138:139], v[132:133], 0, s[44:45]
	v_lshl_add_u64 v[140:141], v[134:135], 0, s[46:47]
	global_load_dwordx4 v[188:191], v[140:141], off
	global_load_dwordx4 v[192:195], v[140:141], off offset:1024
	s_waitcnt vmcnt(0)
	s_branch .LBB0_162

.LBB0_168:
	s_or_b64 exec, exec, s[30:31]
	s_cmp_eq_u32 s98, 1
	s_cbranch_scc1 .Lph1_again

.LBB0_238:
	v_add_u32_e32 v142, s85, v180
	v_add_u32_e32 v158, s86, v180
	ds_read_b128 v[130:133], v142
	ds_read_b128 v[134:137], v142 offset:1024
	ds_read_b128 v[138:141], v142 offset:2048
	ds_read_b128 v[142:145], v142 offset:3072
	ds_read_b128 v[146:149], v158
	ds_read_b128 v[172:175], v158 offset:1024
	ds_read_b128 v[176:179], v158 offset:2048
	ds_read_b128 v[210:213], v158 offset:3072
	s_add_u32 s60, s6, 0xfffc0080
	s_addc_u32 s61, s7, -1
	s_cmp_eq_u32 s96, 12
	s_cselect_b32 s69, s9, s61
	s_cselect_b32 s68, s45, s60
	s_cselect_b32 s67, s43, s95
	s_cselect_b32 s66, s93, s94
	v_lshl_add_u64 v[246:247], s[6:7], 0, v[164:165]
	s_add_i32 m0, s41, 0xc000
	ds_read_b128 v[214:217], v204
	ds_read_b128 v[218:221], v204 offset:1024
	ds_read_b128 v[222:225], v204 offset:2048
	ds_read_b128 v[226:229], v204 offset:3072
	ds_read_b128 v[230:233], v204 offset:4096
	ds_read_b128 v[234:237], v204 offset:5120
	ds_read_b128 v[238:241], v204 offset:6144
	ds_read_b128 v[242:245], v204 offset:7168
	global_load_lds_dwordx4 v[246:247], off
	v_lshl_add_u64 v[246:247], s[6:7], 0, v[166:167]
	s_add_i32 m0, s41, 0xe000
	s_nop 0
	global_load_lds_dwordx4 v[246:247], off
	s_waitcnt vmcnt(8)
	s_waitcnt lgkmcnt(0)
	s_barrier
	s_waitcnt lgkmcnt(0)
	v_mfma_f32_16x16x32_bf16 v[126:129], v[130:133], v[214:217], v[126:129]
	v_mfma_f32_16x16x32_bf16 v[122:125], v[138:141], v[214:217], v[122:125]
	v_mfma_f32_16x16x32_bf16 v[118:121], v[130:133], v[222:225], v[118:121]
	v_mfma_f32_16x16x32_bf16 v[110:113], v[138:141], v[222:225], v[110:113]
	v_mfma_f32_16x16x32_bf16 v[102:105], v[130:133], v[230:233], v[102:105]
	v_mfma_f32_16x16x32_bf16 v[94:97], v[138:141], v[230:233], v[94:97]
	v_mfma_f32_16x16x32_bf16 v[86:89], v[130:133], v[238:241], v[86:89]
	v_mfma_f32_16x16x32_bf16 v[78:81], v[138:141], v[238:241], v[78:81]
	v_mfma_f32_16x16x32_bf16 v[126:129], v[134:137], v[218:221], v[126:129]
	v_mfma_f32_16x16x32_bf16 v[122:125], v[142:145], v[218:221], v[122:125]
	v_mfma_f32_16x16x32_bf16 v[118:121], v[134:137], v[226:229], v[118:121]
	v_mfma_f32_16x16x32_bf16 v[110:113], v[142:145], v[226:229], v[110:113]
	v_mfma_f32_16x16x32_bf16 v[102:105], v[134:137], v[234:237], v[102:105]
	v_mfma_f32_16x16x32_bf16 v[94:97], v[142:145], v[234:237], v[94:97]
	v_mfma_f32_16x16x32_bf16 v[86:89], v[134:137], v[242:245], v[86:89]
	v_mfma_f32_16x16x32_bf16 v[78:81], v[142:145], v[242:245], v[78:81]
	v_mfma_f32_16x16x32_bf16 v[114:117], v[146:149], v[214:217], v[114:117]
	v_mfma_f32_16x16x32_bf16 v[106:109], v[176:179], v[214:217], v[106:109]
	v_mfma_f32_16x16x32_bf16 v[98:101], v[146:149], v[222:225], v[98:101]
	v_mfma_f32_16x16x32_bf16 v[90:93], v[176:179], v[222:225], v[90:93]
	v_mfma_f32_16x16x32_bf16 v[82:85], v[146:149], v[230:233], v[82:85]
	v_mfma_f32_16x16x32_bf16 v[74:77], v[176:179], v[230:233], v[74:77]
	v_mfma_f32_16x16x32_bf16 v[70:73], v[146:149], v[238:241], v[70:73]
	v_mfma_f32_16x16x32_bf16 v[66:69], v[176:179], v[238:241], v[66:69]
	v_mfma_f32_16x16x32_bf16 v[114:117], v[172:175], v[218:221], v[114:117]
	v_mfma_f32_16x16x32_bf16 v[106:109], v[210:213], v[218:221], v[106:109]
	v_mfma_f32_16x16x32_bf16 v[98:101], v[172:175], v[226:229], v[98:101]
	v_mfma_f32_16x16x32_bf16 v[90:93], v[210:213], v[226:229], v[90:93]
	v_mfma_f32_16x16x32_bf16 v[82:85], v[172:175], v[234:237], v[82:85]
	v_mfma_f32_16x16x32_bf16 v[74:77], v[210:213], v[234:237], v[74:77]
	v_mfma_f32_16x16x32_bf16 v[70:73], v[172:175], v[242:245], v[70:73]
	v_mfma_f32_16x16x32_bf16 v[66:69], v[210:213], v[242:245], v[66:69]
	s_barrier
	s_add_i32 s60, s85, s3
	v_lshl_add_u64 v[246:247], s[66:67], 0, v[152:153]
	s_mov_b32 m0, s60
	ds_read_b128 v[214:217], v204 offset:16384
	ds_read_b128 v[218:221], v204 offset:17408
	ds_read_b128 v[222:225], v204 offset:18432
	ds_read_b128 v[226:229], v204 offset:19456
	ds_read_b128 v[230:233], v204 offset:20480
	ds_read_b128 v[234:237], v204 offset:21504
	ds_read_b128 v[238:241], v204 offset:22528
	ds_read_b128 v[242:245], v204 offset:23552
	global_load_lds_dwordx4 v[246:247], off
	s_add_i32 m0, s60, 0x2000
	s_add_u32 s60, s66, 0x40000
	v_lshl_add_u64 v[248:249], s[66:67], 0, v[156:157]
	s_addc_u32 s61, s67, 0
	s_add_i32 s97, s86, s3
	global_load_lds_dwordx4 v[248:249], off
	v_lshl_add_u64 v[250:251], s[60:61], 0, v[152:153]
	s_mov_b32 m0, s97
	v_lshl_add_u64 v[252:253], s[68:69], 0, v[154:155]
	global_load_lds_dwordx4 v[250:251], off
	v_lshl_add_u64 v[250:251], s[60:61], 0, v[156:157]
	s_add_i32 m0, s97, 0x2000
	s_nop 0
	global_load_lds_dwordx4 v[250:251], off
	v_lshl_add_u64 v[250:251], s[68:69], 0, v[150:151]
	s_mov_b32 m0, s41
	s_nop 0
	global_load_lds_dwordx4 v[250:251], off
	s_mov_b32 m0, s70
	s_nop 0
	global_load_lds_dwordx4 v[252:253], off
	s_waitcnt vmcnt(8)
	s_waitcnt lgkmcnt(0)
	s_barrier
	s_waitcnt lgkmcnt(0)
	v_mfma_f32_16x16x32_bf16 v[62:65], v[130:133], v[214:217], v[62:65]
	v_mfma_f32_16x16x32_bf16 v[58:61], v[138:141], v[214:217], v[58:61]
	v_mfma_f32_16x16x32_bf16 v[54:57], v[130:133], v[222:225], v[54:57]
	v_mfma_f32_16x16x32_bf16 v[46:49], v[138:141], v[222:225], v[46:49]
	v_mfma_f32_16x16x32_bf16 v[38:41], v[130:133], v[230:233], v[38:41]
	v_mfma_f32_16x16x32_bf16 v[30:33], v[138:141], v[230:233], v[30:33]
	v_mfma_f32_16x16x32_bf16 v[22:25], v[130:133], v[238:241], v[22:25]
	v_mfma_f32_16x16x32_bf16 v[14:17], v[138:141], v[238:241], v[14:17]
	v_mfma_f32_16x16x32_bf16 v[62:65], v[134:137], v[218:221], v[62:65]
	v_mfma_f32_16x16x32_bf16 v[58:61], v[142:145], v[218:221], v[58:61]
	v_mfma_f32_16x16x32_bf16 v[54:57], v[134:137], v[226:229], v[54:57]
	v_mfma_f32_16x16x32_bf16 v[46:49], v[142:145], v[226:229], v[46:49]
	v_mfma_f32_16x16x32_bf16 v[38:41], v[134:137], v[234:237], v[38:41]
	v_mfma_f32_16x16x32_bf16 v[30:33], v[142:145], v[234:237], v[30:33]
	v_mfma_f32_16x16x32_bf16 v[22:25], v[134:137], v[242:245], v[22:25]
	v_mfma_f32_16x16x32_bf16 v[14:17], v[142:145], v[242:245], v[14:17]
	v_mfma_f32_16x16x32_bf16 v[50:53], v[146:149], v[214:217], v[50:53]
	v_mfma_f32_16x16x32_bf16 v[42:45], v[176:179], v[214:217], v[42:45]
	v_mfma_f32_16x16x32_bf16 v[34:37], v[146:149], v[222:225], v[34:37]
	v_mfma_f32_16x16x32_bf16 v[26:29], v[176:179], v[222:225], v[26:29]
	v_mfma_f32_16x16x32_bf16 v[18:21], v[146:149], v[230:233], v[18:21]
	v_mfma_f32_16x16x32_bf16 v[10:13], v[176:179], v[230:233], v[10:13]
	v_mfma_f32_16x16x32_bf16 v[6:9], v[146:149], v[238:241], v[6:9]
	v_mfma_f32_16x16x32_bf16 v[2:5], v[176:179], v[238:241], v[2:5]
	v_mfma_f32_16x16x32_bf16 v[50:53], v[172:175], v[218:221], v[50:53]
	v_mfma_f32_16x16x32_bf16 v[42:45], v[210:213], v[218:221], v[42:45]
	v_mfma_f32_16x16x32_bf16 v[34:37], v[172:175], v[226:229], v[34:37]
	v_mfma_f32_16x16x32_bf16 v[26:29], v[210:213], v[226:229], v[26:29]
	v_mfma_f32_16x16x32_bf16 v[18:21], v[172:175], v[234:237], v[18:21]
	v_mfma_f32_16x16x32_bf16 v[10:13], v[210:213], v[234:237], v[10:13]
	v_mfma_f32_16x16x32_bf16 v[6:9], v[172:175], v[242:245], v[6:9]
	v_mfma_f32_16x16x32_bf16 v[2:5], v[210:213], v[242:245], v[2:5]
	s_barrier
	s_add_i32 s97, 0, 0x18000
	s_add_i32 vcc_lo, 0, 0x1c000
	v_add_u32_e32 v142, s97, v180
	v_add_u32_e32 v158, vcc_lo, v180
	ds_read_b128 v[130:133], v142
	ds_read_b128 v[134:137], v142 offset:1024
	ds_read_b128 v[138:141], v142 offset:2048
	ds_read_b128 v[142:145], v142 offset:3072
	ds_read_b128 v[146:149], v158
	ds_read_b128 v[172:175], v158 offset:1024
	ds_read_b128 v[176:179], v158 offset:2048
	ds_read_b128 v[210:213], v158 offset:3072
	s_add_u32 s60, s68, 0x40000
	s_addc_u32 s61, s69, 0
	s_mov_b32 m0, s71
	v_lshl_add_u64 v[170:171], s[60:61], 0, v[150:151]
	ds_read_b128 v[214:217], v204 offset:32768
	ds_read_b128 v[218:221], v204 offset:33792
	ds_read_b128 v[222:225], v204 offset:34816
	ds_read_b128 v[226:229], v204 offset:35840
	ds_read_b128 v[230:233], v204 offset:36864
	ds_read_b128 v[234:237], v204 offset:37888
	ds_read_b128 v[238:241], v204 offset:38912
	ds_read_b128 v[242:245], v204 offset:39936
	global_load_lds_dwordx4 v[170:171], off
	v_lshl_add_u64 v[170:171], s[60:61], 0, v[154:155]
	s_mov_b32 m0, s72
	s_nop 0
	global_load_lds_dwordx4 v[170:171], off
	s_waitcnt vmcnt(8)
	s_waitcnt lgkmcnt(0)
	s_barrier
	s_waitcnt lgkmcnt(0)
	v_mfma_f32_16x16x32_bf16 v[126:129], v[130:133], v[214:217], v[126:129]
	v_mfma_f32_16x16x32_bf16 v[122:125], v[138:141], v[214:217], v[122:125]
	v_mfma_f32_16x16x32_bf16 v[118:121], v[130:133], v[222:225], v[118:121]
	v_mfma_f32_16x16x32_bf16 v[110:113], v[138:141], v[222:225], v[110:113]
	v_mfma_f32_16x16x32_bf16 v[102:105], v[130:133], v[230:233], v[102:105]
	v_mfma_f32_16x16x32_bf16 v[94:97], v[138:141], v[230:233], v[94:97]
	v_mfma_f32_16x16x32_bf16 v[86:89], v[130:133], v[238:241], v[86:89]
	v_mfma_f32_16x16x32_bf16 v[78:81], v[138:141], v[238:241], v[78:81]
	v_mfma_f32_16x16x32_bf16 v[126:129], v[134:137], v[218:221], v[126:129]
	v_mfma_f32_16x16x32_bf16 v[122:125], v[142:145], v[218:221], v[122:125]
	v_mfma_f32_16x16x32_bf16 v[118:121], v[134:137], v[226:229], v[118:121]
	v_mfma_f32_16x16x32_bf16 v[110:113], v[142:145], v[226:229], v[110:113]
	v_mfma_f32_16x16x32_bf16 v[102:105], v[134:137], v[234:237], v[102:105]
	v_mfma_f32_16x16x32_bf16 v[94:97], v[142:145], v[234:237], v[94:97]
	v_mfma_f32_16x16x32_bf16 v[86:89], v[134:137], v[242:245], v[86:89]
	v_mfma_f32_16x16x32_bf16 v[78:81], v[142:145], v[242:245], v[78:81]
	v_mfma_f32_16x16x32_bf16 v[114:117], v[146:149], v[214:217], v[114:117]
	v_mfma_f32_16x16x32_bf16 v[106:109], v[176:179], v[214:217], v[106:109]
	v_mfma_f32_16x16x32_bf16 v[98:101], v[146:149], v[222:225], v[98:101]
	v_mfma_f32_16x16x32_bf16 v[90:93], v[176:179], v[222:225], v[90:93]
	v_mfma_f32_16x16x32_bf16 v[82:85], v[146:149], v[230:233], v[82:85]
	v_mfma_f32_16x16x32_bf16 v[74:77], v[176:179], v[230:233], v[74:77]
	v_mfma_f32_16x16x32_bf16 v[70:73], v[146:149], v[238:241], v[70:73]
	v_mfma_f32_16x16x32_bf16 v[66:69], v[176:179], v[238:241], v[66:69]
	v_mfma_f32_16x16x32_bf16 v[114:117], v[172:175], v[218:221], v[114:117]
	v_mfma_f32_16x16x32_bf16 v[106:109], v[210:213], v[218:221], v[106:109]
	v_mfma_f32_16x16x32_bf16 v[98:101], v[172:175], v[226:229], v[98:101]
	v_mfma_f32_16x16x32_bf16 v[90:93], v[210:213], v[226:229], v[90:93]
	v_mfma_f32_16x16x32_bf16 v[82:85], v[172:175], v[234:237], v[82:85]
	v_mfma_f32_16x16x32_bf16 v[74:77], v[210:213], v[234:237], v[74:77]
	v_mfma_f32_16x16x32_bf16 v[70:73], v[172:175], v[242:245], v[70:73]
	v_mfma_f32_16x16x32_bf16 v[66:69], v[210:213], v[242:245], v[66:69]
	s_barrier
	s_add_i32 s60, s97, s3
	v_lshl_add_u64 v[170:171], v[246:247], 0, s[28:29]
	s_mov_b32 m0, s60
	ds_read_b128 v[214:217], v204 offset:49152
	ds_read_b128 v[218:221], v204 offset:50176
	ds_read_b128 v[222:225], v204 offset:51200
	ds_read_b128 v[226:229], v204 offset:52224
	ds_read_b128 v[230:233], v204 offset:53248
	ds_read_b128 v[234:237], v204 offset:54272
	ds_read_b128 v[238:241], v204 offset:55296
	ds_read_b128 v[242:245], v204 offset:56320
	global_load_lds_dwordx4 v[170:171], off
	s_add_i32 m0, s60, 0x2000
	s_add_u32 s60, s66, 0x40080
	v_lshl_add_u64 v[170:171], v[248:249], 0, s[28:29]
	s_addc_u32 s61, s67, 0
	s_add_i32 s66, vcc_lo, s3
	global_load_lds_dwordx4 v[170:171], off
	v_lshl_add_u64 v[170:171], s[60:61], 0, v[152:153]
	s_mov_b32 m0, s66
	s_nop 0
	global_load_lds_dwordx4 v[170:171], off
	v_lshl_add_u64 v[170:171], s[60:61], 0, v[156:157]
	s_add_i32 m0, s66, 0x2000
	s_nop 0
	global_load_lds_dwordx4 v[170:171], off
	v_lshl_add_u64 v[170:171], v[250:251], 0, s[28:29]
	s_mov_b32 m0, s76
	s_nop 0
	global_load_lds_dwordx4 v[170:171], off
	v_lshl_add_u64 v[170:171], v[252:253], 0, s[28:29]
	s_mov_b32 m0, s77
	s_nop 0
	global_load_lds_dwordx4 v[170:171], off
	s_waitcnt vmcnt(8)
	s_waitcnt lgkmcnt(0)
	s_barrier
	s_waitcnt lgkmcnt(0)
	v_mfma_f32_16x16x32_bf16 v[62:65], v[130:133], v[214:217], v[62:65]
	v_mfma_f32_16x16x32_bf16 v[58:61], v[138:141], v[214:217], v[58:61]
	v_mfma_f32_16x16x32_bf16 v[54:57], v[130:133], v[222:225], v[54:57]
	v_mfma_f32_16x16x32_bf16 v[46:49], v[138:141], v[222:225], v[46:49]
	v_mfma_f32_16x16x32_bf16 v[38:41], v[130:133], v[230:233], v[38:41]
	v_mfma_f32_16x16x32_bf16 v[30:33], v[138:141], v[230:233], v[30:33]
	v_mfma_f32_16x16x32_bf16 v[22:25], v[130:133], v[238:241], v[22:25]
	v_mfma_f32_16x16x32_bf16 v[14:17], v[138:141], v[238:241], v[14:17]
	v_mfma_f32_16x16x32_bf16 v[62:65], v[134:137], v[218:221], v[62:65]
	v_mfma_f32_16x16x32_bf16 v[58:61], v[142:145], v[218:221], v[58:61]
	v_mfma_f32_16x16x32_bf16 v[54:57], v[134:137], v[226:229], v[54:57]
	v_mfma_f32_16x16x32_bf16 v[46:49], v[142:145], v[226:229], v[46:49]
	v_mfma_f32_16x16x32_bf16 v[38:41], v[134:137], v[234:237], v[38:41]
	v_mfma_f32_16x16x32_bf16 v[30:33], v[142:145], v[234:237], v[30:33]
	v_mfma_f32_16x16x32_bf16 v[22:25], v[134:137], v[242:245], v[22:25]
	v_mfma_f32_16x16x32_bf16 v[14:17], v[142:145], v[242:245], v[14:17]
	v_mfma_f32_16x16x32_bf16 v[50:53], v[146:149], v[214:217], v[50:53]
	v_mfma_f32_16x16x32_bf16 v[42:45], v[176:179], v[214:217], v[42:45]
	v_mfma_f32_16x16x32_bf16 v[34:37], v[146:149], v[222:225], v[34:37]
	v_mfma_f32_16x16x32_bf16 v[26:29], v[176:179], v[222:225], v[26:29]
	v_mfma_f32_16x16x32_bf16 v[18:21], v[146:149], v[230:233], v[18:21]
	v_mfma_f32_16x16x32_bf16 v[10:13], v[176:179], v[230:233], v[10:13]
	v_mfma_f32_16x16x32_bf16 v[6:9], v[146:149], v[238:241], v[6:9]
	v_mfma_f32_16x16x32_bf16 v[2:5], v[176:179], v[238:241], v[2:5]
	v_mfma_f32_16x16x32_bf16 v[50:53], v[172:175], v[218:221], v[50:53]
	v_mfma_f32_16x16x32_bf16 v[42:45], v[210:213], v[218:221], v[42:45]
	v_mfma_f32_16x16x32_bf16 v[34:37], v[172:175], v[226:229], v[34:37]
	v_mfma_f32_16x16x32_bf16 v[26:29], v[210:213], v[226:229], v[26:29]
	v_mfma_f32_16x16x32_bf16 v[18:21], v[172:175], v[234:237], v[18:21]
	v_mfma_f32_16x16x32_bf16 v[10:13], v[210:213], v[234:237], v[10:13]
	v_mfma_f32_16x16x32_bf16 v[6:9], v[172:175], v[242:245], v[6:9]
	v_mfma_f32_16x16x32_bf16 v[2:5], v[210:213], v[242:245], v[2:5]
	s_barrier
	s_add_i32 s96, s96, 2
	s_add_u32 s6, s6, 0x100
	s_addc_u32 s7, s7, 0
	s_add_u32 s94, s94, 0x100
	s_addc_u32 s95, s95, 0
	s_cmp_gt_u32 s96, 13
	s_cbranch_scc0 .LBB0_238
	s_and_b64 vcc, exec, s[30:31]
	s_cbranch_vccnz .LBB0_243
	s_cmp_lg_u32 s8, 5
	s_mov_b64 s[6:7], -1
	s_cbranch_scc1 .LBB0_244

.Lattn_loop:
	s_waitcnt lgkmcnt(6)
	v_mfma_f32_16x16x32_bf16 v[192:195], v[166:169], v[98:101], 0
	v_mfma_f32_16x16x32_bf16 v[208:211], v[166:169], v[114:117], 0
	ds_read_b128 v[166:169], v185 offset:49152
	s_add_i32 m0, s45, 0x18000
	v_add_f32_e32 v130, v66, v67
	v_add_f32_e32 v131, v68, v69
	v_add_f32_e32 v130, v70, v130
	global_load_lds_dwordx4 v152, s[64:65]
	v_mfma_f32_16x16x32_bf16 v[196:199], v[170:173], v[98:101], 0
	v_mfma_f32_16x16x32_bf16 v[212:215], v[170:173], v[114:117], 0
	ds_read_b128 v[170:173], v185 offset:53248
	s_add_i32 m0, s45, 0x1c000
	v_add_f32_e32 v131, v71, v131
	v_add_f32_e32 v130, v72, v130
	v_add_f32_e32 v131, v73, v131
	global_load_lds_dwordx4 v150, s[62:63]
	s_waitcnt lgkmcnt(6)
	v_mfma_f32_16x16x32_bf16 v[200:203], v[174:177], v[98:101], 0
	v_mfma_f32_16x16x32_bf16 v[216:219], v[174:177], v[114:117], 0
	ds_read_b128 v[174:177], v185 offset:57344
	s_add_i32 m0, s45, 0x1a000
	v_add_f32_e32 v130, v74, v130
	v_add_f32_e32 v131, v75, v131
	v_add_f32_e32 v130, v76, v130
	global_load_lds_dwordx4 v153, s[64:65]
	v_mfma_f32_16x16x32_bf16 v[204:207], v[178:181], v[98:101], 0
	v_mfma_f32_16x16x32_bf16 v[220:223], v[178:181], v[114:117], 0
	ds_read_b128 v[178:181], v185 offset:61440
	s_add_i32 m0, s45, 0x1e000
	v_add_f32_e32 v131, v77, v131
	v_add_f32_e32 v130, v78, v130
	v_add_f32_e32 v131, v79, v131
	global_load_lds_dwordx4 v151, s[62:63]
	s_add_u32 s62, s62, 0x4000
	s_addc_u32 s63, s63, 0
	s_add_u32 s64, s64, 0x4000
	s_addc_u32 s65, s65, 0
	s_waitcnt lgkmcnt(6)
	v_mfma_f32_16x16x32_bf16 v[192:195], v[224:227], v[102:105], v[192:195]
	v_mfma_f32_16x16x32_bf16 v[208:211], v[224:227], v[118:121], v[208:211]
	ds_read_b128 v[224:227], v186 offset:49152
	v_add_f32_e32 v130, v80, v130
	v_add_f32_e32 v131, v81, v131
	v_add_f32_e32 v130, v130, v131
	v_mfma_f32_16x16x32_bf16 v[196:199], v[228:231], v[102:105], v[196:199]
	v_mfma_f32_16x16x32_bf16 v[212:215], v[228:231], v[118:121], v[212:215]
	ds_read_b128 v[228:231], v186 offset:53248
	v_add_f32_e32 v165, v165, v130
	v_add_f32_e32 v132, v82, v83
	v_add_f32_e32 v133, v84, v85
	s_waitcnt lgkmcnt(6)
	v_mfma_f32_16x16x32_bf16 v[200:203], v[232:235], v[102:105], v[200:203]
	v_mfma_f32_16x16x32_bf16 v[216:219], v[232:235], v[118:121], v[216:219]
	ds_read_b128 v[232:235], v186 offset:57344
	v_add_f32_e32 v132, v86, v132
	v_add_f32_e32 v133, v87, v133
	v_add_f32_e32 v132, v88, v132
	v_mfma_f32_16x16x32_bf16 v[204:207], v[236:239], v[102:105], v[204:207]
	v_mfma_f32_16x16x32_bf16 v[220:223], v[236:239], v[118:121], v[220:223]
	ds_read_b128 v[236:239], v186 offset:61440
	v_add_f32_e32 v133, v89, v133
	v_add_f32_e32 v132, v90, v132
	v_add_f32_e32 v133, v91, v133
	s_waitcnt lgkmcnt(6)
	v_mfma_f32_16x16x32_bf16 v[192:195], v[166:169], v[106:109], v[192:195]
	v_mfma_f32_16x16x32_bf16 v[208:211], v[166:169], v[122:125], v[208:211]
	ds_read_b64_tr_b16 v[166:167], v240 offset:0
	ds_read_b64_tr_b16 v[168:169], v240 offset:4096
	v_add_f32_e32 v132, v92, v132
	v_add_f32_e32 v133, v93, v133
	v_add_f32_e32 v132, v94, v132
	v_mfma_f32_16x16x32_bf16 v[196:199], v[170:173], v[106:109], v[196:199]
	v_mfma_f32_16x16x32_bf16 v[212:215], v[170:173], v[122:125], v[212:215]
	ds_read_b64_tr_b16 v[170:171], v241 offset:0
	ds_read_b64_tr_b16 v[172:173], v241 offset:4096
	v_add_f32_e32 v133, v95, v133
	v_add_f32_e32 v132, v96, v132
	v_add_f32_e32 v133, v97, v133
	s_waitcnt lgkmcnt(8)
	v_mfma_f32_16x16x32_bf16 v[200:203], v[174:177], v[106:109], v[200:203]
	v_mfma_f32_16x16x32_bf16 v[216:219], v[174:177], v[122:125], v[216:219]
	ds_read_b64_tr_b16 v[174:175], v242 offset:0
	ds_read_b64_tr_b16 v[176:177], v242 offset:4096
	v_add_f32_e32 v132, v132, v133
	v_add_f32_e32 v163, v163, v132
	v_cvt_pk_bf16_f32 v66, v66, v67
	v_mfma_f32_16x16x32_bf16 v[204:207], v[178:181], v[106:109], v[204:207]
	v_mfma_f32_16x16x32_bf16 v[220:223], v[178:181], v[122:125], v[220:223]
	ds_read_b64_tr_b16 v[178:179], v243 offset:0
	ds_read_b64_tr_b16 v[180:181], v243 offset:4096
	v_cvt_pk_bf16_f32 v67, v68, v69
	v_cvt_pk_bf16_f32 v68, v70, v71
	v_cvt_pk_bf16_f32 v69, v72, v73
	s_waitcnt lgkmcnt(10)
	v_mfma_f32_16x16x32_bf16 v[192:195], v[224:227], v[110:113], v[192:195]
	v_mfma_f32_16x16x32_bf16 v[208:211], v[224:227], v[126:129], v[208:211]
	ds_read_b64_tr_b16 v[224:225], v244 offset:0
	ds_read_b64_tr_b16 v[226:227], v244 offset:4096
	v_cvt_pk_bf16_f32 v74, v74, v75
	v_cvt_pk_bf16_f32 v75, v76, v77
	v_cvt_pk_bf16_f32 v76, v78, v79
	v_mfma_f32_16x16x32_bf16 v[196:199], v[228:231], v[110:113], v[196:199]
	v_mfma_f32_16x16x32_bf16 v[212:215], v[228:231], v[126:129], v[212:215]
	v_cvt_pk_bf16_f32 v77, v80, v81
	v_cvt_pk_bf16_f32 v82, v82, v83
	v_cvt_pk_bf16_f32 v83, v84, v85
	s_waitcnt lgkmcnt(10)
	v_mfma_f32_16x16x32_bf16 v[200:203], v[232:235], v[110:113], v[200:203]
	v_mfma_f32_16x16x32_bf16 v[216:219], v[232:235], v[126:129], v[216:219]
	v_cvt_pk_bf16_f32 v84, v86, v87
	v_cvt_pk_bf16_f32 v85, v88, v89
	v_cvt_pk_bf16_f32 v90, v90, v91
	v_mfma_f32_16x16x32_bf16 v[204:207], v[236:239], v[110:113], v[204:207]
	v_mfma_f32_16x16x32_bf16 v[220:223], v[236:239], v[126:129], v[220:223]
	v_cvt_pk_bf16_f32 v91, v92, v93
	v_cvt_pk_bf16_f32 v92, v94, v95
	v_cvt_pk_bf16_f32 v93, v96, v97
	s_waitcnt lgkmcnt(6)
	v_mfma_f32_16x16x32_bf16 v[2:5], v[66:69], v[166:169], v[2:5]
	v_mfma_f32_16x16x32_bf16 v[34:37], v[82:85], v[166:169], v[34:37]
	ds_read_b64_tr_b16 v[228:229], v245 offset:0
	ds_read_b64_tr_b16 v[230:231], v245 offset:4096
	v_mfma_f32_16x16x32_bf16 v[6:9], v[66:69], v[170:173], v[6:9]
	v_mfma_f32_16x16x32_bf16 v[38:41], v[82:85], v[170:173], v[38:41]
	ds_read_b64_tr_b16 v[232:233], v246 offset:0
	ds_read_b64_tr_b16 v[234:235], v246 offset:4096
	s_waitcnt lgkmcnt(6)
	v_mfma_f32_16x16x32_bf16 v[10:13], v[66:69], v[174:177], v[10:13]
	v_mfma_f32_16x16x32_bf16 v[42:45], v[82:85], v[174:177], v[42:45]
	ds_read_b64_tr_b16 v[236:237], v247 offset:0
	ds_read_b64_tr_b16 v[238:239], v247 offset:4096
	v_exp_f32_e32 v192, v192
	v_exp_f32_e32 v193, v193
	v_exp_f32_e32 v194, v194
	v_mfma_f32_16x16x32_bf16 v[14:17], v[66:69], v[178:181], v[14:17]
	v_mfma_f32_16x16x32_bf16 v[46:49], v[82:85], v[178:181], v[46:49]
	ds_read_b64_tr_b16 v[166:167], v240 offset:8192
	ds_read_b64_tr_b16 v[168:169], v240 offset:12288
	v_exp_f32_e32 v195, v195
	v_exp_f32_e32 v208, v208
	s_waitcnt lgkmcnt(6)
	v_mfma_f32_16x16x32_bf16 v[18:21], v[66:69], v[224:227], v[18:21]
	v_mfma_f32_16x16x32_bf16 v[50:53], v[82:85], v[224:227], v[50:53]
	ds_read_b64_tr_b16 v[170:171], v241 offset:8192
	ds_read_b64_tr_b16 v[172:173], v241 offset:12288
	v_exp_f32_e32 v209, v209
	v_exp_f32_e32 v210, v210
	v_mfma_f32_16x16x32_bf16 v[22:25], v[66:69], v[228:231], v[22:25]
	v_mfma_f32_16x16x32_bf16 v[54:57], v[82:85], v[228:231], v[54:57]
	ds_read_b64_tr_b16 v[174:175], v242 offset:8192
	ds_read_b64_tr_b16 v[176:177], v242 offset:12288
	v_exp_f32_e32 v211, v211
	v_exp_f32_e32 v196, v196
	v_exp_f32_e32 v197, v197
	s_waitcnt lgkmcnt(6)
	v_mfma_f32_16x16x32_bf16 v[26:29], v[66:69], v[232:235], v[26:29]
	v_mfma_f32_16x16x32_bf16 v[58:61], v[82:85], v[232:235], v[58:61]
	ds_read_b64_tr_b16 v[178:179], v243 offset:8192
	ds_read_b64_tr_b16 v[180:181], v243 offset:12288
	v_exp_f32_e32 v198, v198
	v_exp_f32_e32 v199, v199
	v_mfma_f32_16x16x32_bf16 v[30:33], v[66:69], v[236:239], v[30:33]
	v_mfma_f32_16x16x32_bf16 v[62:65], v[82:85], v[236:239], v[62:65]
	ds_read_b64_tr_b16 v[224:225], v244 offset:8192
	ds_read_b64_tr_b16 v[226:227], v244 offset:12288
	v_exp_f32_e32 v212, v212
	v_exp_f32_e32 v213, v213
	s_waitcnt lgkmcnt(6)
	v_mfma_f32_16x16x32_bf16 v[2:5], v[74:77], v[166:169], v[2:5]
	v_mfma_f32_16x16x32_bf16 v[34:37], v[90:93], v[166:169], v[34:37]
	ds_read_b64_tr_b16 v[228:229], v245 offset:8192
	ds_read_b64_tr_b16 v[230:231], v245 offset:12288
	ds_read_b128 v[166:169], v187 offset:16384
	v_exp_f32_e32 v214, v214
	v_exp_f32_e32 v215, v215
	v_mfma_f32_16x16x32_bf16 v[6:9], v[74:77], v[170:173], v[6:9]
	v_mfma_f32_16x16x32_bf16 v[38:41], v[90:93], v[170:173], v[38:41]
	ds_read_b64_tr_b16 v[232:233], v246 offset:8192
	ds_read_b64_tr_b16 v[234:235], v246 offset:12288
	ds_read_b128 v[170:173], v187 offset:20480
	v_exp_f32_e32 v200, v200
	v_exp_f32_e32 v201, v201
	v_exp_f32_e32 v202, v202
	s_waitcnt lgkmcnt(8)
	v_mfma_f32_16x16x32_bf16 v[10:13], v[74:77], v[174:177], v[10:13]
	v_mfma_f32_16x16x32_bf16 v[42:45], v[90:93], v[174:177], v[42:45]
	ds_read_b64_tr_b16 v[236:237], v247 offset:8192
	ds_read_b64_tr_b16 v[238:239], v247 offset:12288
	ds_read_b128 v[174:177], v187 offset:24576
	v_exp_f32_e32 v203, v203
	v_exp_f32_e32 v216, v216
	v_mfma_f32_16x16x32_bf16 v[14:17], v[74:77], v[178:181], v[14:17]
	v_mfma_f32_16x16x32_bf16 v[46:49], v[90:93], v[178:181], v[46:49]
	ds_read_b128 v[178:181], v187 offset:28672
	v_exp_f32_e32 v217, v217
	v_exp_f32_e32 v218, v218
	s_waitcnt lgkmcnt(8)
	v_mfma_f32_16x16x32_bf16 v[18:21], v[74:77], v[224:227], v[18:21]
	v_mfma_f32_16x16x32_bf16 v[50:53], v[90:93], v[224:227], v[50:53]
	ds_read_b128 v[224:227], v188 offset:16384
	v_exp_f32_e32 v219, v219
	v_exp_f32_e32 v204, v204
	v_exp_f32_e32 v205, v205
	v_mfma_f32_16x16x32_bf16 v[22:25], v[74:77], v[228:231], v[22:25]
	v_mfma_f32_16x16x32_bf16 v[54:57], v[90:93], v[228:231], v[54:57]
	ds_read_b128 v[228:231], v188 offset:20480
	v_exp_f32_e32 v206, v206
	v_exp_f32_e32 v207, v207
	s_waitcnt lgkmcnt(4)
	v_mfma_f32_16x16x32_bf16 v[26:29], v[74:77], v[232:235], v[26:29]
	v_mfma_f32_16x16x32_bf16 v[58:61], v[90:93], v[232:235], v[58:61]
	ds_read_b128 v[232:235], v188 offset:24576
	v_exp_f32_e32 v220, v220
	v_exp_f32_e32 v221, v221
	v_mfma_f32_16x16x32_bf16 v[30:33], v[74:77], v[236:239], v[30:33]
	v_mfma_f32_16x16x32_bf16 v[62:65], v[90:93], v[236:239], v[62:65]
	ds_read_b128 v[236:239], v188 offset:28672
	v_exp_f32_e32 v222, v222
	v_exp_f32_e32 v223, v223
	s_waitcnt vmcnt(0)
	s_barrier
	v_mfma_f32_16x16x32_bf16 v[66:69], v[166:169], v[98:101], 0
	v_mfma_f32_16x16x32_bf16 v[82:85], v[166:169], v[114:117], 0
	ds_read_b128 v[166:169], v189 offset:16384
	s_add_i32 m0, s45, 0x0
	v_add_f32_e32 v130, v192, v193
	v_add_f32_e32 v131, v194, v195
	v_add_f32_e32 v130, v196, v130
	global_load_lds_dwordx4 v152, s[64:65]
	v_mfma_f32_16x16x32_bf16 v[70:73], v[170:173], v[98:101], 0
	v_mfma_f32_16x16x32_bf16 v[86:89], v[170:173], v[114:117], 0
	ds_read_b128 v[170:173], v189 offset:20480
	s_add_i32 m0, s45, 0x4000
	v_add_f32_e32 v131, v197, v131
	v_add_f32_e32 v130, v198, v130
	v_add_f32_e32 v131, v199, v131
	global_load_lds_dwordx4 v150, s[62:63]
	s_waitcnt lgkmcnt(6)
	v_mfma_f32_16x16x32_bf16 v[74:77], v[174:177], v[98:101], 0
	v_mfma_f32_16x16x32_bf16 v[90:93], v[174:177], v[114:117], 0
	ds_read_b128 v[174:177], v189 offset:24576
	s_add_i32 m0, s45, 0x2000
	v_add_f32_e32 v130, v200, v130
	v_add_f32_e32 v131, v201, v131
	v_add_f32_e32 v130, v202, v130
	global_load_lds_dwordx4 v153, s[64:65]
	v_mfma_f32_16x16x32_bf16 v[78:81], v[178:181], v[98:101], 0
	v_mfma_f32_16x16x32_bf16 v[94:97], v[178:181], v[114:117], 0
	ds_read_b128 v[178:181], v189 offset:28672
	s_add_i32 m0, s45, 0x6000
	v_add_f32_e32 v131, v203, v131
	v_add_f32_e32 v130, v204, v130
	v_add_f32_e32 v131, v205, v131
	global_load_lds_dwordx4 v151, s[62:63]
	s_add_u32 s62, s62, 0x4000
	s_addc_u32 s63, s63, 0
	s_add_u32 s64, s64, 0x4000
	s_addc_u32 s65, s65, 0
	s_waitcnt lgkmcnt(6)
	v_mfma_f32_16x16x32_bf16 v[66:69], v[224:227], v[102:105], v[66:69]
	v_mfma_f32_16x16x32_bf16 v[82:85], v[224:227], v[118:121], v[82:85]
	ds_read_b128 v[224:227], v190 offset:16384
	v_add_f32_e32 v130, v206, v130
	v_add_f32_e32 v131, v207, v131
	v_add_f32_e32 v130, v130, v131
	v_mfma_f32_16x16x32_bf16 v[70:73], v[228:231], v[102:105], v[70:73]
	v_mfma_f32_16x16x32_bf16 v[86:89], v[228:231], v[118:121], v[86:89]
	ds_read_b128 v[228:231], v190 offset:20480
	v_add_f32_e32 v165, v165, v130
	v_add_f32_e32 v132, v208, v209
	v_add_f32_e32 v133, v210, v211
	s_waitcnt lgkmcnt(6)
	v_mfma_f32_16x16x32_bf16 v[74:77], v[232:235], v[102:105], v[74:77]
	v_mfma_f32_16x16x32_bf16 v[90:93], v[232:235], v[118:121], v[90:93]
	ds_read_b128 v[232:235], v190 offset:24576
	v_add_f32_e32 v132, v212, v132
	v_add_f32_e32 v133, v213, v133
	v_add_f32_e32 v132, v214, v132
	v_mfma_f32_16x16x32_bf16 v[78:81], v[236:239], v[102:105], v[78:81]
	v_mfma_f32_16x16x32_bf16 v[94:97], v[236:239], v[118:121], v[94:97]
	ds_read_b128 v[236:239], v190 offset:28672
	v_add_f32_e32 v133, v215, v133
	v_add_f32_e32 v132, v216, v132
	v_add_f32_e32 v133, v217, v133
	s_waitcnt lgkmcnt(6)
	v_mfma_f32_16x16x32_bf16 v[66:69], v[166:169], v[106:109], v[66:69]
	v_mfma_f32_16x16x32_bf16 v[82:85], v[166:169], v[122:125], v[82:85]
	ds_read_b64_tr_b16 v[166:167], v240 offset:32768
	ds_read_b64_tr_b16 v[168:169], v240 offset:36864
	v_add_f32_e32 v132, v218, v132
	v_add_f32_e32 v133, v219, v133
	v_add_f32_e32 v132, v220, v132
	v_mfma_f32_16x16x32_bf16 v[70:73], v[170:173], v[106:109], v[70:73]
	v_mfma_f32_16x16x32_bf16 v[86:89], v[170:173], v[122:125], v[86:89]
	ds_read_b64_tr_b16 v[170:171], v241 offset:32768
	ds_read_b64_tr_b16 v[172:173], v241 offset:36864
	v_add_f32_e32 v133, v221, v133
	v_add_f32_e32 v132, v222, v132
	v_add_f32_e32 v133, v223, v133
	s_waitcnt lgkmcnt(8)
	v_mfma_f32_16x16x32_bf16 v[74:77], v[174:177], v[106:109], v[74:77]
	v_mfma_f32_16x16x32_bf16 v[90:93], v[174:177], v[122:125], v[90:93]
	ds_read_b64_tr_b16 v[174:175], v242 offset:32768
	ds_read_b64_tr_b16 v[176:177], v242 offset:36864
	v_add_f32_e32 v132, v132, v133
	v_add_f32_e32 v163, v163, v132
	v_cvt_pk_bf16_f32 v192, v192, v193
	v_mfma_f32_16x16x32_bf16 v[78:81], v[178:181], v[106:109], v[78:81]
	v_mfma_f32_16x16x32_bf16 v[94:97], v[178:181], v[122:125], v[94:97]
	ds_read_b64_tr_b16 v[178:179], v243 offset:32768
	ds_read_b64_tr_b16 v[180:181], v243 offset:36864
	v_cvt_pk_bf16_f32 v193, v194, v195
	v_cvt_pk_bf16_f32 v194, v196, v197
	v_cvt_pk_bf16_f32 v195, v198, v199
	s_waitcnt lgkmcnt(10)
	v_mfma_f32_16x16x32_bf16 v[66:69], v[224:227], v[110:113], v[66:69]
	v_mfma_f32_16x16x32_bf16 v[82:85], v[224:227], v[126:129], v[82:85]
	ds_read_b64_tr_b16 v[224:225], v244 offset:32768
	ds_read_b64_tr_b16 v[226:227], v244 offset:36864
	v_cvt_pk_bf16_f32 v200, v200, v201
	v_cvt_pk_bf16_f32 v201, v202, v203
	v_cvt_pk_bf16_f32 v202, v204, v205
	v_mfma_f32_16x16x32_bf16 v[70:73], v[228:231], v[110:113], v[70:73]
	v_mfma_f32_16x16x32_bf16 v[86:89], v[228:231], v[126:129], v[86:89]
	v_cvt_pk_bf16_f32 v203, v206, v207
	v_cvt_pk_bf16_f32 v208, v208, v209
	v_cvt_pk_bf16_f32 v209, v210, v211
	s_waitcnt lgkmcnt(10)
	v_mfma_f32_16x16x32_bf16 v[74:77], v[232:235], v[110:113], v[74:77]
	v_mfma_f32_16x16x32_bf16 v[90:93], v[232:235], v[126:129], v[90:93]
	v_cvt_pk_bf16_f32 v210, v212, v213
	v_cvt_pk_bf16_f32 v211, v214, v215
	v_cvt_pk_bf16_f32 v216, v216, v217
	v_mfma_f32_16x16x32_bf16 v[78:81], v[236:239], v[110:113], v[78:81]
	v_mfma_f32_16x16x32_bf16 v[94:97], v[236:239], v[126:129], v[94:97]
	v_cvt_pk_bf16_f32 v217, v218, v219
	v_cvt_pk_bf16_f32 v218, v220, v221
	v_cvt_pk_bf16_f32 v219, v222, v223
	s_waitcnt lgkmcnt(6)
	v_mfma_f32_16x16x32_bf16 v[2:5], v[192:195], v[166:169], v[2:5]
	v_mfma_f32_16x16x32_bf16 v[34:37], v[208:211], v[166:169], v[34:37]
	ds_read_b64_tr_b16 v[228:229], v245 offset:32768
	ds_read_b64_tr_b16 v[230:231], v245 offset:36864
	v_mfma_f32_16x16x32_bf16 v[6:9], v[192:195], v[170:173], v[6:9]
	v_mfma_f32_16x16x32_bf16 v[38:41], v[208:211], v[170:173], v[38:41]
	ds_read_b64_tr_b16 v[232:233], v246 offset:32768
	ds_read_b64_tr_b16 v[234:235], v246 offset:36864
	s_waitcnt lgkmcnt(6)
	v_mfma_f32_16x16x32_bf16 v[10:13], v[192:195], v[174:177], v[10:13]
	v_mfma_f32_16x16x32_bf16 v[42:45], v[208:211], v[174:177], v[42:45]
	ds_read_b64_tr_b16 v[236:237], v247 offset:32768
	ds_read_b64_tr_b16 v[238:239], v247 offset:36864
	v_exp_f32_e32 v66, v66
	v_exp_f32_e32 v67, v67
	v_exp_f32_e32 v68, v68
	v_mfma_f32_16x16x32_bf16 v[14:17], v[192:195], v[178:181], v[14:17]
	v_mfma_f32_16x16x32_bf16 v[46:49], v[208:211], v[178:181], v[46:49]
	ds_read_b64_tr_b16 v[166:167], v240 offset:40960
	ds_read_b64_tr_b16 v[168:169], v240 offset:45056
	v_exp_f32_e32 v69, v69
	v_exp_f32_e32 v82, v82
	s_waitcnt lgkmcnt(6)
	v_mfma_f32_16x16x32_bf16 v[18:21], v[192:195], v[224:227], v[18:21]
	v_mfma_f32_16x16x32_bf16 v[50:53], v[208:211], v[224:227], v[50:53]
	ds_read_b64_tr_b16 v[170:171], v241 offset:40960
	ds_read_b64_tr_b16 v[172:173], v241 offset:45056
	v_exp_f32_e32 v83, v83
	v_exp_f32_e32 v84, v84
	v_mfma_f32_16x16x32_bf16 v[22:25], v[192:195], v[228:231], v[22:25]
	v_mfma_f32_16x16x32_bf16 v[54:57], v[208:211], v[228:231], v[54:57]
	ds_read_b64_tr_b16 v[174:175], v242 offset:40960
	ds_read_b64_tr_b16 v[176:177], v242 offset:45056
	v_exp_f32_e32 v85, v85
	v_exp_f32_e32 v70, v70
	v_exp_f32_e32 v71, v71
	s_waitcnt lgkmcnt(6)
	v_mfma_f32_16x16x32_bf16 v[26:29], v[192:195], v[232:235], v[26:29]
	v_mfma_f32_16x16x32_bf16 v[58:61], v[208:211], v[232:235], v[58:61]
	ds_read_b64_tr_b16 v[178:179], v243 offset:40960
	ds_read_b64_tr_b16 v[180:181], v243 offset:45056
	v_exp_f32_e32 v72, v72
	v_exp_f32_e32 v73, v73
	v_mfma_f32_16x16x32_bf16 v[30:33], v[192:195], v[236:239], v[30:33]
	v_mfma_f32_16x16x32_bf16 v[62:65], v[208:211], v[236:239], v[62:65]
	ds_read_b64_tr_b16 v[224:225], v244 offset:40960
	ds_read_b64_tr_b16 v[226:227], v244 offset:45056
	v_exp_f32_e32 v86, v86
	v_exp_f32_e32 v87, v87
	s_waitcnt lgkmcnt(6)
	v_mfma_f32_16x16x32_bf16 v[2:5], v[200:203], v[166:169], v[2:5]
	v_mfma_f32_16x16x32_bf16 v[34:37], v[216:219], v[166:169], v[34:37]
	ds_read_b64_tr_b16 v[228:229], v245 offset:40960
	ds_read_b64_tr_b16 v[230:231], v245 offset:45056
	ds_read_b128 v[166:169], v187 offset:49152
	v_exp_f32_e32 v88, v88
	v_exp_f32_e32 v89, v89
	v_mfma_f32_16x16x32_bf16 v[6:9], v[200:203], v[170:173], v[6:9]
	v_mfma_f32_16x16x32_bf16 v[38:41], v[216:219], v[170:173], v[38:41]
	ds_read_b64_tr_b16 v[232:233], v246 offset:40960
	ds_read_b64_tr_b16 v[234:235], v246 offset:45056
	ds_read_b128 v[170:173], v187 offset:53248
	v_exp_f32_e32 v74, v74
	v_exp_f32_e32 v75, v75
	v_exp_f32_e32 v76, v76
	s_waitcnt lgkmcnt(8)
	v_mfma_f32_16x16x32_bf16 v[10:13], v[200:203], v[174:177], v[10:13]
	v_mfma_f32_16x16x32_bf16 v[42:45], v[216:219], v[174:177], v[42:45]
	ds_read_b64_tr_b16 v[236:237], v247 offset:40960
	ds_read_b64_tr_b16 v[238:239], v247 offset:45056
	ds_read_b128 v[174:177], v187 offset:57344
	v_exp_f32_e32 v77, v77
	v_exp_f32_e32 v90, v90
	v_mfma_f32_16x16x32_bf16 v[14:17], v[200:203], v[178:181], v[14:17]
	v_mfma_f32_16x16x32_bf16 v[46:49], v[216:219], v[178:181], v[46:49]
	ds_read_b128 v[178:181], v187 offset:61440
	v_exp_f32_e32 v91, v91
	v_exp_f32_e32 v92, v92
	s_waitcnt lgkmcnt(8)
	v_mfma_f32_16x16x32_bf16 v[18:21], v[200:203], v[224:227], v[18:21]
	v_mfma_f32_16x16x32_bf16 v[50:53], v[216:219], v[224:227], v[50:53]
	ds_read_b128 v[224:227], v188 offset:49152
	v_exp_f32_e32 v93, v93
	v_exp_f32_e32 v78, v78
	v_exp_f32_e32 v79, v79
	v_mfma_f32_16x16x32_bf16 v[22:25], v[200:203], v[228:231], v[22:25]
	v_mfma_f32_16x16x32_bf16 v[54:57], v[216:219], v[228:231], v[54:57]
	ds_read_b128 v[228:231], v188 offset:53248
	v_exp_f32_e32 v80, v80
	v_exp_f32_e32 v81, v81
	s_waitcnt lgkmcnt(4)
	v_mfma_f32_16x16x32_bf16 v[26:29], v[200:203], v[232:235], v[26:29]
	v_mfma_f32_16x16x32_bf16 v[58:61], v[216:219], v[232:235], v[58:61]
	ds_read_b128 v[232:235], v188 offset:57344
	v_exp_f32_e32 v94, v94
	v_exp_f32_e32 v95, v95
	v_mfma_f32_16x16x32_bf16 v[30:33], v[200:203], v[236:239], v[30:33]
	v_mfma_f32_16x16x32_bf16 v[62:65], v[216:219], v[236:239], v[62:65]
	ds_read_b128 v[236:239], v188 offset:61440
	v_exp_f32_e32 v96, v96
	v_exp_f32_e32 v97, v97
	s_waitcnt vmcnt(0)
	s_barrier
	v_mfma_f32_16x16x32_bf16 v[192:195], v[166:169], v[98:101], 0
	v_mfma_f32_16x16x32_bf16 v[208:211], v[166:169], v[114:117], 0
	ds_read_b128 v[166:169], v189 offset:49152
	s_add_i32 m0, s45, 0x8000
	v_add_f32_e32 v130, v66, v67
	v_add_f32_e32 v131, v68, v69
	v_add_f32_e32 v130, v70, v130
	global_load_lds_dwordx4 v152, s[64:65]
	v_mfma_f32_16x16x32_bf16 v[196:199], v[170:173], v[98:101], 0
	v_mfma_f32_16x16x32_bf16 v[212:215], v[170:173], v[114:117], 0
	ds_read_b128 v[170:173], v189 offset:53248
	s_add_i32 m0, s45, 0xc000
	v_add_f32_e32 v131, v71, v131
	v_add_f32_e32 v130, v72, v130
	v_add_f32_e32 v131, v73, v131
	global_load_lds_dwordx4 v150, s[62:63]
	s_waitcnt lgkmcnt(6)
	v_mfma_f32_16x16x32_bf16 v[200:203], v[174:177], v[98:101], 0
	v_mfma_f32_16x16x32_bf16 v[216:219], v[174:177], v[114:117], 0
	ds_read_b128 v[174:177], v189 offset:57344
	s_add_i32 m0, s45, 0xa000
	v_add_f32_e32 v130, v74, v130
	v_add_f32_e32 v131, v75, v131
	v_add_f32_e32 v130, v76, v130
	global_load_lds_dwordx4 v153, s[64:65]
	v_mfma_f32_16x16x32_bf16 v[204:207], v[178:181], v[98:101], 0
	v_mfma_f32_16x16x32_bf16 v[220:223], v[178:181], v[114:117], 0
	ds_read_b128 v[178:181], v189 offset:61440
	s_add_i32 m0, s45, 0xe000
	v_add_f32_e32 v131, v77, v131
	v_add_f32_e32 v130, v78, v130
	v_add_f32_e32 v131, v79, v131
	global_load_lds_dwordx4 v151, s[62:63]
	s_add_u32 s62, s62, 0x4000
	s_addc_u32 s63, s63, 0
	s_add_u32 s64, s64, 0x4000
	s_addc_u32 s65, s65, 0
	s_waitcnt lgkmcnt(6)
	v_mfma_f32_16x16x32_bf16 v[192:195], v[224:227], v[102:105], v[192:195]
	v_mfma_f32_16x16x32_bf16 v[208:211], v[224:227], v[118:121], v[208:211]
	ds_read_b128 v[224:227], v190 offset:49152
	v_add_f32_e32 v130, v80, v130
	v_add_f32_e32 v131, v81, v131
	v_add_f32_e32 v130, v130, v131
	v_mfma_f32_16x16x32_bf16 v[196:199], v[228:231], v[102:105], v[196:199]
	v_mfma_f32_16x16x32_bf16 v[212:215], v[228:231], v[118:121], v[212:215]
	ds_read_b128 v[228:231], v190 offset:53248
	v_add_f32_e32 v165, v165, v130
	v_add_f32_e32 v132, v82, v83
	v_add_f32_e32 v133, v84, v85
	s_waitcnt lgkmcnt(6)
	v_mfma_f32_16x16x32_bf16 v[200:203], v[232:235], v[102:105], v[200:203]
	v_mfma_f32_16x16x32_bf16 v[216:219], v[232:235], v[118:121], v[216:219]
	ds_read_b128 v[232:235], v190 offset:57344
	v_add_f32_e32 v132, v86, v132
	v_add_f32_e32 v133, v87, v133
	v_add_f32_e32 v132, v88, v132
	v_mfma_f32_16x16x32_bf16 v[204:207], v[236:239], v[102:105], v[204:207]
	v_mfma_f32_16x16x32_bf16 v[220:223], v[236:239], v[118:121], v[220:223]
	ds_read_b128 v[236:239], v190 offset:61440
	v_add_f32_e32 v133, v89, v133
	v_add_f32_e32 v132, v90, v132
	v_add_f32_e32 v133, v91, v133
	s_waitcnt lgkmcnt(6)
	v_mfma_f32_16x16x32_bf16 v[192:195], v[166:169], v[106:109], v[192:195]
	v_mfma_f32_16x16x32_bf16 v[208:211], v[166:169], v[122:125], v[208:211]
	ds_read_b64_tr_b16 v[166:167], v142 offset:0
	ds_read_b64_tr_b16 v[168:169], v142 offset:4096
	v_add_f32_e32 v132, v92, v132
	v_add_f32_e32 v133, v93, v133
	v_add_f32_e32 v132, v94, v132
	v_mfma_f32_16x16x32_bf16 v[196:199], v[170:173], v[106:109], v[196:199]
	v_mfma_f32_16x16x32_bf16 v[212:215], v[170:173], v[122:125], v[212:215]
	ds_read_b64_tr_b16 v[170:171], v143 offset:0
	ds_read_b64_tr_b16 v[172:173], v143 offset:4096
	v_add_f32_e32 v133, v95, v133
	v_add_f32_e32 v132, v96, v132
	v_add_f32_e32 v133, v97, v133
	s_waitcnt lgkmcnt(8)
	v_mfma_f32_16x16x32_bf16 v[200:203], v[174:177], v[106:109], v[200:203]
	v_mfma_f32_16x16x32_bf16 v[216:219], v[174:177], v[122:125], v[216:219]
	ds_read_b64_tr_b16 v[174:175], v144 offset:0
	ds_read_b64_tr_b16 v[176:177], v144 offset:4096
	v_add_f32_e32 v132, v132, v133
	v_add_f32_e32 v163, v163, v132
	v_cvt_pk_bf16_f32 v66, v66, v67
	v_mfma_f32_16x16x32_bf16 v[204:207], v[178:181], v[106:109], v[204:207]
	v_mfma_f32_16x16x32_bf16 v[220:223], v[178:181], v[122:125], v[220:223]
	ds_read_b64_tr_b16 v[178:179], v145 offset:0
	ds_read_b64_tr_b16 v[180:181], v145 offset:4096
	v_cvt_pk_bf16_f32 v67, v68, v69
	v_cvt_pk_bf16_f32 v68, v70, v71
	v_cvt_pk_bf16_f32 v69, v72, v73
	s_waitcnt lgkmcnt(10)
	v_mfma_f32_16x16x32_bf16 v[192:195], v[224:227], v[110:113], v[192:195]
	v_mfma_f32_16x16x32_bf16 v[208:211], v[224:227], v[126:129], v[208:211]
	ds_read_b64_tr_b16 v[224:225], v146 offset:0
	ds_read_b64_tr_b16 v[226:227], v146 offset:4096
	v_cvt_pk_bf16_f32 v74, v74, v75
	v_cvt_pk_bf16_f32 v75, v76, v77
	v_cvt_pk_bf16_f32 v76, v78, v79
	v_mfma_f32_16x16x32_bf16 v[196:199], v[228:231], v[110:113], v[196:199]
	v_mfma_f32_16x16x32_bf16 v[212:215], v[228:231], v[126:129], v[212:215]
	v_cvt_pk_bf16_f32 v77, v80, v81
	v_cvt_pk_bf16_f32 v82, v82, v83
	v_cvt_pk_bf16_f32 v83, v84, v85
	s_waitcnt lgkmcnt(10)
	v_mfma_f32_16x16x32_bf16 v[200:203], v[232:235], v[110:113], v[200:203]
	v_mfma_f32_16x16x32_bf16 v[216:219], v[232:235], v[126:129], v[216:219]
	v_cvt_pk_bf16_f32 v84, v86, v87
	v_cvt_pk_bf16_f32 v85, v88, v89
	v_cvt_pk_bf16_f32 v90, v90, v91
	v_mfma_f32_16x16x32_bf16 v[204:207], v[236:239], v[110:113], v[204:207]
	v_mfma_f32_16x16x32_bf16 v[220:223], v[236:239], v[126:129], v[220:223]
	v_cvt_pk_bf16_f32 v91, v92, v93
	v_cvt_pk_bf16_f32 v92, v94, v95
	v_cvt_pk_bf16_f32 v93, v96, v97
	s_waitcnt lgkmcnt(6)
	v_mfma_f32_16x16x32_bf16 v[2:5], v[66:69], v[166:169], v[2:5]
	v_mfma_f32_16x16x32_bf16 v[34:37], v[82:85], v[166:169], v[34:37]
	ds_read_b64_tr_b16 v[228:229], v147 offset:0
	ds_read_b64_tr_b16 v[230:231], v147 offset:4096
	v_mfma_f32_16x16x32_bf16 v[6:9], v[66:69], v[170:173], v[6:9]
	v_mfma_f32_16x16x32_bf16 v[38:41], v[82:85], v[170:173], v[38:41]
	ds_read_b64_tr_b16 v[232:233], v148 offset:0
	ds_read_b64_tr_b16 v[234:235], v148 offset:4096
	s_waitcnt lgkmcnt(6)
	v_mfma_f32_16x16x32_bf16 v[10:13], v[66:69], v[174:177], v[10:13]
	v_mfma_f32_16x16x32_bf16 v[42:45], v[82:85], v[174:177], v[42:45]
	ds_read_b64_tr_b16 v[236:237], v149 offset:0
	ds_read_b64_tr_b16 v[238:239], v149 offset:4096
	v_exp_f32_e32 v192, v192
	v_exp_f32_e32 v193, v193
	v_exp_f32_e32 v194, v194
	v_mfma_f32_16x16x32_bf16 v[14:17], v[66:69], v[178:181], v[14:17]
	v_mfma_f32_16x16x32_bf16 v[46:49], v[82:85], v[178:181], v[46:49]
	ds_read_b64_tr_b16 v[166:167], v142 offset:8192
	ds_read_b64_tr_b16 v[168:169], v142 offset:12288
	v_exp_f32_e32 v195, v195
	v_exp_f32_e32 v208, v208
	s_waitcnt lgkmcnt(6)
	v_mfma_f32_16x16x32_bf16 v[18:21], v[66:69], v[224:227], v[18:21]
	v_mfma_f32_16x16x32_bf16 v[50:53], v[82:85], v[224:227], v[50:53]
	ds_read_b64_tr_b16 v[170:171], v143 offset:8192
	ds_read_b64_tr_b16 v[172:173], v143 offset:12288
	v_exp_f32_e32 v209, v209
	v_exp_f32_e32 v210, v210
	v_mfma_f32_16x16x32_bf16 v[22:25], v[66:69], v[228:231], v[22:25]
	v_mfma_f32_16x16x32_bf16 v[54:57], v[82:85], v[228:231], v[54:57]
	ds_read_b64_tr_b16 v[174:175], v144 offset:8192
	ds_read_b64_tr_b16 v[176:177], v144 offset:12288
	v_exp_f32_e32 v211, v211
	v_exp_f32_e32 v196, v196
	v_exp_f32_e32 v197, v197
	s_waitcnt lgkmcnt(6)
	v_mfma_f32_16x16x32_bf16 v[26:29], v[66:69], v[232:235], v[26:29]
	v_mfma_f32_16x16x32_bf16 v[58:61], v[82:85], v[232:235], v[58:61]
	ds_read_b64_tr_b16 v[178:179], v145 offset:8192
	ds_read_b64_tr_b16 v[180:181], v145 offset:12288
	v_exp_f32_e32 v198, v198
	v_exp_f32_e32 v199, v199
	v_mfma_f32_16x16x32_bf16 v[30:33], v[66:69], v[236:239], v[30:33]
	v_mfma_f32_16x16x32_bf16 v[62:65], v[82:85], v[236:239], v[62:65]
	ds_read_b64_tr_b16 v[224:225], v146 offset:8192
	ds_read_b64_tr_b16 v[226:227], v146 offset:12288
	v_exp_f32_e32 v212, v212
	v_exp_f32_e32 v213, v213
	s_waitcnt lgkmcnt(6)
	v_mfma_f32_16x16x32_bf16 v[2:5], v[74:77], v[166:169], v[2:5]
	v_mfma_f32_16x16x32_bf16 v[34:37], v[90:93], v[166:169], v[34:37]
	ds_read_b64_tr_b16 v[228:229], v147 offset:8192
	ds_read_b64_tr_b16 v[230:231], v147 offset:12288
	ds_read_b128 v[166:169], v183 offset:16384
	v_exp_f32_e32 v214, v214
	v_exp_f32_e32 v215, v215
	v_mfma_f32_16x16x32_bf16 v[6:9], v[74:77], v[170:173], v[6:9]
	v_mfma_f32_16x16x32_bf16 v[38:41], v[90:93], v[170:173], v[38:41]
	ds_read_b64_tr_b16 v[232:233], v148 offset:8192
	ds_read_b64_tr_b16 v[234:235], v148 offset:12288
	ds_read_b128 v[170:173], v183 offset:20480
	v_exp_f32_e32 v200, v200
	v_exp_f32_e32 v201, v201
	v_exp_f32_e32 v202, v202
	s_waitcnt lgkmcnt(8)
	v_mfma_f32_16x16x32_bf16 v[10:13], v[74:77], v[174:177], v[10:13]
	v_mfma_f32_16x16x32_bf16 v[42:45], v[90:93], v[174:177], v[42:45]
	ds_read_b64_tr_b16 v[236:237], v149 offset:8192
	ds_read_b64_tr_b16 v[238:239], v149 offset:12288
	ds_read_b128 v[174:177], v183 offset:24576
	v_exp_f32_e32 v203, v203
	v_exp_f32_e32 v216, v216
	v_mfma_f32_16x16x32_bf16 v[14:17], v[74:77], v[178:181], v[14:17]
	v_mfma_f32_16x16x32_bf16 v[46:49], v[90:93], v[178:181], v[46:49]
	ds_read_b128 v[178:181], v183 offset:28672
	v_exp_f32_e32 v217, v217
	v_exp_f32_e32 v218, v218
	s_waitcnt lgkmcnt(8)
	v_mfma_f32_16x16x32_bf16 v[18:21], v[74:77], v[224:227], v[18:21]
	v_mfma_f32_16x16x32_bf16 v[50:53], v[90:93], v[224:227], v[50:53]
	ds_read_b128 v[224:227], v184 offset:16384
	v_exp_f32_e32 v219, v219
	v_exp_f32_e32 v204, v204
	v_exp_f32_e32 v205, v205
	v_mfma_f32_16x16x32_bf16 v[22:25], v[74:77], v[228:231], v[22:25]
	v_mfma_f32_16x16x32_bf16 v[54:57], v[90:93], v[228:231], v[54:57]
	ds_read_b128 v[228:231], v184 offset:20480
	v_exp_f32_e32 v206, v206
	v_exp_f32_e32 v207, v207
	s_waitcnt lgkmcnt(4)
	v_mfma_f32_16x16x32_bf16 v[26:29], v[74:77], v[232:235], v[26:29]
	v_mfma_f32_16x16x32_bf16 v[58:61], v[90:93], v[232:235], v[58:61]
	ds_read_b128 v[232:235], v184 offset:24576
	v_exp_f32_e32 v220, v220
	v_exp_f32_e32 v221, v221
	v_mfma_f32_16x16x32_bf16 v[30:33], v[74:77], v[236:239], v[30:33]
	v_mfma_f32_16x16x32_bf16 v[62:65], v[90:93], v[236:239], v[62:65]
	ds_read_b128 v[236:239], v184 offset:28672
	v_exp_f32_e32 v222, v222
	v_exp_f32_e32 v223, v223
	s_waitcnt vmcnt(0)
	s_barrier
	v_mfma_f32_16x16x32_bf16 v[66:69], v[166:169], v[98:101], 0
	v_mfma_f32_16x16x32_bf16 v[82:85], v[166:169], v[114:117], 0
	ds_read_b128 v[166:169], v185 offset:16384
	s_add_i32 m0, s45, 0x10000
	v_add_f32_e32 v130, v192, v193
	v_add_f32_e32 v131, v194, v195
	v_add_f32_e32 v130, v196, v130
	global_load_lds_dwordx4 v152, s[64:65]
	v_mfma_f32_16x16x32_bf16 v[70:73], v[170:173], v[98:101], 0
	v_mfma_f32_16x16x32_bf16 v[86:89], v[170:173], v[114:117], 0
	ds_read_b128 v[170:173], v185 offset:20480
	s_add_i32 m0, s45, 0x14000
	v_add_f32_e32 v131, v197, v131
	v_add_f32_e32 v130, v198, v130
	v_add_f32_e32 v131, v199, v131
	global_load_lds_dwordx4 v150, s[62:63]
	s_waitcnt lgkmcnt(6)
	v_mfma_f32_16x16x32_bf16 v[74:77], v[174:177], v[98:101], 0
	v_mfma_f32_16x16x32_bf16 v[90:93], v[174:177], v[114:117], 0
	ds_read_b128 v[174:177], v185 offset:24576
	s_add_i32 m0, s45, 0x12000
	v_add_f32_e32 v130, v200, v130
	v_add_f32_e32 v131, v201, v131
	v_add_f32_e32 v130, v202, v130
	global_load_lds_dwordx4 v153, s[64:65]
	v_mfma_f32_16x16x32_bf16 v[78:81], v[178:181], v[98:101], 0
	v_mfma_f32_16x16x32_bf16 v[94:97], v[178:181], v[114:117], 0
	ds_read_b128 v[178:181], v185 offset:28672
	s_add_i32 m0, s45, 0x16000
	v_add_f32_e32 v131, v203, v131
	v_add_f32_e32 v130, v204, v130
	v_add_f32_e32 v131, v205, v131
	global_load_lds_dwordx4 v151, s[62:63]
	s_add_u32 s62, s62, 0x4000
	s_addc_u32 s63, s63, 0
	s_add_u32 s64, s64, 0x4000
	s_addc_u32 s65, s65, 0
	s_waitcnt lgkmcnt(6)
	v_mfma_f32_16x16x32_bf16 v[66:69], v[224:227], v[102:105], v[66:69]
	v_mfma_f32_16x16x32_bf16 v[82:85], v[224:227], v[118:121], v[82:85]
	ds_read_b128 v[224:227], v186 offset:16384
	v_add_f32_e32 v130, v206, v130
	v_add_f32_e32 v131, v207, v131
	v_add_f32_e32 v130, v130, v131
	v_mfma_f32_16x16x32_bf16 v[70:73], v[228:231], v[102:105], v[70:73]
	v_mfma_f32_16x16x32_bf16 v[86:89], v[228:231], v[118:121], v[86:89]
	ds_read_b128 v[228:231], v186 offset:20480
	v_add_f32_e32 v165, v165, v130
	v_add_f32_e32 v132, v208, v209
	v_add_f32_e32 v133, v210, v211
	s_waitcnt lgkmcnt(6)
	v_mfma_f32_16x16x32_bf16 v[74:77], v[232:235], v[102:105], v[74:77]
	v_mfma_f32_16x16x32_bf16 v[90:93], v[232:235], v[118:121], v[90:93]
	ds_read_b128 v[232:235], v186 offset:24576
	v_add_f32_e32 v132, v212, v132
	v_add_f32_e32 v133, v213, v133
	v_add_f32_e32 v132, v214, v132
	v_mfma_f32_16x16x32_bf16 v[78:81], v[236:239], v[102:105], v[78:81]
	v_mfma_f32_16x16x32_bf16 v[94:97], v[236:239], v[118:121], v[94:97]
	ds_read_b128 v[236:239], v186 offset:28672
	v_add_f32_e32 v133, v215, v133
	v_add_f32_e32 v132, v216, v132
	v_add_f32_e32 v133, v217, v133
	s_waitcnt lgkmcnt(6)
	v_mfma_f32_16x16x32_bf16 v[66:69], v[166:169], v[106:109], v[66:69]
	v_mfma_f32_16x16x32_bf16 v[82:85], v[166:169], v[122:125], v[82:85]
	ds_read_b64_tr_b16 v[166:167], v142 offset:32768
	ds_read_b64_tr_b16 v[168:169], v142 offset:36864
	v_add_f32_e32 v132, v218, v132
	v_add_f32_e32 v133, v219, v133
	v_add_f32_e32 v132, v220, v132
	v_mfma_f32_16x16x32_bf16 v[70:73], v[170:173], v[106:109], v[70:73]
	v_mfma_f32_16x16x32_bf16 v[86:89], v[170:173], v[122:125], v[86:89]
	ds_read_b64_tr_b16 v[170:171], v143 offset:32768
	ds_read_b64_tr_b16 v[172:173], v143 offset:36864
	v_add_f32_e32 v133, v221, v133
	v_add_f32_e32 v132, v222, v132
	v_add_f32_e32 v133, v223, v133
	s_waitcnt lgkmcnt(8)
	v_mfma_f32_16x16x32_bf16 v[74:77], v[174:177], v[106:109], v[74:77]
	v_mfma_f32_16x16x32_bf16 v[90:93], v[174:177], v[122:125], v[90:93]
	ds_read_b64_tr_b16 v[174:175], v144 offset:32768
	ds_read_b64_tr_b16 v[176:177], v144 offset:36864
	v_add_f32_e32 v132, v132, v133
	v_add_f32_e32 v163, v163, v132
	v_cvt_pk_bf16_f32 v192, v192, v193
	v_mfma_f32_16x16x32_bf16 v[78:81], v[178:181], v[106:109], v[78:81]
	v_mfma_f32_16x16x32_bf16 v[94:97], v[178:181], v[122:125], v[94:97]
	ds_read_b64_tr_b16 v[178:179], v145 offset:32768
	ds_read_b64_tr_b16 v[180:181], v145 offset:36864
	v_cvt_pk_bf16_f32 v193, v194, v195
	v_cvt_pk_bf16_f32 v194, v196, v197
	v_cvt_pk_bf16_f32 v195, v198, v199
	s_waitcnt lgkmcnt(10)
	v_mfma_f32_16x16x32_bf16 v[66:69], v[224:227], v[110:113], v[66:69]
	v_mfma_f32_16x16x32_bf16 v[82:85], v[224:227], v[126:129], v[82:85]
	ds_read_b64_tr_b16 v[224:225], v146 offset:32768
	ds_read_b64_tr_b16 v[226:227], v146 offset:36864
	v_cvt_pk_bf16_f32 v200, v200, v201
	v_cvt_pk_bf16_f32 v201, v202, v203
	v_cvt_pk_bf16_f32 v202, v204, v205
	v_mfma_f32_16x16x32_bf16 v[70:73], v[228:231], v[110:113], v[70:73]
	v_mfma_f32_16x16x32_bf16 v[86:89], v[228:231], v[126:129], v[86:89]
	v_cvt_pk_bf16_f32 v203, v206, v207
	v_cvt_pk_bf16_f32 v208, v208, v209
	v_cvt_pk_bf16_f32 v209, v210, v211
	s_waitcnt lgkmcnt(10)
	v_mfma_f32_16x16x32_bf16 v[74:77], v[232:235], v[110:113], v[74:77]
	v_mfma_f32_16x16x32_bf16 v[90:93], v[232:235], v[126:129], v[90:93]
	v_cvt_pk_bf16_f32 v210, v212, v213
	v_cvt_pk_bf16_f32 v211, v214, v215
	v_cvt_pk_bf16_f32 v216, v216, v217
	v_mfma_f32_16x16x32_bf16 v[78:81], v[236:239], v[110:113], v[78:81]
	v_mfma_f32_16x16x32_bf16 v[94:97], v[236:239], v[126:129], v[94:97]
	v_cvt_pk_bf16_f32 v217, v218, v219
	v_cvt_pk_bf16_f32 v218, v220, v221
	v_cvt_pk_bf16_f32 v219, v222, v223
	s_waitcnt lgkmcnt(6)
	v_mfma_f32_16x16x32_bf16 v[2:5], v[192:195], v[166:169], v[2:5]
	v_mfma_f32_16x16x32_bf16 v[34:37], v[208:211], v[166:169], v[34:37]
	ds_read_b64_tr_b16 v[228:229], v147 offset:32768
	ds_read_b64_tr_b16 v[230:231], v147 offset:36864
	v_mfma_f32_16x16x32_bf16 v[6:9], v[192:195], v[170:173], v[6:9]
	v_mfma_f32_16x16x32_bf16 v[38:41], v[208:211], v[170:173], v[38:41]
	ds_read_b64_tr_b16 v[232:233], v148 offset:32768
	ds_read_b64_tr_b16 v[234:235], v148 offset:36864
	s_waitcnt lgkmcnt(6)
	v_mfma_f32_16x16x32_bf16 v[10:13], v[192:195], v[174:177], v[10:13]
	v_mfma_f32_16x16x32_bf16 v[42:45], v[208:211], v[174:177], v[42:45]
	ds_read_b64_tr_b16 v[236:237], v149 offset:32768
	ds_read_b64_tr_b16 v[238:239], v149 offset:36864
	v_exp_f32_e32 v66, v66
	v_exp_f32_e32 v67, v67
	v_exp_f32_e32 v68, v68
	v_mfma_f32_16x16x32_bf16 v[14:17], v[192:195], v[178:181], v[14:17]
	v_mfma_f32_16x16x32_bf16 v[46:49], v[208:211], v[178:181], v[46:49]
	ds_read_b64_tr_b16 v[166:167], v142 offset:40960
	ds_read_b64_tr_b16 v[168:169], v142 offset:45056
	v_exp_f32_e32 v69, v69
	v_exp_f32_e32 v82, v82
	s_waitcnt lgkmcnt(6)
	v_mfma_f32_16x16x32_bf16 v[18:21], v[192:195], v[224:227], v[18:21]
	v_mfma_f32_16x16x32_bf16 v[50:53], v[208:211], v[224:227], v[50:53]
	ds_read_b64_tr_b16 v[170:171], v143 offset:40960
	ds_read_b64_tr_b16 v[172:173], v143 offset:45056
	v_exp_f32_e32 v83, v83
	v_exp_f32_e32 v84, v84
	v_mfma_f32_16x16x32_bf16 v[22:25], v[192:195], v[228:231], v[22:25]
	v_mfma_f32_16x16x32_bf16 v[54:57], v[208:211], v[228:231], v[54:57]
	ds_read_b64_tr_b16 v[174:175], v144 offset:40960
	ds_read_b64_tr_b16 v[176:177], v144 offset:45056
	v_exp_f32_e32 v85, v85
	v_exp_f32_e32 v70, v70
	v_exp_f32_e32 v71, v71
	s_waitcnt lgkmcnt(6)
	v_mfma_f32_16x16x32_bf16 v[26:29], v[192:195], v[232:235], v[26:29]
	v_mfma_f32_16x16x32_bf16 v[58:61], v[208:211], v[232:235], v[58:61]
	ds_read_b64_tr_b16 v[178:179], v145 offset:40960
	ds_read_b64_tr_b16 v[180:181], v145 offset:45056
	v_exp_f32_e32 v72, v72
	v_exp_f32_e32 v73, v73
	v_mfma_f32_16x16x32_bf16 v[30:33], v[192:195], v[236:239], v[30:33]
	v_mfma_f32_16x16x32_bf16 v[62:65], v[208:211], v[236:239], v[62:65]
	ds_read_b64_tr_b16 v[224:225], v146 offset:40960
	ds_read_b64_tr_b16 v[226:227], v146 offset:45056
	v_exp_f32_e32 v86, v86
	v_exp_f32_e32 v87, v87
	s_waitcnt lgkmcnt(6)
	v_mfma_f32_16x16x32_bf16 v[2:5], v[200:203], v[166:169], v[2:5]
	v_mfma_f32_16x16x32_bf16 v[34:37], v[216:219], v[166:169], v[34:37]
	ds_read_b64_tr_b16 v[228:229], v147 offset:40960
	ds_read_b64_tr_b16 v[230:231], v147 offset:45056
	ds_read_b128 v[166:169], v183 offset:49152
	v_exp_f32_e32 v88, v88
	v_exp_f32_e32 v89, v89
	v_mfma_f32_16x16x32_bf16 v[6:9], v[200:203], v[170:173], v[6:9]
	v_mfma_f32_16x16x32_bf16 v[38:41], v[216:219], v[170:173], v[38:41]
	ds_read_b64_tr_b16 v[232:233], v148 offset:40960
	ds_read_b64_tr_b16 v[234:235], v148 offset:45056
	ds_read_b128 v[170:173], v183 offset:53248
	v_exp_f32_e32 v74, v74
	v_exp_f32_e32 v75, v75
	v_exp_f32_e32 v76, v76
	s_waitcnt lgkmcnt(8)
	v_mfma_f32_16x16x32_bf16 v[10:13], v[200:203], v[174:177], v[10:13]
	v_mfma_f32_16x16x32_bf16 v[42:45], v[216:219], v[174:177], v[42:45]
	ds_read_b64_tr_b16 v[236:237], v149 offset:40960
	ds_read_b64_tr_b16 v[238:239], v149 offset:45056
	ds_read_b128 v[174:177], v183 offset:57344
	v_exp_f32_e32 v77, v77
	v_exp_f32_e32 v90, v90
	v_mfma_f32_16x16x32_bf16 v[14:17], v[200:203], v[178:181], v[14:17]
	v_mfma_f32_16x16x32_bf16 v[46:49], v[216:219], v[178:181], v[46:49]
	ds_read_b128 v[178:181], v183 offset:61440
	v_exp_f32_e32 v91, v91
	v_exp_f32_e32 v92, v92
	s_waitcnt lgkmcnt(8)
	v_mfma_f32_16x16x32_bf16 v[18:21], v[200:203], v[224:227], v[18:21]
	v_mfma_f32_16x16x32_bf16 v[50:53], v[216:219], v[224:227], v[50:53]
	ds_read_b128 v[224:227], v184 offset:49152
	v_exp_f32_e32 v93, v93
	v_exp_f32_e32 v78, v78
	v_exp_f32_e32 v79, v79
	v_mfma_f32_16x16x32_bf16 v[22:25], v[200:203], v[228:231], v[22:25]
	v_mfma_f32_16x16x32_bf16 v[54:57], v[216:219], v[228:231], v[54:57]
	ds_read_b128 v[228:231], v184 offset:53248
	v_exp_f32_e32 v80, v80
	v_exp_f32_e32 v81, v81
	s_waitcnt lgkmcnt(4)
	v_mfma_f32_16x16x32_bf16 v[26:29], v[200:203], v[232:235], v[26:29]
	v_mfma_f32_16x16x32_bf16 v[58:61], v[216:219], v[232:235], v[58:61]
	ds_read_b128 v[232:235], v184 offset:57344
	v_exp_f32_e32 v94, v94
	v_exp_f32_e32 v95, v95
	v_mfma_f32_16x16x32_bf16 v[30:33], v[200:203], v[236:239], v[30:33]
	v_mfma_f32_16x16x32_bf16 v[62:65], v[216:219], v[236:239], v[62:65]
	ds_read_b128 v[236:239], v184 offset:61440
	v_exp_f32_e32 v96, v96
	v_exp_f32_e32 v97, v97
	s_waitcnt vmcnt(0)
	s_barrier
	s_sub_u32 s66, s66, 1
	s_cmp_lg_u32 s66, 0
	s_cbranch_scc1 .Lattn_loop
	v_mfma_f32_16x16x32_bf16 v[192:195], v[166:169], v[98:101], 0
	v_mfma_f32_16x16x32_bf16 v[208:211], v[166:169], v[114:117], 0
	ds_read_b128 v[166:169], v185 offset:49152
	s_add_i32 m0, s45, 0x18000
	v_add_f32_e32 v130, v66, v67
	v_add_f32_e32 v131, v68, v69
	v_add_f32_e32 v130, v70, v130
	global_load_lds_dwordx4 v152, s[64:65]
	v_mfma_f32_16x16x32_bf16 v[196:199], v[170:173], v[98:101], 0
	v_mfma_f32_16x16x32_bf16 v[212:215], v[170:173], v[114:117], 0
	ds_read_b128 v[170:173], v185 offset:53248
	s_add_i32 m0, s45, 0x1c000
	v_add_f32_e32 v131, v71, v131
	v_add_f32_e32 v130, v72, v130
	v_add_f32_e32 v131, v73, v131
	global_load_lds_dwordx4 v150, s[62:63]
	s_waitcnt lgkmcnt(6)
	v_mfma_f32_16x16x32_bf16 v[200:203], v[174:177], v[98:101], 0
	v_mfma_f32_16x16x32_bf16 v[216:219], v[174:177], v[114:117], 0
	ds_read_b128 v[174:177], v185 offset:57344
	s_add_i32 m0, s45, 0x1a000
	v_add_f32_e32 v130, v74, v130
	v_add_f32_e32 v131, v75, v131
	v_add_f32_e32 v130, v76, v130
	global_load_lds_dwordx4 v153, s[64:65]
	v_mfma_f32_16x16x32_bf16 v[204:207], v[178:181], v[98:101], 0
	v_mfma_f32_16x16x32_bf16 v[220:223], v[178:181], v[114:117], 0
	ds_read_b128 v[178:181], v185 offset:61440
	s_add_i32 m0, s45, 0x1e000
	v_add_f32_e32 v131, v77, v131
	v_add_f32_e32 v130, v78, v130
	v_add_f32_e32 v131, v79, v131
	global_load_lds_dwordx4 v151, s[62:63]
	s_add_u32 s62, s62, 0x4000
	s_addc_u32 s63, s63, 0
	s_add_u32 s64, s64, 0x4000
	s_addc_u32 s65, s65, 0
	s_waitcnt lgkmcnt(6)
	v_mfma_f32_16x16x32_bf16 v[192:195], v[224:227], v[102:105], v[192:195]
	v_mfma_f32_16x16x32_bf16 v[208:211], v[224:227], v[118:121], v[208:211]
	ds_read_b128 v[224:227], v186 offset:49152
	v_add_f32_e32 v130, v80, v130
	v_add_f32_e32 v131, v81, v131
	v_add_f32_e32 v130, v130, v131
	v_mfma_f32_16x16x32_bf16 v[196:199], v[228:231], v[102:105], v[196:199]
	v_mfma_f32_16x16x32_bf16 v[212:215], v[228:231], v[118:121], v[212:215]
	ds_read_b128 v[228:231], v186 offset:53248
	v_add_f32_e32 v165, v165, v130
	v_add_f32_e32 v132, v82, v83
	v_add_f32_e32 v133, v84, v85
	s_waitcnt lgkmcnt(6)
	v_mfma_f32_16x16x32_bf16 v[200:203], v[232:235], v[102:105], v[200:203]
	v_mfma_f32_16x16x32_bf16 v[216:219], v[232:235], v[118:121], v[216:219]
	ds_read_b128 v[232:235], v186 offset:57344
	v_add_f32_e32 v132, v86, v132
	v_add_f32_e32 v133, v87, v133
	v_add_f32_e32 v132, v88, v132
	v_mfma_f32_16x16x32_bf16 v[204:207], v[236:239], v[102:105], v[204:207]
	v_mfma_f32_16x16x32_bf16 v[220:223], v[236:239], v[118:121], v[220:223]
	ds_read_b128 v[236:239], v186 offset:61440
	v_add_f32_e32 v133, v89, v133
	v_add_f32_e32 v132, v90, v132
	v_add_f32_e32 v133, v91, v133
	s_waitcnt lgkmcnt(6)
	v_mfma_f32_16x16x32_bf16 v[192:195], v[166:169], v[106:109], v[192:195]
	v_mfma_f32_16x16x32_bf16 v[208:211], v[166:169], v[122:125], v[208:211]
	ds_read_b64_tr_b16 v[166:167], v240 offset:0
	ds_read_b64_tr_b16 v[168:169], v240 offset:4096
	v_add_f32_e32 v132, v92, v132
	v_add_f32_e32 v133, v93, v133
	v_add_f32_e32 v132, v94, v132
	v_mfma_f32_16x16x32_bf16 v[196:199], v[170:173], v[106:109], v[196:199]
	v_mfma_f32_16x16x32_bf16 v[212:215], v[170:173], v[122:125], v[212:215]
	ds_read_b64_tr_b16 v[170:171], v241 offset:0
	ds_read_b64_tr_b16 v[172:173], v241 offset:4096
	v_add_f32_e32 v133, v95, v133
	v_add_f32_e32 v132, v96, v132
	v_add_f32_e32 v133, v97, v133
	s_waitcnt lgkmcnt(8)
	v_mfma_f32_16x16x32_bf16 v[200:203], v[174:177], v[106:109], v[200:203]
	v_mfma_f32_16x16x32_bf16 v[216:219], v[174:177], v[122:125], v[216:219]
	ds_read_b64_tr_b16 v[174:175], v242 offset:0
	ds_read_b64_tr_b16 v[176:177], v242 offset:4096
	v_add_f32_e32 v132, v132, v133
	v_add_f32_e32 v163, v163, v132
	v_cvt_pk_bf16_f32 v66, v66, v67
	v_mfma_f32_16x16x32_bf16 v[204:207], v[178:181], v[106:109], v[204:207]
	v_mfma_f32_16x16x32_bf16 v[220:223], v[178:181], v[122:125], v[220:223]
	ds_read_b64_tr_b16 v[178:179], v243 offset:0
	ds_read_b64_tr_b16 v[180:181], v243 offset:4096
	v_cvt_pk_bf16_f32 v67, v68, v69
	v_cvt_pk_bf16_f32 v68, v70, v71
	v_cvt_pk_bf16_f32 v69, v72, v73
	s_waitcnt lgkmcnt(10)
	v_mfma_f32_16x16x32_bf16 v[192:195], v[224:227], v[110:113], v[192:195]
	v_mfma_f32_16x16x32_bf16 v[208:211], v[224:227], v[126:129], v[208:211]
	ds_read_b64_tr_b16 v[224:225], v244 offset:0
	ds_read_b64_tr_b16 v[226:227], v244 offset:4096
	v_cvt_pk_bf16_f32 v74, v74, v75
	v_cvt_pk_bf16_f32 v75, v76, v77
	v_cvt_pk_bf16_f32 v76, v78, v79
	v_mfma_f32_16x16x32_bf16 v[196:199], v[228:231], v[110:113], v[196:199]
	v_mfma_f32_16x16x32_bf16 v[212:215], v[228:231], v[126:129], v[212:215]
	v_cvt_pk_bf16_f32 v77, v80, v81
	v_cvt_pk_bf16_f32 v82, v82, v83
	v_cvt_pk_bf16_f32 v83, v84, v85
	s_waitcnt lgkmcnt(10)
	v_mfma_f32_16x16x32_bf16 v[200:203], v[232:235], v[110:113], v[200:203]
	v_mfma_f32_16x16x32_bf16 v[216:219], v[232:235], v[126:129], v[216:219]
	v_cvt_pk_bf16_f32 v84, v86, v87
	v_cvt_pk_bf16_f32 v85, v88, v89
	v_cvt_pk_bf16_f32 v90, v90, v91
	v_mfma_f32_16x16x32_bf16 v[204:207], v[236:239], v[110:113], v[204:207]
	v_mfma_f32_16x16x32_bf16 v[220:223], v[236:239], v[126:129], v[220:223]
	v_cvt_pk_bf16_f32 v91, v92, v93
	v_cvt_pk_bf16_f32 v92, v94, v95
	v_cvt_pk_bf16_f32 v93, v96, v97
	s_waitcnt lgkmcnt(6)
	v_mfma_f32_16x16x32_bf16 v[2:5], v[66:69], v[166:169], v[2:5]
	v_mfma_f32_16x16x32_bf16 v[34:37], v[82:85], v[166:169], v[34:37]
	ds_read_b64_tr_b16 v[228:229], v245 offset:0
	ds_read_b64_tr_b16 v[230:231], v245 offset:4096
	v_mfma_f32_16x16x32_bf16 v[6:9], v[66:69], v[170:173], v[6:9]
	v_mfma_f32_16x16x32_bf16 v[38:41], v[82:85], v[170:173], v[38:41]
	ds_read_b64_tr_b16 v[232:233], v246 offset:0
	ds_read_b64_tr_b16 v[234:235], v246 offset:4096
	s_waitcnt lgkmcnt(6)
	v_mfma_f32_16x16x32_bf16 v[10:13], v[66:69], v[174:177], v[10:13]
	v_mfma_f32_16x16x32_bf16 v[42:45], v[82:85], v[174:177], v[42:45]
	ds_read_b64_tr_b16 v[236:237], v247 offset:0
	ds_read_b64_tr_b16 v[238:239], v247 offset:4096
	v_exp_f32_e32 v192, v192
	v_exp_f32_e32 v193, v193
	v_exp_f32_e32 v194, v194
	v_mfma_f32_16x16x32_bf16 v[14:17], v[66:69], v[178:181], v[14:17]
	v_mfma_f32_16x16x32_bf16 v[46:49], v[82:85], v[178:181], v[46:49]
	ds_read_b64_tr_b16 v[166:167], v240 offset:8192
	ds_read_b64_tr_b16 v[168:169], v240 offset:12288
	v_exp_f32_e32 v195, v195
	v_exp_f32_e32 v208, v208
	s_waitcnt lgkmcnt(6)
	v_mfma_f32_16x16x32_bf16 v[18:21], v[66:69], v[224:227], v[18:21]
	v_mfma_f32_16x16x32_bf16 v[50:53], v[82:85], v[224:227], v[50:53]
	ds_read_b64_tr_b16 v[170:171], v241 offset:8192
	ds_read_b64_tr_b16 v[172:173], v241 offset:12288
	v_exp_f32_e32 v209, v209
	v_exp_f32_e32 v210, v210
	v_mfma_f32_16x16x32_bf16 v[22:25], v[66:69], v[228:231], v[22:25]
	v_mfma_f32_16x16x32_bf16 v[54:57], v[82:85], v[228:231], v[54:57]
	ds_read_b64_tr_b16 v[174:175], v242 offset:8192
	ds_read_b64_tr_b16 v[176:177], v242 offset:12288
	v_exp_f32_e32 v211, v211
	v_exp_f32_e32 v196, v196
	v_exp_f32_e32 v197, v197
	s_waitcnt lgkmcnt(6)
	v_mfma_f32_16x16x32_bf16 v[26:29], v[66:69], v[232:235], v[26:29]
	v_mfma_f32_16x16x32_bf16 v[58:61], v[82:85], v[232:235], v[58:61]
	ds_read_b64_tr_b16 v[178:179], v243 offset:8192
	ds_read_b64_tr_b16 v[180:181], v243 offset:12288
	v_exp_f32_e32 v198, v198
	v_exp_f32_e32 v199, v199
	v_mfma_f32_16x16x32_bf16 v[30:33], v[66:69], v[236:239], v[30:33]
	v_mfma_f32_16x16x32_bf16 v[62:65], v[82:85], v[236:239], v[62:65]
	ds_read_b64_tr_b16 v[224:225], v244 offset:8192
	ds_read_b64_tr_b16 v[226:227], v244 offset:12288
	v_exp_f32_e32 v212, v212
	v_exp_f32_e32 v213, v213
	s_waitcnt lgkmcnt(6)
	v_mfma_f32_16x16x32_bf16 v[2:5], v[74:77], v[166:169], v[2:5]
	v_mfma_f32_16x16x32_bf16 v[34:37], v[90:93], v[166:169], v[34:37]
	ds_read_b64_tr_b16 v[228:229], v245 offset:8192
	ds_read_b64_tr_b16 v[230:231], v245 offset:12288
	ds_read_b128 v[166:169], v187 offset:16384
	v_exp_f32_e32 v214, v214
	v_exp_f32_e32 v215, v215
	v_mfma_f32_16x16x32_bf16 v[6:9], v[74:77], v[170:173], v[6:9]
	v_mfma_f32_16x16x32_bf16 v[38:41], v[90:93], v[170:173], v[38:41]
	ds_read_b64_tr_b16 v[232:233], v246 offset:8192
	ds_read_b64_tr_b16 v[234:235], v246 offset:12288
	ds_read_b128 v[170:173], v187 offset:20480
	v_exp_f32_e32 v200, v200
	v_exp_f32_e32 v201, v201
	v_exp_f32_e32 v202, v202
	s_waitcnt lgkmcnt(8)
	v_mfma_f32_16x16x32_bf16 v[10:13], v[74:77], v[174:177], v[10:13]
	v_mfma_f32_16x16x32_bf16 v[42:45], v[90:93], v[174:177], v[42:45]
	ds_read_b64_tr_b16 v[236:237], v247 offset:8192
	ds_read_b64_tr_b16 v[238:239], v247 offset:12288
	ds_read_b128 v[174:177], v187 offset:24576
	v_exp_f32_e32 v203, v203
	v_exp_f32_e32 v216, v216
	v_mfma_f32_16x16x32_bf16 v[14:17], v[74:77], v[178:181], v[14:17]
	v_mfma_f32_16x16x32_bf16 v[46:49], v[90:93], v[178:181], v[46:49]
	ds_read_b128 v[178:181], v187 offset:28672
	v_exp_f32_e32 v217, v217
	v_exp_f32_e32 v218, v218
	s_waitcnt lgkmcnt(8)
	v_mfma_f32_16x16x32_bf16 v[18:21], v[74:77], v[224:227], v[18:21]
	v_mfma_f32_16x16x32_bf16 v[50:53], v[90:93], v[224:227], v[50:53]
	ds_read_b128 v[224:227], v188 offset:16384
	v_exp_f32_e32 v219, v219
	v_exp_f32_e32 v204, v204
	v_exp_f32_e32 v205, v205
	v_mfma_f32_16x16x32_bf16 v[22:25], v[74:77], v[228:231], v[22:25]
	v_mfma_f32_16x16x32_bf16 v[54:57], v[90:93], v[228:231], v[54:57]
	ds_read_b128 v[228:231], v188 offset:20480
	v_exp_f32_e32 v206, v206
	v_exp_f32_e32 v207, v207
	s_waitcnt lgkmcnt(4)
	v_mfma_f32_16x16x32_bf16 v[26:29], v[74:77], v[232:235], v[26:29]
	v_mfma_f32_16x16x32_bf16 v[58:61], v[90:93], v[232:235], v[58:61]
	ds_read_b128 v[232:235], v188 offset:24576
	v_exp_f32_e32 v220, v220
	v_exp_f32_e32 v221, v221
	v_mfma_f32_16x16x32_bf16 v[30:33], v[74:77], v[236:239], v[30:33]
	v_mfma_f32_16x16x32_bf16 v[62:65], v[90:93], v[236:239], v[62:65]
	ds_read_b128 v[236:239], v188 offset:28672
	v_exp_f32_e32 v222, v222
	v_exp_f32_e32 v223, v223
	s_waitcnt vmcnt(0)
	s_barrier
	s_add_i32 s66, s3, s33
	s_cmpk_lt_i32 s66, 0x400
	s_cselect_b32 s66, s66, s3
	s_lshr_b32 s0, s66, 7
	s_lshl_b32 s0, s0, 23
	s_and_b32 s1, s66, 15
	s_lshl_b32 s1, s1, 19
	s_or_b32 s0, s0, s1
	s_bfe_u32 s1, s66, 0x30004
	s_lshl_b32 s1, s1, 8
	s_or_b32 s0, s0, s1
	s_add_u32 s60, s25, s0
	s_addc_u32 s61, s28, 0
	s_add_u32 s18, s21, s0
	s_addc_u32 s19, s24, 0
	s_lshr_b32 s1, s66, 6
	s_mul_i32 s1, s1, 0x110000
	s_add_u32 s62, s9, s1
	s_addc_u32 s63, s20, 0
	s_add_u32 s64, s29, s1
	s_addc_u32 s65, s30, 0
	v_mfma_f32_16x16x32_bf16 v[66:69], v[166:169], v[98:101], 0
	v_mfma_f32_16x16x32_bf16 v[82:85], v[166:169], v[114:117], 0
	ds_read_b128 v[166:169], v189 offset:16384
	v_add_f32_e32 v130, v192, v193
	v_add_f32_e32 v131, v194, v195
	v_add_f32_e32 v130, v196, v130
	v_mfma_f32_16x16x32_bf16 v[70:73], v[170:173], v[98:101], 0
	v_mfma_f32_16x16x32_bf16 v[86:89], v[170:173], v[114:117], 0
	ds_read_b128 v[170:173], v189 offset:20480
	v_add_f32_e32 v131, v197, v131
	v_add_f32_e32 v130, v198, v130
	v_add_f32_e32 v131, v199, v131
	s_waitcnt lgkmcnt(6)
	v_mfma_f32_16x16x32_bf16 v[74:77], v[174:177], v[98:101], 0
	v_mfma_f32_16x16x32_bf16 v[90:93], v[174:177], v[114:117], 0
	ds_read_b128 v[174:177], v189 offset:24576
	v_add_f32_e32 v130, v200, v130
	v_add_f32_e32 v131, v201, v131
	v_add_f32_e32 v130, v202, v130
	v_mfma_f32_16x16x32_bf16 v[78:81], v[178:181], v[98:101], 0
	v_mfma_f32_16x16x32_bf16 v[94:97], v[178:181], v[114:117], 0
	ds_read_b128 v[178:181], v189 offset:28672
	v_add_f32_e32 v131, v203, v131
	v_add_f32_e32 v130, v204, v130
	v_add_f32_e32 v131, v205, v131
	s_waitcnt lgkmcnt(6)
	v_mfma_f32_16x16x32_bf16 v[66:69], v[224:227], v[102:105], v[66:69]
	v_mfma_f32_16x16x32_bf16 v[82:85], v[224:227], v[118:121], v[82:85]
	ds_read_b128 v[224:227], v190 offset:16384
	v_add_f32_e32 v130, v206, v130
	v_add_f32_e32 v131, v207, v131
	v_add_f32_e32 v130, v130, v131
	v_mfma_f32_16x16x32_bf16 v[70:73], v[228:231], v[102:105], v[70:73]
	v_mfma_f32_16x16x32_bf16 v[86:89], v[228:231], v[118:121], v[86:89]
	ds_read_b128 v[228:231], v190 offset:20480
	v_add_f32_e32 v165, v165, v130
	v_add_f32_e32 v132, v208, v209
	v_add_f32_e32 v133, v210, v211
	s_waitcnt lgkmcnt(6)
	v_mfma_f32_16x16x32_bf16 v[74:77], v[232:235], v[102:105], v[74:77]
	v_mfma_f32_16x16x32_bf16 v[90:93], v[232:235], v[118:121], v[90:93]
	ds_read_b128 v[232:235], v190 offset:24576
	v_add_f32_e32 v132, v212, v132
	v_add_f32_e32 v133, v213, v133
	v_add_f32_e32 v132, v214, v132
	v_mfma_f32_16x16x32_bf16 v[78:81], v[236:239], v[102:105], v[78:81]
	v_mfma_f32_16x16x32_bf16 v[94:97], v[236:239], v[118:121], v[94:97]
	ds_read_b128 v[236:239], v190 offset:28672
	v_add_f32_e32 v133, v215, v133
	v_add_f32_e32 v132, v216, v132
	v_add_f32_e32 v133, v217, v133
	s_waitcnt lgkmcnt(6)
	v_mfma_f32_16x16x32_bf16 v[66:69], v[166:169], v[106:109], v[66:69]
	v_mfma_f32_16x16x32_bf16 v[82:85], v[166:169], v[122:125], v[82:85]
	ds_read_b64_tr_b16 v[166:167], v240 offset:32768
	ds_read_b64_tr_b16 v[168:169], v240 offset:36864
	v_add_f32_e32 v132, v218, v132
	v_add_f32_e32 v133, v219, v133
	v_add_f32_e32 v132, v220, v132
	v_mfma_f32_16x16x32_bf16 v[70:73], v[170:173], v[106:109], v[70:73]
	v_mfma_f32_16x16x32_bf16 v[86:89], v[170:173], v[122:125], v[86:89]
	ds_read_b64_tr_b16 v[170:171], v241 offset:32768
	ds_read_b64_tr_b16 v[172:173], v241 offset:36864
	v_add_f32_e32 v133, v221, v133
	v_add_f32_e32 v132, v222, v132
	v_add_f32_e32 v133, v223, v133
	s_waitcnt lgkmcnt(8)
	v_mfma_f32_16x16x32_bf16 v[74:77], v[174:177], v[106:109], v[74:77]
	v_mfma_f32_16x16x32_bf16 v[90:93], v[174:177], v[122:125], v[90:93]
	ds_read_b64_tr_b16 v[174:175], v242 offset:32768
	ds_read_b64_tr_b16 v[176:177], v242 offset:36864
	v_add_f32_e32 v132, v132, v133
	v_add_f32_e32 v163, v163, v132
	v_cvt_pk_bf16_f32 v192, v192, v193
	v_mfma_f32_16x16x32_bf16 v[78:81], v[178:181], v[106:109], v[78:81]
	v_mfma_f32_16x16x32_bf16 v[94:97], v[178:181], v[122:125], v[94:97]
	ds_read_b64_tr_b16 v[178:179], v243 offset:32768
	ds_read_b64_tr_b16 v[180:181], v243 offset:36864
	v_cvt_pk_bf16_f32 v193, v194, v195
	v_cvt_pk_bf16_f32 v194, v196, v197
	v_cvt_pk_bf16_f32 v195, v198, v199
	s_waitcnt lgkmcnt(10)
	v_mfma_f32_16x16x32_bf16 v[66:69], v[224:227], v[110:113], v[66:69]
	v_mfma_f32_16x16x32_bf16 v[82:85], v[224:227], v[126:129], v[82:85]
	ds_read_b64_tr_b16 v[224:225], v244 offset:32768
	ds_read_b64_tr_b16 v[226:227], v244 offset:36864
	v_cvt_pk_bf16_f32 v200, v200, v201
	v_cvt_pk_bf16_f32 v201, v202, v203
	v_cvt_pk_bf16_f32 v202, v204, v205
	v_mfma_f32_16x16x32_bf16 v[70:73], v[228:231], v[110:113], v[70:73]
	v_mfma_f32_16x16x32_bf16 v[86:89], v[228:231], v[126:129], v[86:89]
	v_cvt_pk_bf16_f32 v203, v206, v207
	v_cvt_pk_bf16_f32 v208, v208, v209
	v_cvt_pk_bf16_f32 v209, v210, v211
	s_waitcnt lgkmcnt(10)
	v_mfma_f32_16x16x32_bf16 v[74:77], v[232:235], v[110:113], v[74:77]
	v_mfma_f32_16x16x32_bf16 v[90:93], v[232:235], v[126:129], v[90:93]
	v_cvt_pk_bf16_f32 v210, v212, v213
	v_cvt_pk_bf16_f32 v211, v214, v215
	v_cvt_pk_bf16_f32 v216, v216, v217
	v_mfma_f32_16x16x32_bf16 v[78:81], v[236:239], v[110:113], v[78:81]
	v_mfma_f32_16x16x32_bf16 v[94:97], v[236:239], v[126:129], v[94:97]
	v_cvt_pk_bf16_f32 v217, v218, v219
	v_cvt_pk_bf16_f32 v218, v220, v221
	v_cvt_pk_bf16_f32 v219, v222, v223
	s_waitcnt lgkmcnt(6)
	v_mfma_f32_16x16x32_bf16 v[2:5], v[192:195], v[166:169], v[2:5]
	v_mfma_f32_16x16x32_bf16 v[34:37], v[208:211], v[166:169], v[34:37]
	ds_read_b64_tr_b16 v[228:229], v245 offset:32768
	ds_read_b64_tr_b16 v[230:231], v245 offset:36864
	v_mfma_f32_16x16x32_bf16 v[6:9], v[192:195], v[170:173], v[6:9]
	v_mfma_f32_16x16x32_bf16 v[38:41], v[208:211], v[170:173], v[38:41]
	ds_read_b64_tr_b16 v[232:233], v246 offset:32768
	ds_read_b64_tr_b16 v[234:235], v246 offset:36864
	s_waitcnt lgkmcnt(6)
	v_mfma_f32_16x16x32_bf16 v[10:13], v[192:195], v[174:177], v[10:13]
	v_mfma_f32_16x16x32_bf16 v[42:45], v[208:211], v[174:177], v[42:45]
	ds_read_b64_tr_b16 v[236:237], v247 offset:32768
	ds_read_b64_tr_b16 v[238:239], v247 offset:36864
	v_exp_f32_e32 v66, v66
	v_exp_f32_e32 v67, v67
	v_exp_f32_e32 v68, v68
	v_mfma_f32_16x16x32_bf16 v[14:17], v[192:195], v[178:181], v[14:17]
	v_mfma_f32_16x16x32_bf16 v[46:49], v[208:211], v[178:181], v[46:49]
	ds_read_b64_tr_b16 v[166:167], v240 offset:40960
	ds_read_b64_tr_b16 v[168:169], v240 offset:45056
	v_exp_f32_e32 v69, v69
	v_exp_f32_e32 v82, v82
	s_waitcnt lgkmcnt(6)
	v_mfma_f32_16x16x32_bf16 v[18:21], v[192:195], v[224:227], v[18:21]
	v_mfma_f32_16x16x32_bf16 v[50:53], v[208:211], v[224:227], v[50:53]
	ds_read_b64_tr_b16 v[170:171], v241 offset:40960
	ds_read_b64_tr_b16 v[172:173], v241 offset:45056
	v_exp_f32_e32 v83, v83
	v_exp_f32_e32 v84, v84
	v_mfma_f32_16x16x32_bf16 v[22:25], v[192:195], v[228:231], v[22:25]
	v_mfma_f32_16x16x32_bf16 v[54:57], v[208:211], v[228:231], v[54:57]
	ds_read_b64_tr_b16 v[174:175], v242 offset:40960
	ds_read_b64_tr_b16 v[176:177], v242 offset:45056
	v_exp_f32_e32 v85, v85
	v_exp_f32_e32 v70, v70
	v_exp_f32_e32 v71, v71
	s_waitcnt lgkmcnt(6)
	v_mfma_f32_16x16x32_bf16 v[26:29], v[192:195], v[232:235], v[26:29]
	v_mfma_f32_16x16x32_bf16 v[58:61], v[208:211], v[232:235], v[58:61]
	ds_read_b64_tr_b16 v[178:179], v243 offset:40960
	ds_read_b64_tr_b16 v[180:181], v243 offset:45056
	v_exp_f32_e32 v72, v72
	v_exp_f32_e32 v73, v73
	v_mfma_f32_16x16x32_bf16 v[30:33], v[192:195], v[236:239], v[30:33]
	v_mfma_f32_16x16x32_bf16 v[62:65], v[208:211], v[236:239], v[62:65]
	ds_read_b64_tr_b16 v[224:225], v244 offset:40960
	ds_read_b64_tr_b16 v[226:227], v244 offset:45056
	v_exp_f32_e32 v86, v86
	v_exp_f32_e32 v87, v87
	s_waitcnt lgkmcnt(6)
	v_mfma_f32_16x16x32_bf16 v[2:5], v[200:203], v[166:169], v[2:5]
	v_mfma_f32_16x16x32_bf16 v[34:37], v[216:219], v[166:169], v[34:37]
	ds_read_b64_tr_b16 v[228:229], v245 offset:40960
	ds_read_b64_tr_b16 v[230:231], v245 offset:45056
	ds_read_b128 v[166:169], v187 offset:49152
	v_exp_f32_e32 v88, v88
	v_exp_f32_e32 v89, v89
	v_mfma_f32_16x16x32_bf16 v[6:9], v[200:203], v[170:173], v[6:9]
	v_mfma_f32_16x16x32_bf16 v[38:41], v[216:219], v[170:173], v[38:41]
	ds_read_b64_tr_b16 v[232:233], v246 offset:40960
	ds_read_b64_tr_b16 v[234:235], v246 offset:45056
	ds_read_b128 v[170:173], v187 offset:53248
	v_exp_f32_e32 v74, v74
	v_exp_f32_e32 v75, v75
	v_exp_f32_e32 v76, v76
	s_waitcnt lgkmcnt(8)
	v_mfma_f32_16x16x32_bf16 v[10:13], v[200:203], v[174:177], v[10:13]
	v_mfma_f32_16x16x32_bf16 v[42:45], v[216:219], v[174:177], v[42:45]
	ds_read_b64_tr_b16 v[236:237], v247 offset:40960
	ds_read_b64_tr_b16 v[238:239], v247 offset:45056
	ds_read_b128 v[174:177], v187 offset:57344
	v_exp_f32_e32 v77, v77
	v_exp_f32_e32 v90, v90
	v_mfma_f32_16x16x32_bf16 v[14:17], v[200:203], v[178:181], v[14:17]
	v_mfma_f32_16x16x32_bf16 v[46:49], v[216:219], v[178:181], v[46:49]
	ds_read_b128 v[178:181], v187 offset:61440
	v_exp_f32_e32 v91, v91
	v_exp_f32_e32 v92, v92
	s_waitcnt lgkmcnt(8)
	v_mfma_f32_16x16x32_bf16 v[18:21], v[200:203], v[224:227], v[18:21]
	v_mfma_f32_16x16x32_bf16 v[50:53], v[216:219], v[224:227], v[50:53]
	ds_read_b128 v[224:227], v188 offset:49152
	v_exp_f32_e32 v93, v93
	v_exp_f32_e32 v78, v78
	v_exp_f32_e32 v79, v79
	v_mfma_f32_16x16x32_bf16 v[22:25], v[200:203], v[228:231], v[22:25]
	v_mfma_f32_16x16x32_bf16 v[54:57], v[216:219], v[228:231], v[54:57]
	ds_read_b128 v[228:231], v188 offset:53248
	v_exp_f32_e32 v80, v80
	v_exp_f32_e32 v81, v81
	s_waitcnt lgkmcnt(4)
	v_mfma_f32_16x16x32_bf16 v[26:29], v[200:203], v[232:235], v[26:29]
	v_mfma_f32_16x16x32_bf16 v[58:61], v[216:219], v[232:235], v[58:61]
	ds_read_b128 v[232:235], v188 offset:57344
	v_exp_f32_e32 v94, v94
	v_exp_f32_e32 v95, v95
	v_mfma_f32_16x16x32_bf16 v[30:33], v[200:203], v[236:239], v[30:33]
	v_mfma_f32_16x16x32_bf16 v[62:65], v[216:219], v[236:239], v[62:65]
	ds_read_b128 v[236:239], v188 offset:61440
	v_exp_f32_e32 v96, v96
	v_exp_f32_e32 v97, v97
	s_barrier
	v_mfma_f32_16x16x32_bf16 v[192:195], v[166:169], v[98:101], 0
	v_mfma_f32_16x16x32_bf16 v[208:211], v[166:169], v[114:117], 0
	ds_read_b128 v[166:169], v189 offset:49152
	s_add_i32 m0, s45, 0x0
	v_add_f32_e32 v130, v66, v67
	v_add_f32_e32 v131, v68, v69
	v_add_f32_e32 v130, v70, v130
	global_load_lds_dwordx4 v152, s[64:65]
	v_mfma_f32_16x16x32_bf16 v[196:199], v[170:173], v[98:101], 0
	v_mfma_f32_16x16x32_bf16 v[212:215], v[170:173], v[114:117], 0
	ds_read_b128 v[170:173], v189 offset:53248
	s_add_i32 m0, s45, 0x4000
	v_add_f32_e32 v131, v71, v131
	v_add_f32_e32 v130, v72, v130
	v_add_f32_e32 v131, v73, v131
	global_load_lds_dwordx4 v150, s[62:63]
	s_waitcnt lgkmcnt(6)
	v_mfma_f32_16x16x32_bf16 v[200:203], v[174:177], v[98:101], 0
	v_mfma_f32_16x16x32_bf16 v[216:219], v[174:177], v[114:117], 0
	ds_read_b128 v[174:177], v189 offset:57344
	s_add_i32 m0, s45, 0x2000
	v_add_f32_e32 v130, v74, v130
	v_add_f32_e32 v131, v75, v131
	v_add_f32_e32 v130, v76, v130
	global_load_lds_dwordx4 v153, s[64:65]
	v_mfma_f32_16x16x32_bf16 v[204:207], v[178:181], v[98:101], 0
	v_mfma_f32_16x16x32_bf16 v[220:223], v[178:181], v[114:117], 0
	ds_read_b128 v[178:181], v189 offset:61440
	s_add_i32 m0, s45, 0x6000
	v_add_f32_e32 v131, v77, v131
	v_add_f32_e32 v130, v78, v130
	v_add_f32_e32 v131, v79, v131
	global_load_lds_dwordx4 v151, s[62:63]
	s_add_u32 s62, s62, 0x4000
	s_addc_u32 s63, s63, 0
	s_add_u32 s64, s64, 0x4000
	s_addc_u32 s65, s65, 0
	s_waitcnt lgkmcnt(6)
	v_mfma_f32_16x16x32_bf16 v[192:195], v[224:227], v[102:105], v[192:195]
	v_mfma_f32_16x16x32_bf16 v[208:211], v[224:227], v[118:121], v[208:211]
	ds_read_b128 v[224:227], v190 offset:49152
	v_add_f32_e32 v130, v80, v130
	v_add_f32_e32 v131, v81, v131
	v_add_f32_e32 v130, v130, v131
	v_mfma_f32_16x16x32_bf16 v[196:199], v[228:231], v[102:105], v[196:199]
	v_mfma_f32_16x16x32_bf16 v[212:215], v[228:231], v[118:121], v[212:215]
	ds_read_b128 v[228:231], v190 offset:53248
	v_add_f32_e32 v165, v165, v130
	v_add_f32_e32 v132, v82, v83
	v_add_f32_e32 v133, v84, v85
	s_waitcnt lgkmcnt(6)
	v_mfma_f32_16x16x32_bf16 v[200:203], v[232:235], v[102:105], v[200:203]
	v_mfma_f32_16x16x32_bf16 v[216:219], v[232:235], v[118:121], v[216:219]
	ds_read_b128 v[232:235], v190 offset:57344
	v_add_f32_e32 v132, v86, v132
	v_add_f32_e32 v133, v87, v133
	v_add_f32_e32 v132, v88, v132
	v_mfma_f32_16x16x32_bf16 v[204:207], v[236:239], v[102:105], v[204:207]
	v_mfma_f32_16x16x32_bf16 v[220:223], v[236:239], v[118:121], v[220:223]
	ds_read_b128 v[236:239], v190 offset:61440
	v_add_f32_e32 v133, v89, v133
	v_add_f32_e32 v132, v90, v132
	v_add_f32_e32 v133, v91, v133
	s_waitcnt lgkmcnt(6)
	v_mfma_f32_16x16x32_bf16 v[192:195], v[166:169], v[106:109], v[192:195]
	v_mfma_f32_16x16x32_bf16 v[208:211], v[166:169], v[122:125], v[208:211]
	ds_read_b64_tr_b16 v[166:167], v142 offset:0
	ds_read_b64_tr_b16 v[168:169], v142 offset:4096
	v_add_f32_e32 v132, v92, v132
	v_add_f32_e32 v133, v93, v133
	v_add_f32_e32 v132, v94, v132
	v_mfma_f32_16x16x32_bf16 v[196:199], v[170:173], v[106:109], v[196:199]
	v_mfma_f32_16x16x32_bf16 v[212:215], v[170:173], v[122:125], v[212:215]
	ds_read_b64_tr_b16 v[170:171], v143 offset:0
	ds_read_b64_tr_b16 v[172:173], v143 offset:4096
	v_add_f32_e32 v133, v95, v133
	v_add_f32_e32 v132, v96, v132
	v_add_f32_e32 v133, v97, v133
	s_waitcnt lgkmcnt(8)
	v_mfma_f32_16x16x32_bf16 v[200:203], v[174:177], v[106:109], v[200:203]
	v_mfma_f32_16x16x32_bf16 v[216:219], v[174:177], v[122:125], v[216:219]
	ds_read_b64_tr_b16 v[174:175], v144 offset:0
	ds_read_b64_tr_b16 v[176:177], v144 offset:4096
	v_add_f32_e32 v132, v132, v133
	v_add_f32_e32 v163, v163, v132
	v_cvt_pk_bf16_f32 v66, v66, v67
	v_mfma_f32_16x16x32_bf16 v[204:207], v[178:181], v[106:109], v[204:207]
	v_mfma_f32_16x16x32_bf16 v[220:223], v[178:181], v[122:125], v[220:223]
	ds_read_b64_tr_b16 v[178:179], v145 offset:0
	ds_read_b64_tr_b16 v[180:181], v145 offset:4096
	v_cvt_pk_bf16_f32 v67, v68, v69
	v_cvt_pk_bf16_f32 v68, v70, v71
	v_cvt_pk_bf16_f32 v69, v72, v73
	s_waitcnt lgkmcnt(10)
	v_mfma_f32_16x16x32_bf16 v[192:195], v[224:227], v[110:113], v[192:195]
	v_mfma_f32_16x16x32_bf16 v[208:211], v[224:227], v[126:129], v[208:211]
	ds_read_b64_tr_b16 v[224:225], v146 offset:0
	ds_read_b64_tr_b16 v[226:227], v146 offset:4096
	v_cvt_pk_bf16_f32 v74, v74, v75
	v_cvt_pk_bf16_f32 v75, v76, v77
	v_cvt_pk_bf16_f32 v76, v78, v79
	v_mfma_f32_16x16x32_bf16 v[196:199], v[228:231], v[110:113], v[196:199]
	v_mfma_f32_16x16x32_bf16 v[212:215], v[228:231], v[126:129], v[212:215]
	v_cvt_pk_bf16_f32 v77, v80, v81
	v_cvt_pk_bf16_f32 v82, v82, v83
	v_cvt_pk_bf16_f32 v83, v84, v85
	s_waitcnt lgkmcnt(10)
	v_mfma_f32_16x16x32_bf16 v[200:203], v[232:235], v[110:113], v[200:203]
	v_mfma_f32_16x16x32_bf16 v[216:219], v[232:235], v[126:129], v[216:219]
	v_cvt_pk_bf16_f32 v84, v86, v87
	v_cvt_pk_bf16_f32 v85, v88, v89
	v_cvt_pk_bf16_f32 v90, v90, v91
	v_mfma_f32_16x16x32_bf16 v[204:207], v[236:239], v[110:113], v[204:207]
	v_mfma_f32_16x16x32_bf16 v[220:223], v[236:239], v[126:129], v[220:223]
	v_cvt_pk_bf16_f32 v91, v92, v93
	v_cvt_pk_bf16_f32 v92, v94, v95
	v_cvt_pk_bf16_f32 v93, v96, v97
	s_waitcnt lgkmcnt(6)
	v_mfma_f32_16x16x32_bf16 v[2:5], v[66:69], v[166:169], v[2:5]
	v_mfma_f32_16x16x32_bf16 v[34:37], v[82:85], v[166:169], v[34:37]
	ds_read_b64_tr_b16 v[228:229], v147 offset:0
	ds_read_b64_tr_b16 v[230:231], v147 offset:4096
	v_mfma_f32_16x16x32_bf16 v[6:9], v[66:69], v[170:173], v[6:9]
	v_mfma_f32_16x16x32_bf16 v[38:41], v[82:85], v[170:173], v[38:41]
	ds_read_b64_tr_b16 v[232:233], v148 offset:0
	ds_read_b64_tr_b16 v[234:235], v148 offset:4096
	s_waitcnt lgkmcnt(6)
	v_mfma_f32_16x16x32_bf16 v[10:13], v[66:69], v[174:177], v[10:13]
	v_mfma_f32_16x16x32_bf16 v[42:45], v[82:85], v[174:177], v[42:45]
	ds_read_b64_tr_b16 v[236:237], v149 offset:0
	ds_read_b64_tr_b16 v[238:239], v149 offset:4096
	v_exp_f32_e32 v192, v192
	v_exp_f32_e32 v193, v193
	v_exp_f32_e32 v194, v194
	v_mfma_f32_16x16x32_bf16 v[14:17], v[66:69], v[178:181], v[14:17]
	v_mfma_f32_16x16x32_bf16 v[46:49], v[82:85], v[178:181], v[46:49]
	ds_read_b64_tr_b16 v[166:167], v142 offset:8192
	ds_read_b64_tr_b16 v[168:169], v142 offset:12288
	v_exp_f32_e32 v195, v195
	v_exp_f32_e32 v208, v208
	s_waitcnt lgkmcnt(6)
	v_mfma_f32_16x16x32_bf16 v[18:21], v[66:69], v[224:227], v[18:21]
	v_mfma_f32_16x16x32_bf16 v[50:53], v[82:85], v[224:227], v[50:53]
	ds_read_b64_tr_b16 v[170:171], v143 offset:8192
	ds_read_b64_tr_b16 v[172:173], v143 offset:12288
	v_exp_f32_e32 v209, v209
	v_exp_f32_e32 v210, v210
	v_mfma_f32_16x16x32_bf16 v[22:25], v[66:69], v[228:231], v[22:25]
	v_mfma_f32_16x16x32_bf16 v[54:57], v[82:85], v[228:231], v[54:57]
	ds_read_b64_tr_b16 v[174:175], v144 offset:8192
	ds_read_b64_tr_b16 v[176:177], v144 offset:12288
	v_exp_f32_e32 v211, v211
	v_exp_f32_e32 v196, v196
	v_exp_f32_e32 v197, v197
	s_waitcnt lgkmcnt(6)
	v_mfma_f32_16x16x32_bf16 v[26:29], v[66:69], v[232:235], v[26:29]
	v_mfma_f32_16x16x32_bf16 v[58:61], v[82:85], v[232:235], v[58:61]
	ds_read_b64_tr_b16 v[178:179], v145 offset:8192
	ds_read_b64_tr_b16 v[180:181], v145 offset:12288
	v_exp_f32_e32 v198, v198
	v_exp_f32_e32 v199, v199
	v_mfma_f32_16x16x32_bf16 v[30:33], v[66:69], v[236:239], v[30:33]
	v_mfma_f32_16x16x32_bf16 v[62:65], v[82:85], v[236:239], v[62:65]
	ds_read_b64_tr_b16 v[224:225], v146 offset:8192
	ds_read_b64_tr_b16 v[226:227], v146 offset:12288
	v_exp_f32_e32 v212, v212
	v_exp_f32_e32 v213, v213
	s_waitcnt lgkmcnt(6)
	v_mfma_f32_16x16x32_bf16 v[2:5], v[74:77], v[166:169], v[2:5]
	v_mfma_f32_16x16x32_bf16 v[34:37], v[90:93], v[166:169], v[34:37]
	ds_read_b64_tr_b16 v[228:229], v147 offset:8192
	ds_read_b64_tr_b16 v[230:231], v147 offset:12288
	v_exp_f32_e32 v214, v214
	v_exp_f32_e32 v215, v215
	v_mfma_f32_16x16x32_bf16 v[6:9], v[74:77], v[170:173], v[6:9]
	v_mfma_f32_16x16x32_bf16 v[38:41], v[90:93], v[170:173], v[38:41]
	ds_read_b64_tr_b16 v[232:233], v148 offset:8192
	ds_read_b64_tr_b16 v[234:235], v148 offset:12288
	v_exp_f32_e32 v200, v200
	v_exp_f32_e32 v201, v201
	v_exp_f32_e32 v202, v202
	s_waitcnt lgkmcnt(6)
	v_mfma_f32_16x16x32_bf16 v[10:13], v[74:77], v[174:177], v[10:13]
	v_mfma_f32_16x16x32_bf16 v[42:45], v[90:93], v[174:177], v[42:45]
	ds_read_b64_tr_b16 v[236:237], v149 offset:8192
	ds_read_b64_tr_b16 v[238:239], v149 offset:12288
	v_exp_f32_e32 v203, v203
	v_exp_f32_e32 v216, v216
	v_mfma_f32_16x16x32_bf16 v[14:17], v[74:77], v[178:181], v[14:17]
	v_mfma_f32_16x16x32_bf16 v[46:49], v[90:93], v[178:181], v[46:49]
	v_exp_f32_e32 v217, v217
	v_exp_f32_e32 v218, v218
	s_waitcnt lgkmcnt(4)
	v_mfma_f32_16x16x32_bf16 v[18:21], v[74:77], v[224:227], v[18:21]
	v_mfma_f32_16x16x32_bf16 v[50:53], v[90:93], v[224:227], v[50:53]
	v_exp_f32_e32 v219, v219
	v_exp_f32_e32 v204, v204
	v_exp_f32_e32 v205, v205
	v_mfma_f32_16x16x32_bf16 v[22:25], v[74:77], v[228:231], v[22:25]
	v_mfma_f32_16x16x32_bf16 v[54:57], v[90:93], v[228:231], v[54:57]
	v_exp_f32_e32 v206, v206
	v_exp_f32_e32 v207, v207
	s_waitcnt lgkmcnt(0)
	v_mfma_f32_16x16x32_bf16 v[26:29], v[74:77], v[232:235], v[26:29]
	v_mfma_f32_16x16x32_bf16 v[58:61], v[90:93], v[232:235], v[58:61]
	v_exp_f32_e32 v220, v220
	v_exp_f32_e32 v221, v221
	v_mfma_f32_16x16x32_bf16 v[30:33], v[74:77], v[236:239], v[30:33]
	v_mfma_f32_16x16x32_bf16 v[62:65], v[90:93], v[236:239], v[62:65]
	v_exp_f32_e32 v222, v222
	v_exp_f32_e32 v223, v223
	s_add_i32 m0, s45, 0x8000
	s_nop 0
	global_load_lds_dwordx4 v152, s[64:65]
	s_add_i32 m0, s45, 0xc000
	s_nop 0
	global_load_lds_dwordx4 v150, s[62:63]
	s_add_i32 m0, s45, 0xa000
	s_nop 0
	global_load_lds_dwordx4 v153, s[64:65]
	s_add_i32 m0, s45, 0xe000
	s_nop 0
	global_load_lds_dwordx4 v151, s[62:63]
	s_add_u32 s62, s62, 0x4000
	s_addc_u32 s63, s63, 0
	s_add_u32 s64, s64, 0x4000
	s_addc_u32 s65, s65, 0
	global_load_dwordx4 v[98:101], v154, s[60:61]
	global_load_dwordx4 v[102:105], v154, s[60:61] offset:64
	global_load_dwordx4 v[106:109], v154, s[60:61] offset:128
	global_load_dwordx4 v[110:113], v154, s[60:61] offset:192
	global_load_dwordx4 v[114:117], v155, s[60:61]
	global_load_dwordx4 v[118:121], v155, s[60:61] offset:64
	global_load_dwordx4 v[122:125], v155, s[60:61] offset:128
	global_load_dwordx4 v[126:129], v155, s[60:61] offset:192
	s_barrier
	ds_read_b64_tr_b16 v[166:167], v142 offset:32768
	ds_read_b64_tr_b16 v[168:169], v142 offset:36864
	ds_read_b64_tr_b16 v[170:171], v143 offset:32768
	ds_read_b64_tr_b16 v[172:173], v143 offset:36864
	ds_read_b64_tr_b16 v[174:175], v144 offset:32768
	ds_read_b64_tr_b16 v[176:177], v144 offset:36864
	ds_read_b64_tr_b16 v[178:179], v145 offset:32768
	ds_read_b64_tr_b16 v[180:181], v145 offset:36864
	ds_read_b64_tr_b16 v[224:225], v146 offset:32768
	ds_read_b64_tr_b16 v[226:227], v146 offset:36864
	v_add_f32_e32 v130, v192, v193
	v_add_f32_e32 v131, v194, v195
	v_add_f32_e32 v130, v196, v130
	v_add_f32_e32 v131, v197, v131
	v_add_f32_e32 v130, v198, v130
	v_add_f32_e32 v131, v199, v131
	v_add_f32_e32 v130, v200, v130
	v_add_f32_e32 v131, v201, v131
	v_add_f32_e32 v130, v202, v130
	v_add_f32_e32 v131, v203, v131
	v_add_f32_e32 v130, v204, v130
	v_add_f32_e32 v131, v205, v131
	v_add_f32_e32 v130, v206, v130
	v_add_f32_e32 v131, v207, v131
	v_add_f32_e32 v130, v130, v131
	v_add_f32_e32 v165, v165, v130
	v_add_f32_e32 v132, v208, v209
	v_add_f32_e32 v133, v210, v211
	v_add_f32_e32 v132, v212, v132
	v_add_f32_e32 v133, v213, v133
	v_add_f32_e32 v132, v214, v132
	v_add_f32_e32 v133, v215, v133
	v_add_f32_e32 v132, v216, v132
	v_add_f32_e32 v133, v217, v133
	v_add_f32_e32 v132, v218, v132
	v_add_f32_e32 v133, v219, v133
	v_add_f32_e32 v132, v220, v132
	v_add_f32_e32 v133, v221, v133
	v_add_f32_e32 v132, v222, v132
	v_add_f32_e32 v133, v223, v133
	v_add_f32_e32 v132, v132, v133
	v_add_f32_e32 v163, v163, v132
	v_cvt_pk_bf16_f32 v192, v192, v193
	v_cvt_pk_bf16_f32 v193, v194, v195
	v_cvt_pk_bf16_f32 v194, v196, v197
	v_cvt_pk_bf16_f32 v195, v198, v199
	v_cvt_pk_bf16_f32 v200, v200, v201
	v_cvt_pk_bf16_f32 v201, v202, v203
	v_cvt_pk_bf16_f32 v202, v204, v205
	v_cvt_pk_bf16_f32 v203, v206, v207
	v_cvt_pk_bf16_f32 v208, v208, v209
	v_cvt_pk_bf16_f32 v209, v210, v211
	v_cvt_pk_bf16_f32 v210, v212, v213
	v_cvt_pk_bf16_f32 v211, v214, v215
	v_cvt_pk_bf16_f32 v216, v216, v217
	v_cvt_pk_bf16_f32 v217, v218, v219
	v_cvt_pk_bf16_f32 v218, v220, v221
	v_cvt_pk_bf16_f32 v219, v222, v223
	s_waitcnt lgkmcnt(6)
	v_mfma_f32_16x16x32_bf16 v[2:5], v[192:195], v[166:169], v[2:5]
	v_mfma_f32_16x16x32_bf16 v[34:37], v[208:211], v[166:169], v[34:37]
	ds_read_b64_tr_b16 v[228:229], v147 offset:32768
	ds_read_b64_tr_b16 v[230:231], v147 offset:36864
	v_mfma_f32_16x16x32_bf16 v[6:9], v[192:195], v[170:173], v[6:9]
	v_mfma_f32_16x16x32_bf16 v[38:41], v[208:211], v[170:173], v[38:41]
	ds_read_b64_tr_b16 v[232:233], v148 offset:32768
	ds_read_b64_tr_b16 v[234:235], v148 offset:36864
	s_waitcnt lgkmcnt(6)
	v_mfma_f32_16x16x32_bf16 v[10:13], v[192:195], v[174:177], v[10:13]
	v_mfma_f32_16x16x32_bf16 v[42:45], v[208:211], v[174:177], v[42:45]
	ds_read_b64_tr_b16 v[236:237], v149 offset:32768
	ds_read_b64_tr_b16 v[238:239], v149 offset:36864
	v_mfma_f32_16x16x32_bf16 v[14:17], v[192:195], v[178:181], v[14:17]
	v_mfma_f32_16x16x32_bf16 v[46:49], v[208:211], v[178:181], v[46:49]
	ds_read_b64_tr_b16 v[166:167], v142 offset:40960
	ds_read_b64_tr_b16 v[168:169], v142 offset:45056
	s_waitcnt lgkmcnt(6)
	v_mfma_f32_16x16x32_bf16 v[18:21], v[192:195], v[224:227], v[18:21]
	v_mfma_f32_16x16x32_bf16 v[50:53], v[208:211], v[224:227], v[50:53]
	ds_read_b64_tr_b16 v[170:171], v143 offset:40960
	ds_read_b64_tr_b16 v[172:173], v143 offset:45056
	v_mfma_f32_16x16x32_bf16 v[22:25], v[192:195], v[228:231], v[22:25]
	v_mfma_f32_16x16x32_bf16 v[54:57], v[208:211], v[228:231], v[54:57]
	ds_read_b64_tr_b16 v[174:175], v144 offset:40960
	ds_read_b64_tr_b16 v[176:177], v144 offset:45056
	s_waitcnt lgkmcnt(6)
	v_mfma_f32_16x16x32_bf16 v[26:29], v[192:195], v[232:235], v[26:29]
	v_mfma_f32_16x16x32_bf16 v[58:61], v[208:211], v[232:235], v[58:61]
	ds_read_b64_tr_b16 v[178:179], v145 offset:40960
	ds_read_b64_tr_b16 v[180:181], v145 offset:45056
	v_mfma_f32_16x16x32_bf16 v[30:33], v[192:195], v[236:239], v[30:33]
	v_mfma_f32_16x16x32_bf16 v[62:65], v[208:211], v[236:239], v[62:65]
	ds_read_b64_tr_b16 v[224:225], v146 offset:40960
	ds_read_b64_tr_b16 v[226:227], v146 offset:45056
	s_waitcnt lgkmcnt(6)
	v_mfma_f32_16x16x32_bf16 v[2:5], v[200:203], v[166:169], v[2:5]
	v_mfma_f32_16x16x32_bf16 v[34:37], v[216:219], v[166:169], v[34:37]
	ds_read_b64_tr_b16 v[228:229], v147 offset:40960
	ds_read_b64_tr_b16 v[230:231], v147 offset:45056
	v_mfma_f32_16x16x32_bf16 v[6:9], v[200:203], v[170:173], v[6:9]
	v_mfma_f32_16x16x32_bf16 v[38:41], v[216:219], v[170:173], v[38:41]
	ds_read_b64_tr_b16 v[232:233], v148 offset:40960
	ds_read_b64_tr_b16 v[234:235], v148 offset:45056
	s_waitcnt lgkmcnt(6)
	v_mfma_f32_16x16x32_bf16 v[10:13], v[200:203], v[174:177], v[10:13]
	v_mfma_f32_16x16x32_bf16 v[42:45], v[216:219], v[174:177], v[42:45]
	ds_read_b64_tr_b16 v[236:237], v149 offset:40960
	ds_read_b64_tr_b16 v[238:239], v149 offset:45056
	v_mfma_f32_16x16x32_bf16 v[14:17], v[200:203], v[178:181], v[14:17]
	v_mfma_f32_16x16x32_bf16 v[46:49], v[216:219], v[178:181], v[46:49]
	s_waitcnt lgkmcnt(4)
	v_mfma_f32_16x16x32_bf16 v[18:21], v[200:203], v[224:227], v[18:21]
	v_mfma_f32_16x16x32_bf16 v[50:53], v[216:219], v[224:227], v[50:53]
	v_mfma_f32_16x16x32_bf16 v[22:25], v[200:203], v[228:231], v[22:25]
	v_mfma_f32_16x16x32_bf16 v[54:57], v[216:219], v[228:231], v[54:57]
	s_waitcnt lgkmcnt(0)
	v_mfma_f32_16x16x32_bf16 v[26:29], v[200:203], v[232:235], v[26:29]
	v_mfma_f32_16x16x32_bf16 v[58:61], v[216:219], v[232:235], v[58:61]
	v_mfma_f32_16x16x32_bf16 v[30:33], v[200:203], v[236:239], v[30:33]
	v_mfma_f32_16x16x32_bf16 v[62:65], v[216:219], v[236:239], v[62:65]
	ds_write_b32 v160, v165
	ds_write_b32 v160, v163 offset:256
	s_waitcnt lgkmcnt(0)
	ds_read_b128 v[66:69], v161 offset:0
	ds_read_b128 v[70:73], v161 offset:64
	ds_read_b128 v[74:77], v161 offset:128
	ds_read_b128 v[78:81], v161 offset:192
	ds_read_b128 v[82:85], v161 offset:256
	ds_read_b128 v[86:89], v161 offset:320
	ds_read_b128 v[90:93], v161 offset:384
	ds_read_b128 v[94:97], v161 offset:448
	s_waitcnt lgkmcnt(0)
	v_add_f32_e32 v66, v66, v70
	v_add_f32_e32 v74, v74, v78
	v_add_f32_e32 v66, v66, v74
	v_rcp_f32_e32 v192, v66
	v_add_f32_e32 v67, v67, v71
	v_add_f32_e32 v75, v75, v79
	v_add_f32_e32 v67, v67, v75
	v_rcp_f32_e32 v193, v67
	v_add_f32_e32 v68, v68, v72
	v_add_f32_e32 v76, v76, v80
	v_add_f32_e32 v68, v68, v76
	v_rcp_f32_e32 v194, v68
	v_add_f32_e32 v69, v69, v73
	v_add_f32_e32 v77, v77, v81
	v_add_f32_e32 v69, v69, v77
	v_rcp_f32_e32 v195, v69
	v_add_f32_e32 v82, v82, v86
	v_add_f32_e32 v90, v90, v94
	v_add_f32_e32 v82, v82, v90
	v_rcp_f32_e32 v196, v82
	v_add_f32_e32 v83, v83, v87
	v_add_f32_e32 v91, v91, v95
	v_add_f32_e32 v83, v83, v91
	v_rcp_f32_e32 v197, v83
	v_add_f32_e32 v84, v84, v88
	v_add_f32_e32 v92, v92, v96
	v_add_f32_e32 v84, v84, v92
	v_rcp_f32_e32 v198, v84
	v_add_f32_e32 v85, v85, v89
	v_add_f32_e32 v93, v93, v97
	v_add_f32_e32 v85, v85, v93
	v_rcp_f32_e32 v199, v85
	s_nop 0
	v_mul_f32_e32 v2, v2, v192
	v_mul_f32_e32 v6, v6, v192
	v_cvt_pk_bf16_f32 v200, v2, v6
	global_store_short v156, v200, s[46:47] offset:0
	global_store_short_d16_hi v156, v200, s[46:47] offset:32
	v_mul_f32_e32 v10, v10, v192
	v_mul_f32_e32 v14, v14, v192
	v_cvt_pk_bf16_f32 v201, v10, v14
	global_store_short v156, v201, s[46:47] offset:64
	global_store_short_d16_hi v156, v201, s[46:47] offset:96
	v_mul_f32_e32 v18, v18, v192
	v_mul_f32_e32 v22, v22, v192
	v_cvt_pk_bf16_f32 v202, v18, v22
	global_store_short v156, v202, s[46:47] offset:128
	global_store_short_d16_hi v156, v202, s[46:47] offset:160
	v_mul_f32_e32 v26, v26, v192
	v_mul_f32_e32 v30, v30, v192
	v_cvt_pk_bf16_f32 v203, v26, v30
	global_store_short v156, v203, s[46:47] offset:192
	global_store_short_d16_hi v156, v203, s[46:47] offset:224
	v_mul_f32_e32 v3, v3, v193
	v_mul_f32_e32 v7, v7, v193
	v_cvt_pk_bf16_f32 v204, v3, v7
	global_store_short v156, v204, s[46:47] offset:2048
	global_store_short_d16_hi v156, v204, s[46:47] offset:2080
	v_mul_f32_e32 v11, v11, v193
	v_mul_f32_e32 v15, v15, v193
	v_cvt_pk_bf16_f32 v205, v11, v15
	global_store_short v156, v205, s[46:47] offset:2112
	global_store_short_d16_hi v156, v205, s[46:47] offset:2144
	v_mul_f32_e32 v19, v19, v193
	v_mul_f32_e32 v23, v23, v193
	v_cvt_pk_bf16_f32 v206, v19, v23
	global_store_short v156, v206, s[46:47] offset:2176
	global_store_short_d16_hi v156, v206, s[46:47] offset:2208
	v_mul_f32_e32 v27, v27, v193
	v_mul_f32_e32 v31, v31, v193
	v_cvt_pk_bf16_f32 v207, v27, v31
	global_store_short v156, v207, s[46:47] offset:2240
	global_store_short_d16_hi v156, v207, s[46:47] offset:2272
	v_mul_f32_e32 v4, v4, v194
	v_mul_f32_e32 v8, v8, v194
	v_cvt_pk_bf16_f32 v200, v4, v8
	global_store_short v157, v200, s[46:47] offset:0
	global_store_short_d16_hi v157, v200, s[46:47] offset:32
	v_mul_f32_e32 v12, v12, v194
	v_mul_f32_e32 v16, v16, v194
	v_cvt_pk_bf16_f32 v201, v12, v16
	global_store_short v157, v201, s[46:47] offset:64
	global_store_short_d16_hi v157, v201, s[46:47] offset:96
	v_mul_f32_e32 v20, v20, v194
	v_mul_f32_e32 v24, v24, v194
	v_cvt_pk_bf16_f32 v202, v20, v24
	global_store_short v157, v202, s[46:47] offset:128
	global_store_short_d16_hi v157, v202, s[46:47] offset:160
	v_mul_f32_e32 v28, v28, v194
	v_mul_f32_e32 v32, v32, v194
	v_cvt_pk_bf16_f32 v203, v28, v32
	global_store_short v157, v203, s[46:47] offset:192
	global_store_short_d16_hi v157, v203, s[46:47] offset:224
	v_mul_f32_e32 v5, v5, v195
	v_mul_f32_e32 v9, v9, v195
	v_cvt_pk_bf16_f32 v204, v5, v9
	global_store_short v157, v204, s[46:47] offset:2048
	global_store_short_d16_hi v157, v204, s[46:47] offset:2080
	v_mul_f32_e32 v13, v13, v195
	v_mul_f32_e32 v17, v17, v195
	v_cvt_pk_bf16_f32 v205, v13, v17
	global_store_short v157, v205, s[46:47] offset:2112
	global_store_short_d16_hi v157, v205, s[46:47] offset:2144
	v_mul_f32_e32 v21, v21, v195
	v_mul_f32_e32 v25, v25, v195
	v_cvt_pk_bf16_f32 v206, v21, v25
	global_store_short v157, v206, s[46:47] offset:2176
	global_store_short_d16_hi v157, v206, s[46:47] offset:2208
	v_mul_f32_e32 v29, v29, v195
	v_mul_f32_e32 v33, v33, v195
	v_cvt_pk_bf16_f32 v207, v29, v33
	global_store_short v157, v207, s[46:47] offset:2240
	global_store_short_d16_hi v157, v207, s[46:47] offset:2272
	v_mul_f32_e32 v34, v34, v196
	v_mul_f32_e32 v38, v38, v196
	v_cvt_pk_bf16_f32 v200, v34, v38
	global_store_short v158, v200, s[46:47] offset:0
	global_store_short_d16_hi v158, v200, s[46:47] offset:32
	v_mul_f32_e32 v42, v42, v196
	v_mul_f32_e32 v46, v46, v196
	v_cvt_pk_bf16_f32 v201, v42, v46
	global_store_short v158, v201, s[46:47] offset:64
	global_store_short_d16_hi v158, v201, s[46:47] offset:96
	v_mul_f32_e32 v50, v50, v196
	v_mul_f32_e32 v54, v54, v196
	v_cvt_pk_bf16_f32 v202, v50, v54
	global_store_short v158, v202, s[46:47] offset:128
	global_store_short_d16_hi v158, v202, s[46:47] offset:160
	v_mul_f32_e32 v58, v58, v196
	v_mul_f32_e32 v62, v62, v196
	v_cvt_pk_bf16_f32 v203, v58, v62
	global_store_short v158, v203, s[46:47] offset:192
	global_store_short_d16_hi v158, v203, s[46:47] offset:224
	v_mul_f32_e32 v35, v35, v197
	v_mul_f32_e32 v39, v39, v197
	v_cvt_pk_bf16_f32 v204, v35, v39
	global_store_short v158, v204, s[46:47] offset:2048
	global_store_short_d16_hi v158, v204, s[46:47] offset:2080
	v_mul_f32_e32 v43, v43, v197
	v_mul_f32_e32 v47, v47, v197
	v_cvt_pk_bf16_f32 v205, v43, v47
	global_store_short v158, v205, s[46:47] offset:2112
	global_store_short_d16_hi v158, v205, s[46:47] offset:2144
	v_mul_f32_e32 v51, v51, v197
	v_mul_f32_e32 v55, v55, v197
	v_cvt_pk_bf16_f32 v206, v51, v55
	global_store_short v158, v206, s[46:47] offset:2176
	global_store_short_d16_hi v158, v206, s[46:47] offset:2208
	v_mul_f32_e32 v59, v59, v197
	v_mul_f32_e32 v63, v63, v197
	v_cvt_pk_bf16_f32 v207, v59, v63
	global_store_short v158, v207, s[46:47] offset:2240
	global_store_short_d16_hi v158, v207, s[46:47] offset:2272
	v_mul_f32_e32 v36, v36, v198
	v_mul_f32_e32 v40, v40, v198
	v_cvt_pk_bf16_f32 v200, v36, v40
	global_store_short v159, v200, s[46:47] offset:0
	global_store_short_d16_hi v159, v200, s[46:47] offset:32
	v_mul_f32_e32 v44, v44, v198
	v_mul_f32_e32 v48, v48, v198
	v_cvt_pk_bf16_f32 v201, v44, v48
	global_store_short v159, v201, s[46:47] offset:64
	global_store_short_d16_hi v159, v201, s[46:47] offset:96
	v_mul_f32_e32 v52, v52, v198
	v_mul_f32_e32 v56, v56, v198
	v_cvt_pk_bf16_f32 v202, v52, v56
	global_store_short v159, v202, s[46:47] offset:128
	global_store_short_d16_hi v159, v202, s[46:47] offset:160
	v_mul_f32_e32 v60, v60, v198
	v_mul_f32_e32 v64, v64, v198
	v_cvt_pk_bf16_f32 v203, v60, v64
	global_store_short v159, v203, s[46:47] offset:192
	global_store_short_d16_hi v159, v203, s[46:47] offset:224
	v_mul_f32_e32 v37, v37, v199
	v_mul_f32_e32 v41, v41, v199
	v_cvt_pk_bf16_f32 v204, v37, v41
	global_store_short v159, v204, s[46:47] offset:2048
	global_store_short_d16_hi v159, v204, s[46:47] offset:2080
	v_mul_f32_e32 v45, v45, v199
	v_mul_f32_e32 v49, v49, v199
	v_cvt_pk_bf16_f32 v205, v45, v49
	global_store_short v159, v205, s[46:47] offset:2112
	global_store_short_d16_hi v159, v205, s[46:47] offset:2144
	v_mul_f32_e32 v53, v53, v199
	v_mul_f32_e32 v57, v57, v199
	v_cvt_pk_bf16_f32 v206, v53, v57
	global_store_short v159, v206, s[46:47] offset:2176
	global_store_short_d16_hi v159, v206, s[46:47] offset:2208
	v_mul_f32_e32 v61, v61, v199
	v_mul_f32_e32 v65, v65, v199
	v_cvt_pk_bf16_f32 v207, v61, v65
	global_store_short v159, v207, s[46:47] offset:2240
	global_store_short_d16_hi v159, v207, s[46:47] offset:2272
	s_mov_b32 s46, s18
	s_mov_b32 s47, s19
	v_mov_b32_e32 v2, 0
	v_mov_b32_e32 v3, 0
	v_mov_b32_e32 v4, 0
	v_mov_b32_e32 v5, 0
	v_mov_b32_e32 v6, 0
	v_mov_b32_e32 v7, 0
	v_mov_b32_e32 v8, 0
	v_mov_b32_e32 v9, 0
	v_mov_b32_e32 v10, 0
	v_mov_b32_e32 v11, 0
	v_mov_b32_e32 v12, 0
	v_mov_b32_e32 v13, 0
	v_mov_b32_e32 v14, 0
	v_mov_b32_e32 v15, 0
	v_mov_b32_e32 v16, 0
	v_mov_b32_e32 v17, 0
	v_mov_b32_e32 v18, 0
	v_mov_b32_e32 v19, 0
	v_mov_b32_e32 v20, 0
	v_mov_b32_e32 v21, 0
	v_mov_b32_e32 v22, 0
	v_mov_b32_e32 v23, 0
	v_mov_b32_e32 v24, 0
	v_mov_b32_e32 v25, 0
	v_mov_b32_e32 v26, 0
	v_mov_b32_e32 v27, 0
	v_mov_b32_e32 v28, 0
	v_mov_b32_e32 v29, 0
	v_mov_b32_e32 v30, 0
	v_mov_b32_e32 v31, 0
	v_mov_b32_e32 v32, 0
	v_mov_b32_e32 v33, 0
	v_mov_b32_e32 v34, 0
	v_mov_b32_e32 v35, 0
	v_mov_b32_e32 v36, 0
	v_mov_b32_e32 v37, 0
	v_mov_b32_e32 v38, 0
	v_mov_b32_e32 v39, 0
	v_mov_b32_e32 v40, 0
	v_mov_b32_e32 v41, 0
	v_mov_b32_e32 v42, 0
	v_mov_b32_e32 v43, 0
	v_mov_b32_e32 v44, 0
	v_mov_b32_e32 v45, 0
	v_mov_b32_e32 v46, 0
	v_mov_b32_e32 v47, 0
	v_mov_b32_e32 v48, 0
	v_mov_b32_e32 v49, 0
	v_mov_b32_e32 v50, 0
	v_mov_b32_e32 v51, 0
	v_mov_b32_e32 v52, 0
	v_mov_b32_e32 v53, 0
	v_mov_b32_e32 v54, 0
	v_mov_b32_e32 v55, 0
	v_mov_b32_e32 v56, 0
	v_mov_b32_e32 v57, 0
	v_mov_b32_e32 v58, 0
	v_mov_b32_e32 v59, 0
	v_mov_b32_e32 v60, 0
	v_mov_b32_e32 v61, 0
	v_mov_b32_e32 v62, 0
	v_mov_b32_e32 v63, 0
	v_mov_b32_e32 v64, 0
	v_mov_b32_e32 v65, 0
	v_mov_b32_e32 v165, 0
	v_mov_b32_e32 v163, 0
	s_waitcnt vmcnt(63)
	s_add_i32 s3, s3, s33
	s_cmpk_lt_i32 s3, 0x400
	s_cbranch_scc1 .Lattn_unit

.LBB0_493:
	ds_read_b128 v[74:77], v170
	ds_read_b128 v[78:81], v170 offset:1024
	ds_read_b128 v[154:157], v170 offset:2048
	ds_read_b128 v[158:161], v170 offset:3072
	ds_read_b128 v[162:165], v171
	ds_read_b128 v[174:177], v171 offset:1024
	ds_read_b128 v[178:181], v171 offset:2048
	ds_read_b128 v[182:185], v171 offset:3072
	s_add_u32 s42, s40, 0xfffc0080
	s_addc_u32 s43, s41, -1
	s_cmp_eq_u32 s83, 12
	s_cselect_b32 s45, s25, s43
	s_cselect_b32 s44, s39, s42
	s_cselect_b32 s43, s19, s82
	s_cselect_b32 s42, s80, s81
	v_lshl_add_u64 v[166:167], s[40:41], 0, v[146:147]
	s_add_i32 m0, s64, 0xc000
	ds_read_b128 v[186:189], v172
	ds_read_b128 v[190:193], v172 offset:1024
	ds_read_b128 v[194:197], v172 offset:2048
	ds_read_b128 v[198:201], v172 offset:3072
	ds_read_b128 v[202:205], v172 offset:4096
	ds_read_b128 v[206:209], v172 offset:5120
	ds_read_b128 v[210:213], v172 offset:6144
	ds_read_b128 v[214:217], v172 offset:7168
	global_load_lds_dwordx4 v[166:167], off
	v_lshl_add_u64 v[166:167], s[40:41], 0, v[148:149]
	s_add_i32 m0, s64, 0xe000
	s_nop 0
	global_load_lds_dwordx4 v[166:167], off
	s_waitcnt vmcnt(8)
	s_waitcnt lgkmcnt(0)
	s_barrier
	s_waitcnt lgkmcnt(0)
	v_mfma_f32_16x16x32_bf16 v[86:89], v[74:77], v[186:189], v[86:89]
	v_mfma_f32_16x16x32_bf16 v[82:85], v[154:157], v[186:189], v[82:85]
	v_mfma_f32_16x16x32_bf16 v[126:129], v[74:77], v[194:197], v[126:129]
	v_mfma_f32_16x16x32_bf16 v[122:125], v[154:157], v[194:197], v[122:125]
	v_mfma_f32_16x16x32_bf16 v[110:113], v[74:77], v[202:205], v[110:113]
	v_mfma_f32_16x16x32_bf16 v[106:109], v[154:157], v[202:205], v[106:109]
	v_mfma_f32_16x16x32_bf16 v[94:97], v[74:77], v[210:213], v[94:97]
	v_mfma_f32_16x16x32_bf16 v[90:93], v[154:157], v[210:213], v[90:93]
	v_mfma_f32_16x16x32_bf16 v[86:89], v[78:81], v[190:193], v[86:89]
	v_mfma_f32_16x16x32_bf16 v[82:85], v[158:161], v[190:193], v[82:85]
	v_mfma_f32_16x16x32_bf16 v[126:129], v[78:81], v[198:201], v[126:129]
	v_mfma_f32_16x16x32_bf16 v[122:125], v[158:161], v[198:201], v[122:125]
	v_mfma_f32_16x16x32_bf16 v[110:113], v[78:81], v[206:209], v[110:113]
	v_mfma_f32_16x16x32_bf16 v[106:109], v[158:161], v[206:209], v[106:109]
	v_mfma_f32_16x16x32_bf16 v[94:97], v[78:81], v[214:217], v[94:97]
	v_mfma_f32_16x16x32_bf16 v[90:93], v[158:161], v[214:217], v[90:93]
	v_mfma_f32_16x16x32_bf16 v[134:137], v[162:165], v[186:189], v[134:137]
	v_mfma_f32_16x16x32_bf16 v[130:133], v[178:181], v[186:189], v[130:133]
	v_mfma_f32_16x16x32_bf16 v[118:121], v[162:165], v[194:197], v[118:121]
	v_mfma_f32_16x16x32_bf16 v[114:117], v[178:181], v[194:197], v[114:117]
	v_mfma_f32_16x16x32_bf16 v[102:105], v[162:165], v[202:205], v[102:105]
	v_mfma_f32_16x16x32_bf16 v[98:101], v[178:181], v[202:205], v[98:101]
	v_mfma_f32_16x16x32_bf16 v[70:73], v[162:165], v[210:213], v[70:73]
	v_mfma_f32_16x16x32_bf16 v[66:69], v[178:181], v[210:213], v[66:69]
	v_mfma_f32_16x16x32_bf16 v[134:137], v[174:177], v[190:193], v[134:137]
	v_mfma_f32_16x16x32_bf16 v[130:133], v[182:185], v[190:193], v[130:133]
	v_mfma_f32_16x16x32_bf16 v[118:121], v[174:177], v[198:201], v[118:121]
	v_mfma_f32_16x16x32_bf16 v[114:117], v[182:185], v[198:201], v[114:117]
	v_mfma_f32_16x16x32_bf16 v[102:105], v[174:177], v[206:209], v[102:105]
	v_mfma_f32_16x16x32_bf16 v[98:101], v[182:185], v[206:209], v[98:101]
	v_mfma_f32_16x16x32_bf16 v[70:73], v[174:177], v[214:217], v[70:73]
	v_mfma_f32_16x16x32_bf16 v[66:69], v[182:185], v[214:217], v[66:69]
	s_barrier
	s_add_i32 s60, s77, s63
	v_lshl_add_u64 v[166:167], s[42:43], 0, v[140:141]
	s_mov_b32 m0, s60
	ds_read_b128 v[186:189], v172 offset:16384
	ds_read_b128 v[190:193], v172 offset:17408
	ds_read_b128 v[194:197], v172 offset:18432
	ds_read_b128 v[198:201], v172 offset:19456
	ds_read_b128 v[202:205], v172 offset:20480
	ds_read_b128 v[206:209], v172 offset:21504
	ds_read_b128 v[210:213], v172 offset:22528
	ds_read_b128 v[214:217], v172 offset:23552
	global_load_lds_dwordx4 v[166:167], off
	s_add_i32 m0, s60, 0x2000
	s_add_u32 s60, s42, 0x40000
	v_lshl_add_u64 v[218:219], s[42:43], 0, v[144:145]
	s_addc_u32 s61, s43, 0
	s_add_i32 s84, s78, s63
	global_load_lds_dwordx4 v[218:219], off
	v_lshl_add_u64 v[220:221], s[60:61], 0, v[140:141]
	s_mov_b32 m0, s84
	v_lshl_add_u64 v[222:223], s[44:45], 0, v[142:143]
	global_load_lds_dwordx4 v[220:221], off
	v_lshl_add_u64 v[220:221], s[60:61], 0, v[144:145]
	s_add_i32 m0, s84, 0x2000
	s_nop 0
	global_load_lds_dwordx4 v[220:221], off
	v_lshl_add_u64 v[220:221], s[44:45], 0, v[138:139]
	s_mov_b32 m0, s64
	s_nop 0
	global_load_lds_dwordx4 v[220:221], off
	s_mov_b32 m0, s65
	s_nop 0
	global_load_lds_dwordx4 v[222:223], off
	s_waitcnt vmcnt(8)
	s_waitcnt lgkmcnt(0)
	s_barrier
	s_waitcnt lgkmcnt(0)
	v_mfma_f32_16x16x32_bf16 v[62:65], v[74:77], v[186:189], v[62:65]
	v_mfma_f32_16x16x32_bf16 v[58:61], v[154:157], v[186:189], v[58:61]
	v_mfma_f32_16x16x32_bf16 v[46:49], v[74:77], v[194:197], v[46:49]
	v_mfma_f32_16x16x32_bf16 v[42:45], v[154:157], v[194:197], v[42:45]
	v_mfma_f32_16x16x32_bf16 v[30:33], v[74:77], v[202:205], v[30:33]
	v_mfma_f32_16x16x32_bf16 v[26:29], v[154:157], v[202:205], v[26:29]
	v_mfma_f32_16x16x32_bf16 v[14:17], v[74:77], v[210:213], v[14:17]
	v_mfma_f32_16x16x32_bf16 v[10:13], v[154:157], v[210:213], v[10:13]
	v_mfma_f32_16x16x32_bf16 v[62:65], v[78:81], v[190:193], v[62:65]
	v_mfma_f32_16x16x32_bf16 v[58:61], v[158:161], v[190:193], v[58:61]
	v_mfma_f32_16x16x32_bf16 v[46:49], v[78:81], v[198:201], v[46:49]
	v_mfma_f32_16x16x32_bf16 v[42:45], v[158:161], v[198:201], v[42:45]
	v_mfma_f32_16x16x32_bf16 v[30:33], v[78:81], v[206:209], v[30:33]
	v_mfma_f32_16x16x32_bf16 v[26:29], v[158:161], v[206:209], v[26:29]
	v_mfma_f32_16x16x32_bf16 v[14:17], v[78:81], v[214:217], v[14:17]
	v_mfma_f32_16x16x32_bf16 v[10:13], v[158:161], v[214:217], v[10:13]
	v_mfma_f32_16x16x32_bf16 v[54:57], v[162:165], v[186:189], v[54:57]
	v_mfma_f32_16x16x32_bf16 v[50:53], v[178:181], v[186:189], v[50:53]
	v_mfma_f32_16x16x32_bf16 v[38:41], v[162:165], v[194:197], v[38:41]
	v_mfma_f32_16x16x32_bf16 v[34:37], v[178:181], v[194:197], v[34:37]
	v_mfma_f32_16x16x32_bf16 v[22:25], v[162:165], v[202:205], v[22:25]
	v_mfma_f32_16x16x32_bf16 v[18:21], v[178:181], v[202:205], v[18:21]
	v_mfma_f32_16x16x32_bf16 v[6:9], v[162:165], v[210:213], v[6:9]
	v_mfma_f32_16x16x32_bf16 v[2:5], v[178:181], v[210:213], v[2:5]
	v_mfma_f32_16x16x32_bf16 v[54:57], v[174:177], v[190:193], v[54:57]
	v_mfma_f32_16x16x32_bf16 v[50:53], v[182:185], v[190:193], v[50:53]
	v_mfma_f32_16x16x32_bf16 v[38:41], v[174:177], v[198:201], v[38:41]
	v_mfma_f32_16x16x32_bf16 v[34:37], v[182:185], v[198:201], v[34:37]
	v_mfma_f32_16x16x32_bf16 v[22:25], v[174:177], v[206:209], v[22:25]
	v_mfma_f32_16x16x32_bf16 v[18:21], v[182:185], v[206:209], v[18:21]
	v_mfma_f32_16x16x32_bf16 v[6:9], v[174:177], v[214:217], v[6:9]
	v_mfma_f32_16x16x32_bf16 v[2:5], v[182:185], v[214:217], v[2:5]
	s_barrier
	s_add_i32 s60, 0, 0x18000
	s_add_i32 s61, 0, 0x1c000
	v_add_u32_e32 v158, s60, v168
	v_add_u32_e32 v182, s61, v168
	ds_read_b128 v[74:77], v158
	ds_read_b128 v[78:81], v158 offset:1024
	ds_read_b128 v[154:157], v158 offset:2048
	ds_read_b128 v[158:161], v158 offset:3072
	ds_read_b128 v[162:165], v182
	ds_read_b128 v[174:177], v182 offset:1024
	ds_read_b128 v[178:181], v182 offset:2048
	ds_read_b128 v[182:185], v182 offset:3072
	s_add_u32 s44, s44, 0x40000
	s_addc_u32 s45, s45, 0
	s_mov_b32 m0, s66
	v_lshl_add_u64 v[224:225], s[44:45], 0, v[138:139]
	ds_read_b128 v[186:189], v172 offset:32768
	ds_read_b128 v[190:193], v172 offset:33792
	ds_read_b128 v[194:197], v172 offset:34816
	ds_read_b128 v[198:201], v172 offset:35840
	ds_read_b128 v[202:205], v172 offset:36864
	ds_read_b128 v[206:209], v172 offset:37888
	ds_read_b128 v[210:213], v172 offset:38912
	ds_read_b128 v[214:217], v172 offset:39936
	global_load_lds_dwordx4 v[224:225], off
	v_lshl_add_u64 v[224:225], s[44:45], 0, v[142:143]
	s_mov_b32 m0, s67
	s_nop 0
	global_load_lds_dwordx4 v[224:225], off
	s_waitcnt vmcnt(8)
	s_waitcnt lgkmcnt(0)
	s_barrier
	s_waitcnt lgkmcnt(0)
	v_mfma_f32_16x16x32_bf16 v[86:89], v[74:77], v[186:189], v[86:89]
	v_mfma_f32_16x16x32_bf16 v[82:85], v[154:157], v[186:189], v[82:85]
	v_mfma_f32_16x16x32_bf16 v[126:129], v[74:77], v[194:197], v[126:129]
	v_mfma_f32_16x16x32_bf16 v[122:125], v[154:157], v[194:197], v[122:125]
	v_mfma_f32_16x16x32_bf16 v[110:113], v[74:77], v[202:205], v[110:113]
	v_mfma_f32_16x16x32_bf16 v[106:109], v[154:157], v[202:205], v[106:109]
	v_mfma_f32_16x16x32_bf16 v[94:97], v[74:77], v[210:213], v[94:97]
	v_mfma_f32_16x16x32_bf16 v[90:93], v[154:157], v[210:213], v[90:93]
	v_mfma_f32_16x16x32_bf16 v[86:89], v[78:81], v[190:193], v[86:89]
	v_mfma_f32_16x16x32_bf16 v[82:85], v[158:161], v[190:193], v[82:85]
	v_mfma_f32_16x16x32_bf16 v[126:129], v[78:81], v[198:201], v[126:129]
	v_mfma_f32_16x16x32_bf16 v[122:125], v[158:161], v[198:201], v[122:125]
	v_mfma_f32_16x16x32_bf16 v[110:113], v[78:81], v[206:209], v[110:113]
	v_mfma_f32_16x16x32_bf16 v[106:109], v[158:161], v[206:209], v[106:109]
	v_mfma_f32_16x16x32_bf16 v[94:97], v[78:81], v[214:217], v[94:97]
	v_mfma_f32_16x16x32_bf16 v[90:93], v[158:161], v[214:217], v[90:93]
	v_mfma_f32_16x16x32_bf16 v[134:137], v[162:165], v[186:189], v[134:137]
	v_mfma_f32_16x16x32_bf16 v[130:133], v[178:181], v[186:189], v[130:133]
	v_mfma_f32_16x16x32_bf16 v[118:121], v[162:165], v[194:197], v[118:121]
	v_mfma_f32_16x16x32_bf16 v[114:117], v[178:181], v[194:197], v[114:117]
	v_mfma_f32_16x16x32_bf16 v[102:105], v[162:165], v[202:205], v[102:105]
	v_mfma_f32_16x16x32_bf16 v[98:101], v[178:181], v[202:205], v[98:101]
	v_mfma_f32_16x16x32_bf16 v[70:73], v[162:165], v[210:213], v[70:73]
	v_mfma_f32_16x16x32_bf16 v[66:69], v[178:181], v[210:213], v[66:69]
	v_mfma_f32_16x16x32_bf16 v[134:137], v[174:177], v[190:193], v[134:137]
	v_mfma_f32_16x16x32_bf16 v[130:133], v[182:185], v[190:193], v[130:133]
	v_mfma_f32_16x16x32_bf16 v[118:121], v[174:177], v[198:201], v[118:121]
	v_mfma_f32_16x16x32_bf16 v[114:117], v[182:185], v[198:201], v[114:117]
	v_mfma_f32_16x16x32_bf16 v[102:105], v[174:177], v[206:209], v[102:105]
	v_mfma_f32_16x16x32_bf16 v[98:101], v[182:185], v[206:209], v[98:101]
	v_mfma_f32_16x16x32_bf16 v[70:73], v[174:177], v[214:217], v[70:73]
	v_mfma_f32_16x16x32_bf16 v[66:69], v[182:185], v[214:217], v[66:69]
	s_barrier
	s_add_i32 s44, s60, s63
	v_lshl_add_u64 v[166:167], v[166:167], 0, s[14:15]
	s_mov_b32 m0, s44
	ds_read_b128 v[186:189], v172 offset:49152
	ds_read_b128 v[190:193], v172 offset:50176
	ds_read_b128 v[194:197], v172 offset:51200
	ds_read_b128 v[198:201], v172 offset:52224
	ds_read_b128 v[202:205], v172 offset:53248
	ds_read_b128 v[206:209], v172 offset:54272
	ds_read_b128 v[210:213], v172 offset:55296
	ds_read_b128 v[214:217], v172 offset:56320
	global_load_lds_dwordx4 v[166:167], off
	s_add_i32 m0, s44, 0x2000
	s_add_u32 s42, s42, 0x40080
	v_lshl_add_u64 v[166:167], v[218:219], 0, s[14:15]
	s_addc_u32 s43, s43, 0
	s_add_i32 s44, s61, s63
	global_load_lds_dwordx4 v[166:167], off
	v_lshl_add_u64 v[166:167], s[42:43], 0, v[140:141]
	s_mov_b32 m0, s44
	s_nop 0
	global_load_lds_dwordx4 v[166:167], off
	v_lshl_add_u64 v[166:167], s[42:43], 0, v[144:145]
	s_add_i32 m0, s44, 0x2000
	s_nop 0
	global_load_lds_dwordx4 v[166:167], off
	v_lshl_add_u64 v[166:167], v[220:221], 0, s[14:15]
	s_mov_b32 m0, s74
	s_nop 0
	global_load_lds_dwordx4 v[166:167], off
	v_lshl_add_u64 v[166:167], v[222:223], 0, s[14:15]
	s_mov_b32 m0, s75
	s_nop 0
	global_load_lds_dwordx4 v[166:167], off
	s_waitcnt vmcnt(8)
	s_waitcnt lgkmcnt(0)
	s_barrier
	s_waitcnt lgkmcnt(0)
	v_mfma_f32_16x16x32_bf16 v[62:65], v[74:77], v[186:189], v[62:65]
	v_mfma_f32_16x16x32_bf16 v[58:61], v[154:157], v[186:189], v[58:61]
	v_mfma_f32_16x16x32_bf16 v[46:49], v[74:77], v[194:197], v[46:49]
	v_mfma_f32_16x16x32_bf16 v[42:45], v[154:157], v[194:197], v[42:45]
	v_mfma_f32_16x16x32_bf16 v[30:33], v[74:77], v[202:205], v[30:33]
	v_mfma_f32_16x16x32_bf16 v[26:29], v[154:157], v[202:205], v[26:29]
	v_mfma_f32_16x16x32_bf16 v[14:17], v[74:77], v[210:213], v[14:17]
	v_mfma_f32_16x16x32_bf16 v[10:13], v[154:157], v[210:213], v[10:13]
	v_mfma_f32_16x16x32_bf16 v[62:65], v[78:81], v[190:193], v[62:65]
	v_mfma_f32_16x16x32_bf16 v[58:61], v[158:161], v[190:193], v[58:61]
	v_mfma_f32_16x16x32_bf16 v[46:49], v[78:81], v[198:201], v[46:49]
	v_mfma_f32_16x16x32_bf16 v[42:45], v[158:161], v[198:201], v[42:45]
	v_mfma_f32_16x16x32_bf16 v[30:33], v[78:81], v[206:209], v[30:33]
	v_mfma_f32_16x16x32_bf16 v[26:29], v[158:161], v[206:209], v[26:29]
	v_mfma_f32_16x16x32_bf16 v[14:17], v[78:81], v[214:217], v[14:17]
	v_mfma_f32_16x16x32_bf16 v[10:13], v[158:161], v[214:217], v[10:13]
	v_mfma_f32_16x16x32_bf16 v[54:57], v[162:165], v[186:189], v[54:57]
	v_mfma_f32_16x16x32_bf16 v[50:53], v[178:181], v[186:189], v[50:53]
	v_mfma_f32_16x16x32_bf16 v[38:41], v[162:165], v[194:197], v[38:41]
	v_mfma_f32_16x16x32_bf16 v[34:37], v[178:181], v[194:197], v[34:37]
	v_mfma_f32_16x16x32_bf16 v[22:25], v[162:165], v[202:205], v[22:25]
	v_mfma_f32_16x16x32_bf16 v[18:21], v[178:181], v[202:205], v[18:21]
	v_mfma_f32_16x16x32_bf16 v[6:9], v[162:165], v[210:213], v[6:9]
	v_mfma_f32_16x16x32_bf16 v[2:5], v[178:181], v[210:213], v[2:5]
	v_mfma_f32_16x16x32_bf16 v[54:57], v[174:177], v[190:193], v[54:57]
	v_mfma_f32_16x16x32_bf16 v[50:53], v[182:185], v[190:193], v[50:53]
	v_mfma_f32_16x16x32_bf16 v[38:41], v[174:177], v[198:201], v[38:41]
	v_mfma_f32_16x16x32_bf16 v[34:37], v[182:185], v[198:201], v[34:37]
	v_mfma_f32_16x16x32_bf16 v[22:25], v[174:177], v[206:209], v[22:25]
	v_mfma_f32_16x16x32_bf16 v[18:21], v[182:185], v[206:209], v[18:21]
	v_mfma_f32_16x16x32_bf16 v[6:9], v[174:177], v[214:217], v[6:9]
	v_mfma_f32_16x16x32_bf16 v[2:5], v[182:185], v[214:217], v[2:5]
	s_barrier
	s_add_i32 s83, s83, 2
	s_add_u32 s40, s40, 0x100
	s_addc_u32 s41, s41, 0
	s_add_u32 s81, s81, 0x100
	s_addc_u32 s82, s82, 0
	s_cmp_gt_u32 s83, 13
	s_cbranch_scc0 .LBB0_493
	s_and_b64 vcc, exec, s[16:17]
	s_cbranch_vccz .LBB0_496
	s_barrier

.LBB0_584:
	ds_read_b128 v[130:133], v166
	ds_read_b128 v[134:137], v166 offset:1024
	ds_read_b128 v[138:141], v166 offset:2048
	ds_read_b128 v[142:145], v166 offset:3072
	ds_read_b128 v[170:173], v167
	ds_read_b128 v[174:177], v167 offset:1024
	ds_read_b128 v[178:181], v167 offset:2048
	ds_read_b128 v[182:185], v167 offset:3072
	s_add_u32 s36, s30, 0xfffc0080
	s_addc_u32 s37, s31, -1
	s_cmp_eq_u32 s75, 12
	s_cselect_b32 s39, s17, s37
	s_cselect_b32 s38, s71, s36
	s_cselect_b32 s37, s15, s74
	s_cselect_b32 s36, s72, s73
	v_lshl_add_u64 v[220:221], s[30:31], 0, v[154:155]
	s_add_i32 m0, s29, 0xc000
	ds_read_b128 v[186:189], v168
	ds_read_b128 v[190:193], v168 offset:1024
	ds_read_b128 v[194:197], v168 offset:2048
	ds_read_b128 v[198:201], v168 offset:3072
	ds_read_b128 v[202:205], v168 offset:4096
	ds_read_b128 v[206:209], v168 offset:5120
	ds_read_b128 v[212:215], v168 offset:6144
	ds_read_b128 v[216:219], v168 offset:7168
	global_load_lds_dwordx4 v[220:221], off
	v_lshl_add_u64 v[220:221], s[30:31], 0, v[156:157]
	s_add_i32 m0, s29, 0xe000
	s_nop 0
	global_load_lds_dwordx4 v[220:221], off
	s_waitcnt vmcnt(8)
	s_waitcnt lgkmcnt(0)
	s_barrier
	s_waitcnt lgkmcnt(0)
	v_mfma_f32_16x16x32_bf16 v[126:129], v[130:133], v[186:189], v[126:129]
	v_mfma_f32_16x16x32_bf16 v[122:125], v[138:141], v[186:189], v[122:125]
	v_mfma_f32_16x16x32_bf16 v[110:113], v[130:133], v[194:197], v[110:113]
	v_mfma_f32_16x16x32_bf16 v[106:109], v[138:141], v[194:197], v[106:109]
	v_mfma_f32_16x16x32_bf16 v[94:97], v[130:133], v[202:205], v[94:97]
	v_mfma_f32_16x16x32_bf16 v[90:93], v[138:141], v[202:205], v[90:93]
	v_mfma_f32_16x16x32_bf16 v[78:81], v[130:133], v[212:215], v[78:81]
	v_mfma_f32_16x16x32_bf16 v[74:77], v[138:141], v[212:215], v[74:77]
	v_mfma_f32_16x16x32_bf16 v[126:129], v[134:137], v[190:193], v[126:129]
	v_mfma_f32_16x16x32_bf16 v[122:125], v[142:145], v[190:193], v[122:125]
	v_mfma_f32_16x16x32_bf16 v[110:113], v[134:137], v[198:201], v[110:113]
	v_mfma_f32_16x16x32_bf16 v[106:109], v[142:145], v[198:201], v[106:109]
	v_mfma_f32_16x16x32_bf16 v[94:97], v[134:137], v[206:209], v[94:97]
	v_mfma_f32_16x16x32_bf16 v[90:93], v[142:145], v[206:209], v[90:93]
	v_mfma_f32_16x16x32_bf16 v[78:81], v[134:137], v[216:219], v[78:81]
	v_mfma_f32_16x16x32_bf16 v[74:77], v[142:145], v[216:219], v[74:77]
	v_mfma_f32_16x16x32_bf16 v[118:121], v[170:173], v[186:189], v[118:121]
	v_mfma_f32_16x16x32_bf16 v[114:117], v[178:181], v[186:189], v[114:117]
	v_mfma_f32_16x16x32_bf16 v[102:105], v[170:173], v[194:197], v[102:105]
	v_mfma_f32_16x16x32_bf16 v[98:101], v[178:181], v[194:197], v[98:101]
	v_mfma_f32_16x16x32_bf16 v[86:89], v[170:173], v[202:205], v[86:89]
	v_mfma_f32_16x16x32_bf16 v[82:85], v[178:181], v[202:205], v[82:85]
	v_mfma_f32_16x16x32_bf16 v[70:73], v[170:173], v[212:215], v[70:73]
	v_mfma_f32_16x16x32_bf16 v[66:69], v[178:181], v[212:215], v[66:69]
	v_mfma_f32_16x16x32_bf16 v[118:121], v[174:177], v[190:193], v[118:121]
	v_mfma_f32_16x16x32_bf16 v[114:117], v[182:185], v[190:193], v[114:117]
	v_mfma_f32_16x16x32_bf16 v[102:105], v[174:177], v[198:201], v[102:105]
	v_mfma_f32_16x16x32_bf16 v[98:101], v[182:185], v[198:201], v[98:101]
	v_mfma_f32_16x16x32_bf16 v[86:89], v[174:177], v[206:209], v[86:89]
	v_mfma_f32_16x16x32_bf16 v[82:85], v[182:185], v[206:209], v[82:85]
	v_mfma_f32_16x16x32_bf16 v[70:73], v[174:177], v[216:219], v[70:73]
	v_mfma_f32_16x16x32_bf16 v[66:69], v[182:185], v[216:219], v[66:69]
	s_barrier
	s_add_i32 s60, s65, s41
	v_lshl_add_u64 v[220:221], s[36:37], 0, v[150:151]
	s_mov_b32 m0, s60
	ds_read_b128 v[186:189], v168 offset:16384
	ds_read_b128 v[190:193], v168 offset:17408
	ds_read_b128 v[194:197], v168 offset:18432
	ds_read_b128 v[198:201], v168 offset:19456
	ds_read_b128 v[202:205], v168 offset:20480
	ds_read_b128 v[206:209], v168 offset:21504
	ds_read_b128 v[212:215], v168 offset:22528
	ds_read_b128 v[216:219], v168 offset:23552
	global_load_lds_dwordx4 v[220:221], off
	s_add_i32 m0, s60, 0x2000
	s_add_u32 s60, s36, 0x40000
	v_lshl_add_u64 v[222:223], s[36:37], 0, v[146:147]
	s_addc_u32 s61, s37, 0
	s_add_i32 s76, s66, s41
	global_load_lds_dwordx4 v[222:223], off
	v_lshl_add_u64 v[224:225], s[60:61], 0, v[150:151]
	s_mov_b32 m0, s76
	v_lshl_add_u64 v[226:227], s[38:39], 0, v[148:149]
	global_load_lds_dwordx4 v[224:225], off
	v_lshl_add_u64 v[224:225], s[60:61], 0, v[146:147]
	s_add_i32 m0, s76, 0x2000
	s_nop 0
	global_load_lds_dwordx4 v[224:225], off
	v_lshl_add_u64 v[224:225], s[38:39], 0, v[152:153]
	s_mov_b32 m0, s29
	s_nop 0
	global_load_lds_dwordx4 v[224:225], off
	s_mov_b32 m0, s45
	s_nop 0
	global_load_lds_dwordx4 v[226:227], off
	s_waitcnt vmcnt(8)
	s_waitcnt lgkmcnt(0)
	s_barrier
	s_waitcnt lgkmcnt(0)
	v_mfma_f32_16x16x32_bf16 v[62:65], v[130:133], v[186:189], v[62:65]
	v_mfma_f32_16x16x32_bf16 v[58:61], v[138:141], v[186:189], v[58:61]
	v_mfma_f32_16x16x32_bf16 v[46:49], v[130:133], v[194:197], v[46:49]
	v_mfma_f32_16x16x32_bf16 v[42:45], v[138:141], v[194:197], v[42:45]
	v_mfma_f32_16x16x32_bf16 v[30:33], v[130:133], v[202:205], v[30:33]
	v_mfma_f32_16x16x32_bf16 v[26:29], v[138:141], v[202:205], v[26:29]
	v_mfma_f32_16x16x32_bf16 v[14:17], v[130:133], v[212:215], v[14:17]
	v_mfma_f32_16x16x32_bf16 v[10:13], v[138:141], v[212:215], v[10:13]
	v_mfma_f32_16x16x32_bf16 v[62:65], v[134:137], v[190:193], v[62:65]
	v_mfma_f32_16x16x32_bf16 v[58:61], v[142:145], v[190:193], v[58:61]
	v_mfma_f32_16x16x32_bf16 v[46:49], v[134:137], v[198:201], v[46:49]
	v_mfma_f32_16x16x32_bf16 v[42:45], v[142:145], v[198:201], v[42:45]
	v_mfma_f32_16x16x32_bf16 v[30:33], v[134:137], v[206:209], v[30:33]
	v_mfma_f32_16x16x32_bf16 v[26:29], v[142:145], v[206:209], v[26:29]
	v_mfma_f32_16x16x32_bf16 v[14:17], v[134:137], v[216:219], v[14:17]
	v_mfma_f32_16x16x32_bf16 v[10:13], v[142:145], v[216:219], v[10:13]
	v_mfma_f32_16x16x32_bf16 v[54:57], v[170:173], v[186:189], v[54:57]
	v_mfma_f32_16x16x32_bf16 v[50:53], v[178:181], v[186:189], v[50:53]
	v_mfma_f32_16x16x32_bf16 v[38:41], v[170:173], v[194:197], v[38:41]
	v_mfma_f32_16x16x32_bf16 v[34:37], v[178:181], v[194:197], v[34:37]
	v_mfma_f32_16x16x32_bf16 v[22:25], v[170:173], v[202:205], v[22:25]
	v_mfma_f32_16x16x32_bf16 v[18:21], v[178:181], v[202:205], v[18:21]
	v_mfma_f32_16x16x32_bf16 v[6:9], v[170:173], v[212:215], v[6:9]
	v_mfma_f32_16x16x32_bf16 v[2:5], v[178:181], v[212:215], v[2:5]
	v_mfma_f32_16x16x32_bf16 v[54:57], v[174:177], v[190:193], v[54:57]
	v_mfma_f32_16x16x32_bf16 v[50:53], v[182:185], v[190:193], v[50:53]
	v_mfma_f32_16x16x32_bf16 v[38:41], v[174:177], v[198:201], v[38:41]
	v_mfma_f32_16x16x32_bf16 v[34:37], v[182:185], v[198:201], v[34:37]
	v_mfma_f32_16x16x32_bf16 v[22:25], v[174:177], v[206:209], v[22:25]
	v_mfma_f32_16x16x32_bf16 v[18:21], v[182:185], v[206:209], v[18:21]
	v_mfma_f32_16x16x32_bf16 v[6:9], v[174:177], v[216:219], v[6:9]
	v_mfma_f32_16x16x32_bf16 v[2:5], v[182:185], v[216:219], v[2:5]
	s_barrier
	s_add_i32 s60, 0, 0x18000
	s_add_i32 s61, 0, 0x1c000
	v_add_u32_e32 v142, s60, v164
	v_add_u32_e32 v169, s61, v164
	ds_read_b128 v[130:133], v142
	ds_read_b128 v[134:137], v142 offset:1024
	ds_read_b128 v[138:141], v142 offset:2048
	ds_read_b128 v[142:145], v142 offset:3072
	ds_read_b128 v[170:173], v169
	ds_read_b128 v[174:177], v169 offset:1024
	ds_read_b128 v[178:181], v169 offset:2048
	ds_read_b128 v[182:185], v169 offset:3072
	s_add_u32 s38, s38, 0x40000
	s_addc_u32 s39, s39, 0
	s_mov_b32 m0, s46
	v_lshl_add_u64 v[228:229], s[38:39], 0, v[152:153]
	ds_read_b128 v[186:189], v168 offset:32768
	ds_read_b128 v[190:193], v168 offset:33792
	ds_read_b128 v[194:197], v168 offset:34816
	ds_read_b128 v[198:201], v168 offset:35840
	ds_read_b128 v[202:205], v168 offset:36864
	ds_read_b128 v[206:209], v168 offset:37888
	ds_read_b128 v[212:215], v168 offset:38912
	ds_read_b128 v[216:219], v168 offset:39936
	global_load_lds_dwordx4 v[228:229], off
	v_lshl_add_u64 v[228:229], s[38:39], 0, v[148:149]
	s_mov_b32 m0, s47
	s_nop 0
	global_load_lds_dwordx4 v[228:229], off
	s_waitcnt vmcnt(8)
	s_waitcnt lgkmcnt(0)
	s_barrier
	s_waitcnt lgkmcnt(0)
	v_mfma_f32_16x16x32_bf16 v[126:129], v[130:133], v[186:189], v[126:129]
	v_mfma_f32_16x16x32_bf16 v[122:125], v[138:141], v[186:189], v[122:125]
	v_mfma_f32_16x16x32_bf16 v[110:113], v[130:133], v[194:197], v[110:113]
	v_mfma_f32_16x16x32_bf16 v[106:109], v[138:141], v[194:197], v[106:109]
	v_mfma_f32_16x16x32_bf16 v[94:97], v[130:133], v[202:205], v[94:97]
	v_mfma_f32_16x16x32_bf16 v[90:93], v[138:141], v[202:205], v[90:93]
	v_mfma_f32_16x16x32_bf16 v[78:81], v[130:133], v[212:215], v[78:81]
	v_mfma_f32_16x16x32_bf16 v[74:77], v[138:141], v[212:215], v[74:77]
	v_mfma_f32_16x16x32_bf16 v[126:129], v[134:137], v[190:193], v[126:129]
	v_mfma_f32_16x16x32_bf16 v[122:125], v[142:145], v[190:193], v[122:125]
	v_mfma_f32_16x16x32_bf16 v[110:113], v[134:137], v[198:201], v[110:113]
	v_mfma_f32_16x16x32_bf16 v[106:109], v[142:145], v[198:201], v[106:109]
	v_mfma_f32_16x16x32_bf16 v[94:97], v[134:137], v[206:209], v[94:97]
	v_mfma_f32_16x16x32_bf16 v[90:93], v[142:145], v[206:209], v[90:93]
	v_mfma_f32_16x16x32_bf16 v[78:81], v[134:137], v[216:219], v[78:81]
	v_mfma_f32_16x16x32_bf16 v[74:77], v[142:145], v[216:219], v[74:77]
	v_mfma_f32_16x16x32_bf16 v[118:121], v[170:173], v[186:189], v[118:121]
	v_mfma_f32_16x16x32_bf16 v[114:117], v[178:181], v[186:189], v[114:117]
	v_mfma_f32_16x16x32_bf16 v[102:105], v[170:173], v[194:197], v[102:105]
	v_mfma_f32_16x16x32_bf16 v[98:101], v[178:181], v[194:197], v[98:101]
	v_mfma_f32_16x16x32_bf16 v[86:89], v[170:173], v[202:205], v[86:89]
	v_mfma_f32_16x16x32_bf16 v[82:85], v[178:181], v[202:205], v[82:85]
	v_mfma_f32_16x16x32_bf16 v[70:73], v[170:173], v[212:215], v[70:73]
	v_mfma_f32_16x16x32_bf16 v[66:69], v[178:181], v[212:215], v[66:69]
	v_mfma_f32_16x16x32_bf16 v[118:121], v[174:177], v[190:193], v[118:121]
	v_mfma_f32_16x16x32_bf16 v[114:117], v[182:185], v[190:193], v[114:117]
	v_mfma_f32_16x16x32_bf16 v[102:105], v[174:177], v[198:201], v[102:105]
	v_mfma_f32_16x16x32_bf16 v[98:101], v[182:185], v[198:201], v[98:101]
	v_mfma_f32_16x16x32_bf16 v[86:89], v[174:177], v[206:209], v[86:89]
	v_mfma_f32_16x16x32_bf16 v[82:85], v[182:185], v[206:209], v[82:85]
	v_mfma_f32_16x16x32_bf16 v[70:73], v[174:177], v[216:219], v[70:73]
	v_mfma_f32_16x16x32_bf16 v[66:69], v[182:185], v[216:219], v[66:69]
	s_barrier
	s_add_i32 s38, s60, s41
	v_lshl_add_u64 v[220:221], v[220:221], 0, s[10:11]
	s_mov_b32 m0, s38
	ds_read_b128 v[186:189], v168 offset:49152
	ds_read_b128 v[190:193], v168 offset:50176
	ds_read_b128 v[194:197], v168 offset:51200
	ds_read_b128 v[198:201], v168 offset:52224
	ds_read_b128 v[202:205], v168 offset:53248
	ds_read_b128 v[206:209], v168 offset:54272
	ds_read_b128 v[212:215], v168 offset:55296
	ds_read_b128 v[216:219], v168 offset:56320
	global_load_lds_dwordx4 v[220:221], off
	s_add_i32 m0, s38, 0x2000
	s_add_u32 s36, s36, 0x40080
	v_lshl_add_u64 v[220:221], v[222:223], 0, s[10:11]
	s_addc_u32 s37, s37, 0
	s_add_i32 s38, s61, s41
	global_load_lds_dwordx4 v[220:221], off
	v_lshl_add_u64 v[220:221], s[36:37], 0, v[150:151]
	s_mov_b32 m0, s38
	s_nop 0
	global_load_lds_dwordx4 v[220:221], off
	v_lshl_add_u64 v[220:221], s[36:37], 0, v[146:147]
	s_add_i32 m0, s38, 0x2000
	s_nop 0
	global_load_lds_dwordx4 v[220:221], off
	v_lshl_add_u64 v[220:221], v[224:225], 0, s[10:11]
	s_mov_b32 m0, s63
	s_nop 0
	global_load_lds_dwordx4 v[220:221], off
	v_lshl_add_u64 v[220:221], v[226:227], 0, s[10:11]
	s_mov_b32 m0, s64
	s_nop 0
	global_load_lds_dwordx4 v[220:221], off
	s_waitcnt vmcnt(8)
	s_waitcnt lgkmcnt(0)
	s_barrier
	s_waitcnt lgkmcnt(0)
	v_mfma_f32_16x16x32_bf16 v[62:65], v[130:133], v[186:189], v[62:65]
	v_mfma_f32_16x16x32_bf16 v[58:61], v[138:141], v[186:189], v[58:61]
	v_mfma_f32_16x16x32_bf16 v[46:49], v[130:133], v[194:197], v[46:49]
	v_mfma_f32_16x16x32_bf16 v[42:45], v[138:141], v[194:197], v[42:45]
	v_mfma_f32_16x16x32_bf16 v[30:33], v[130:133], v[202:205], v[30:33]
	v_mfma_f32_16x16x32_bf16 v[26:29], v[138:141], v[202:205], v[26:29]
	v_mfma_f32_16x16x32_bf16 v[14:17], v[130:133], v[212:215], v[14:17]
	v_mfma_f32_16x16x32_bf16 v[10:13], v[138:141], v[212:215], v[10:13]
	v_mfma_f32_16x16x32_bf16 v[62:65], v[134:137], v[190:193], v[62:65]
	v_mfma_f32_16x16x32_bf16 v[58:61], v[142:145], v[190:193], v[58:61]
	v_mfma_f32_16x16x32_bf16 v[46:49], v[134:137], v[198:201], v[46:49]
	v_mfma_f32_16x16x32_bf16 v[42:45], v[142:145], v[198:201], v[42:45]
	v_mfma_f32_16x16x32_bf16 v[30:33], v[134:137], v[206:209], v[30:33]
	v_mfma_f32_16x16x32_bf16 v[26:29], v[142:145], v[206:209], v[26:29]
	v_mfma_f32_16x16x32_bf16 v[14:17], v[134:137], v[216:219], v[14:17]
	v_mfma_f32_16x16x32_bf16 v[10:13], v[142:145], v[216:219], v[10:13]
	v_mfma_f32_16x16x32_bf16 v[54:57], v[170:173], v[186:189], v[54:57]
	v_mfma_f32_16x16x32_bf16 v[50:53], v[178:181], v[186:189], v[50:53]
	v_mfma_f32_16x16x32_bf16 v[38:41], v[170:173], v[194:197], v[38:41]
	v_mfma_f32_16x16x32_bf16 v[34:37], v[178:181], v[194:197], v[34:37]
	v_mfma_f32_16x16x32_bf16 v[22:25], v[170:173], v[202:205], v[22:25]
	v_mfma_f32_16x16x32_bf16 v[18:21], v[178:181], v[202:205], v[18:21]
	v_mfma_f32_16x16x32_bf16 v[6:9], v[170:173], v[212:215], v[6:9]
	v_mfma_f32_16x16x32_bf16 v[2:5], v[178:181], v[212:215], v[2:5]
	v_mfma_f32_16x16x32_bf16 v[54:57], v[174:177], v[190:193], v[54:57]
	v_mfma_f32_16x16x32_bf16 v[50:53], v[182:185], v[190:193], v[50:53]
	v_mfma_f32_16x16x32_bf16 v[38:41], v[174:177], v[198:201], v[38:41]
	v_mfma_f32_16x16x32_bf16 v[34:37], v[182:185], v[198:201], v[34:37]
	v_mfma_f32_16x16x32_bf16 v[22:25], v[174:177], v[206:209], v[22:25]
	v_mfma_f32_16x16x32_bf16 v[18:21], v[182:185], v[206:209], v[18:21]
	v_mfma_f32_16x16x32_bf16 v[6:9], v[174:177], v[216:219], v[6:9]
	v_mfma_f32_16x16x32_bf16 v[2:5], v[182:185], v[216:219], v[2:5]
	s_barrier
	s_add_i32 s75, s75, 2
	s_add_u32 s30, s30, 0x100
	s_addc_u32 s31, s31, 0
	s_add_u32 s73, s73, 0x100
	s_addc_u32 s74, s74, 0
	s_cmp_gt_u32 s75, 13
	s_cbranch_scc0 .LBB0_584
	s_and_b64 vcc, exec, s[12:13]
	s_cbranch_vccz .LBB0_587
	s_barrier

.LBB0_665:
	ds_read_b128 v[82:85], v169
	ds_read_b128 v[86:89], v169 offset:1024
	ds_read_b128 v[90:93], v169 offset:2048
	ds_read_b128 v[94:97], v169 offset:3072
	ds_read_b128 v[162:165], v170
	ds_read_b128 v[174:177], v170 offset:1024
	ds_read_b128 v[178:181], v170 offset:2048
	ds_read_b128 v[182:185], v170 offset:3072
	s_add_u32 s30, s28, 0xfff50080
	s_addc_u32 s31, s29, -1
	s_cmp_eq_u32 s75, 40
	s_cselect_b32 s37, s7, s31
	s_cselect_b32 s36, s6, s30
	s_cselect_b32 s31, s25, s74
	s_cselect_b32 s30, s24, s73
	v_lshl_add_u64 v[220:221], s[28:29], 0, v[154:155]
	s_add_i32 m0, s42, 0xc000
	ds_read_b128 v[186:189], v171
	ds_read_b128 v[190:193], v171 offset:1024
	ds_read_b128 v[194:197], v171 offset:2048
	ds_read_b128 v[198:201], v171 offset:3072
	ds_read_b128 v[202:205], v171 offset:4096
	ds_read_b128 v[206:209], v171 offset:5120
	ds_read_b128 v[212:215], v171 offset:6144
	ds_read_b128 v[216:219], v171 offset:7168
	global_load_lds_dwordx4 v[220:221], off
	v_lshl_add_u64 v[220:221], s[28:29], 0, v[156:157]
	s_add_i32 m0, s42, 0xe000
	s_nop 0
	global_load_lds_dwordx4 v[220:221], off
	s_waitcnt vmcnt(8)
	s_waitcnt lgkmcnt(0)
	s_barrier
	s_waitcnt lgkmcnt(0)
	v_mfma_f32_16x16x32_bf16 v[142:145], v[82:85], v[186:189], v[142:145]
	v_mfma_f32_16x16x32_bf16 v[138:141], v[90:93], v[186:189], v[138:141]
	v_mfma_f32_16x16x32_bf16 v[126:129], v[82:85], v[194:197], v[126:129]
	v_mfma_f32_16x16x32_bf16 v[122:125], v[90:93], v[194:197], v[122:125]
	v_mfma_f32_16x16x32_bf16 v[110:113], v[82:85], v[202:205], v[110:113]
	v_mfma_f32_16x16x32_bf16 v[106:109], v[90:93], v[202:205], v[106:109]
	v_mfma_f32_16x16x32_bf16 v[78:81], v[82:85], v[212:215], v[78:81]
	v_mfma_f32_16x16x32_bf16 v[74:77], v[90:93], v[212:215], v[74:77]
	v_mfma_f32_16x16x32_bf16 v[142:145], v[86:89], v[190:193], v[142:145]
	v_mfma_f32_16x16x32_bf16 v[138:141], v[94:97], v[190:193], v[138:141]
	v_mfma_f32_16x16x32_bf16 v[126:129], v[86:89], v[198:201], v[126:129]
	v_mfma_f32_16x16x32_bf16 v[122:125], v[94:97], v[198:201], v[122:125]
	v_mfma_f32_16x16x32_bf16 v[110:113], v[86:89], v[206:209], v[110:113]
	v_mfma_f32_16x16x32_bf16 v[106:109], v[94:97], v[206:209], v[106:109]
	v_mfma_f32_16x16x32_bf16 v[78:81], v[86:89], v[216:219], v[78:81]
	v_mfma_f32_16x16x32_bf16 v[74:77], v[94:97], v[216:219], v[74:77]
	v_mfma_f32_16x16x32_bf16 v[134:137], v[162:165], v[186:189], v[134:137]
	v_mfma_f32_16x16x32_bf16 v[130:133], v[178:181], v[186:189], v[130:133]
	v_mfma_f32_16x16x32_bf16 v[118:121], v[162:165], v[194:197], v[118:121]
	v_mfma_f32_16x16x32_bf16 v[114:117], v[178:181], v[194:197], v[114:117]
	v_mfma_f32_16x16x32_bf16 v[102:105], v[162:165], v[202:205], v[102:105]
	v_mfma_f32_16x16x32_bf16 v[98:101], v[178:181], v[202:205], v[98:101]
	v_mfma_f32_16x16x32_bf16 v[70:73], v[162:165], v[212:215], v[70:73]
	v_mfma_f32_16x16x32_bf16 v[66:69], v[178:181], v[212:215], v[66:69]
	v_mfma_f32_16x16x32_bf16 v[134:137], v[174:177], v[190:193], v[134:137]
	v_mfma_f32_16x16x32_bf16 v[130:133], v[182:185], v[190:193], v[130:133]
	v_mfma_f32_16x16x32_bf16 v[118:121], v[174:177], v[198:201], v[118:121]
	v_mfma_f32_16x16x32_bf16 v[114:117], v[182:185], v[198:201], v[114:117]
	v_mfma_f32_16x16x32_bf16 v[102:105], v[174:177], v[206:209], v[102:105]
	v_mfma_f32_16x16x32_bf16 v[98:101], v[182:185], v[206:209], v[98:101]
	v_mfma_f32_16x16x32_bf16 v[70:73], v[174:177], v[216:219], v[70:73]
	v_mfma_f32_16x16x32_bf16 v[66:69], v[182:185], v[216:219], v[66:69]
	s_barrier
	s_add_i32 s60, s67, s41
	v_lshl_add_u64 v[220:221], s[30:31], 0, v[148:149]
	s_mov_b32 m0, s60
	ds_read_b128 v[186:189], v171 offset:16384
	ds_read_b128 v[190:193], v171 offset:17408
	ds_read_b128 v[194:197], v171 offset:18432
	ds_read_b128 v[198:201], v171 offset:19456
	ds_read_b128 v[202:205], v171 offset:20480
	ds_read_b128 v[206:209], v171 offset:21504
	ds_read_b128 v[212:215], v171 offset:22528
	ds_read_b128 v[216:219], v171 offset:23552
	global_load_lds_dwordx4 v[220:221], off
	s_add_i32 m0, s60, 0x2000
	s_add_u32 s60, s30, 0xb0000
	v_lshl_add_u64 v[222:223], s[30:31], 0, v[152:153]
	s_addc_u32 s61, s31, 0
	s_add_i32 s76, s68, s41
	global_load_lds_dwordx4 v[222:223], off
	v_lshl_add_u64 v[224:225], s[60:61], 0, v[148:149]
	s_mov_b32 m0, s76
	v_lshl_add_u64 v[226:227], s[36:37], 0, v[150:151]
	global_load_lds_dwordx4 v[224:225], off
	v_lshl_add_u64 v[224:225], s[60:61], 0, v[152:153]
	s_add_i32 m0, s76, 0x2000
	s_nop 0
	global_load_lds_dwordx4 v[224:225], off
	v_lshl_add_u64 v[224:225], s[36:37], 0, v[146:147]
	s_mov_b32 m0, s42
	s_nop 0
	global_load_lds_dwordx4 v[224:225], off
	s_mov_b32 m0, s43
	s_nop 0
	global_load_lds_dwordx4 v[226:227], off
	s_waitcnt vmcnt(8)
	s_waitcnt lgkmcnt(0)
	s_barrier
	s_waitcnt lgkmcnt(0)
	v_mfma_f32_16x16x32_bf16 v[62:65], v[82:85], v[186:189], v[62:65]
	v_mfma_f32_16x16x32_bf16 v[58:61], v[90:93], v[186:189], v[58:61]
	v_mfma_f32_16x16x32_bf16 v[46:49], v[82:85], v[194:197], v[46:49]
	v_mfma_f32_16x16x32_bf16 v[42:45], v[90:93], v[194:197], v[42:45]
	v_mfma_f32_16x16x32_bf16 v[30:33], v[82:85], v[202:205], v[30:33]
	v_mfma_f32_16x16x32_bf16 v[26:29], v[90:93], v[202:205], v[26:29]
	v_mfma_f32_16x16x32_bf16 v[14:17], v[82:85], v[212:215], v[14:17]
	v_mfma_f32_16x16x32_bf16 v[10:13], v[90:93], v[212:215], v[10:13]
	v_mfma_f32_16x16x32_bf16 v[62:65], v[86:89], v[190:193], v[62:65]
	v_mfma_f32_16x16x32_bf16 v[58:61], v[94:97], v[190:193], v[58:61]
	v_mfma_f32_16x16x32_bf16 v[46:49], v[86:89], v[198:201], v[46:49]
	v_mfma_f32_16x16x32_bf16 v[42:45], v[94:97], v[198:201], v[42:45]
	v_mfma_f32_16x16x32_bf16 v[30:33], v[86:89], v[206:209], v[30:33]
	v_mfma_f32_16x16x32_bf16 v[26:29], v[94:97], v[206:209], v[26:29]
	v_mfma_f32_16x16x32_bf16 v[14:17], v[86:89], v[216:219], v[14:17]
	v_mfma_f32_16x16x32_bf16 v[10:13], v[94:97], v[216:219], v[10:13]
	v_mfma_f32_16x16x32_bf16 v[54:57], v[162:165], v[186:189], v[54:57]
	v_mfma_f32_16x16x32_bf16 v[50:53], v[178:181], v[186:189], v[50:53]
	v_mfma_f32_16x16x32_bf16 v[38:41], v[162:165], v[194:197], v[38:41]
	v_mfma_f32_16x16x32_bf16 v[34:37], v[178:181], v[194:197], v[34:37]
	v_mfma_f32_16x16x32_bf16 v[22:25], v[162:165], v[202:205], v[22:25]
	v_mfma_f32_16x16x32_bf16 v[18:21], v[178:181], v[202:205], v[18:21]
	v_mfma_f32_16x16x32_bf16 v[6:9], v[162:165], v[212:215], v[6:9]
	v_mfma_f32_16x16x32_bf16 v[2:5], v[178:181], v[212:215], v[2:5]
	v_mfma_f32_16x16x32_bf16 v[54:57], v[174:177], v[190:193], v[54:57]
	v_mfma_f32_16x16x32_bf16 v[50:53], v[182:185], v[190:193], v[50:53]
	v_mfma_f32_16x16x32_bf16 v[38:41], v[174:177], v[198:201], v[38:41]
	v_mfma_f32_16x16x32_bf16 v[34:37], v[182:185], v[198:201], v[34:37]
	v_mfma_f32_16x16x32_bf16 v[22:25], v[174:177], v[206:209], v[22:25]
	v_mfma_f32_16x16x32_bf16 v[18:21], v[182:185], v[206:209], v[18:21]
	v_mfma_f32_16x16x32_bf16 v[6:9], v[174:177], v[216:219], v[6:9]
	v_mfma_f32_16x16x32_bf16 v[2:5], v[182:185], v[216:219], v[2:5]
	s_barrier
	s_add_i32 s60, 0, 0x18000
	s_add_i32 s61, 0, 0x1c000
	v_add_u32_e32 v94, s60, v167
	v_add_u32_e32 v173, s61, v167
	ds_read_b128 v[82:85], v94
	ds_read_b128 v[86:89], v94 offset:1024
	ds_read_b128 v[90:93], v94 offset:2048
	ds_read_b128 v[94:97], v94 offset:3072
	ds_read_b128 v[162:165], v173
	ds_read_b128 v[174:177], v173 offset:1024
	ds_read_b128 v[178:181], v173 offset:2048
	ds_read_b128 v[182:185], v173 offset:3072
	s_add_u32 s36, s36, 0xb0000
	s_addc_u32 s37, s37, 0
	s_mov_b32 m0, s44
	v_lshl_add_u64 v[228:229], s[36:37], 0, v[146:147]
	ds_read_b128 v[186:189], v171 offset:32768
	ds_read_b128 v[190:193], v171 offset:33792
	ds_read_b128 v[194:197], v171 offset:34816
	ds_read_b128 v[198:201], v171 offset:35840
	ds_read_b128 v[202:205], v171 offset:36864
	ds_read_b128 v[206:209], v171 offset:37888
	ds_read_b128 v[212:215], v171 offset:38912
	ds_read_b128 v[216:219], v171 offset:39936
	global_load_lds_dwordx4 v[228:229], off
	v_lshl_add_u64 v[228:229], s[36:37], 0, v[150:151]
	s_mov_b32 m0, s45
	s_nop 0
	global_load_lds_dwordx4 v[228:229], off
	s_waitcnt vmcnt(8)
	s_waitcnt lgkmcnt(0)
	s_barrier
	s_waitcnt lgkmcnt(0)
	v_mfma_f32_16x16x32_bf16 v[142:145], v[82:85], v[186:189], v[142:145]
	v_mfma_f32_16x16x32_bf16 v[138:141], v[90:93], v[186:189], v[138:141]
	v_mfma_f32_16x16x32_bf16 v[126:129], v[82:85], v[194:197], v[126:129]
	v_mfma_f32_16x16x32_bf16 v[122:125], v[90:93], v[194:197], v[122:125]
	v_mfma_f32_16x16x32_bf16 v[110:113], v[82:85], v[202:205], v[110:113]
	v_mfma_f32_16x16x32_bf16 v[106:109], v[90:93], v[202:205], v[106:109]
	v_mfma_f32_16x16x32_bf16 v[78:81], v[82:85], v[212:215], v[78:81]
	v_mfma_f32_16x16x32_bf16 v[74:77], v[90:93], v[212:215], v[74:77]
	v_mfma_f32_16x16x32_bf16 v[142:145], v[86:89], v[190:193], v[142:145]
	v_mfma_f32_16x16x32_bf16 v[138:141], v[94:97], v[190:193], v[138:141]
	v_mfma_f32_16x16x32_bf16 v[126:129], v[86:89], v[198:201], v[126:129]
	v_mfma_f32_16x16x32_bf16 v[122:125], v[94:97], v[198:201], v[122:125]
	v_mfma_f32_16x16x32_bf16 v[110:113], v[86:89], v[206:209], v[110:113]
	v_mfma_f32_16x16x32_bf16 v[106:109], v[94:97], v[206:209], v[106:109]
	v_mfma_f32_16x16x32_bf16 v[78:81], v[86:89], v[216:219], v[78:81]
	v_mfma_f32_16x16x32_bf16 v[74:77], v[94:97], v[216:219], v[74:77]
	v_mfma_f32_16x16x32_bf16 v[134:137], v[162:165], v[186:189], v[134:137]
	v_mfma_f32_16x16x32_bf16 v[130:133], v[178:181], v[186:189], v[130:133]
	v_mfma_f32_16x16x32_bf16 v[118:121], v[162:165], v[194:197], v[118:121]
	v_mfma_f32_16x16x32_bf16 v[114:117], v[178:181], v[194:197], v[114:117]
	v_mfma_f32_16x16x32_bf16 v[102:105], v[162:165], v[202:205], v[102:105]
	v_mfma_f32_16x16x32_bf16 v[98:101], v[178:181], v[202:205], v[98:101]
	v_mfma_f32_16x16x32_bf16 v[70:73], v[162:165], v[212:215], v[70:73]
	v_mfma_f32_16x16x32_bf16 v[66:69], v[178:181], v[212:215], v[66:69]
	v_mfma_f32_16x16x32_bf16 v[134:137], v[174:177], v[190:193], v[134:137]
	v_mfma_f32_16x16x32_bf16 v[130:133], v[182:185], v[190:193], v[130:133]
	v_mfma_f32_16x16x32_bf16 v[118:121], v[174:177], v[198:201], v[118:121]
	v_mfma_f32_16x16x32_bf16 v[114:117], v[182:185], v[198:201], v[114:117]
	v_mfma_f32_16x16x32_bf16 v[102:105], v[174:177], v[206:209], v[102:105]
	v_mfma_f32_16x16x32_bf16 v[98:101], v[182:185], v[206:209], v[98:101]
	v_mfma_f32_16x16x32_bf16 v[70:73], v[174:177], v[216:219], v[70:73]
	v_mfma_f32_16x16x32_bf16 v[66:69], v[182:185], v[216:219], v[66:69]
	s_barrier
	s_add_i32 s36, s60, s41
	v_lshl_add_u64 v[220:221], v[220:221], 0, s[16:17]
	s_mov_b32 m0, s36
	ds_read_b128 v[186:189], v171 offset:49152
	ds_read_b128 v[190:193], v171 offset:50176
	ds_read_b128 v[194:197], v171 offset:51200
	ds_read_b128 v[198:201], v171 offset:52224
	ds_read_b128 v[202:205], v171 offset:53248
	ds_read_b128 v[206:209], v171 offset:54272
	ds_read_b128 v[212:215], v171 offset:55296
	ds_read_b128 v[216:219], v171 offset:56320
	global_load_lds_dwordx4 v[220:221], off
	s_add_i32 m0, s36, 0x2000
	s_add_u32 s30, s30, 0xb0080
	v_lshl_add_u64 v[220:221], v[222:223], 0, s[16:17]
	s_addc_u32 s31, s31, 0
	s_add_i32 s36, s61, s41
	global_load_lds_dwordx4 v[220:221], off
	v_lshl_add_u64 v[220:221], s[30:31], 0, v[148:149]
	s_mov_b32 m0, s36
	s_nop 0
	global_load_lds_dwordx4 v[220:221], off
	v_lshl_add_u64 v[220:221], s[30:31], 0, v[152:153]
	s_add_i32 m0, s36, 0x2000
	s_nop 0
	global_load_lds_dwordx4 v[220:221], off
	v_lshl_add_u64 v[220:221], v[224:225], 0, s[16:17]
	s_mov_b32 m0, s64
	s_nop 0
	global_load_lds_dwordx4 v[220:221], off
	v_lshl_add_u64 v[220:221], v[226:227], 0, s[16:17]
	s_mov_b32 m0, s65
	s_nop 0
	global_load_lds_dwordx4 v[220:221], off
	s_waitcnt vmcnt(8)
	s_waitcnt lgkmcnt(0)
	s_barrier
	s_waitcnt lgkmcnt(0)
	v_mfma_f32_16x16x32_bf16 v[62:65], v[82:85], v[186:189], v[62:65]
	v_mfma_f32_16x16x32_bf16 v[58:61], v[90:93], v[186:189], v[58:61]
	v_mfma_f32_16x16x32_bf16 v[46:49], v[82:85], v[194:197], v[46:49]
	v_mfma_f32_16x16x32_bf16 v[42:45], v[90:93], v[194:197], v[42:45]
	v_mfma_f32_16x16x32_bf16 v[30:33], v[82:85], v[202:205], v[30:33]
	v_mfma_f32_16x16x32_bf16 v[26:29], v[90:93], v[202:205], v[26:29]
	v_mfma_f32_16x16x32_bf16 v[14:17], v[82:85], v[212:215], v[14:17]
	v_mfma_f32_16x16x32_bf16 v[10:13], v[90:93], v[212:215], v[10:13]
	v_mfma_f32_16x16x32_bf16 v[62:65], v[86:89], v[190:193], v[62:65]
	v_mfma_f32_16x16x32_bf16 v[58:61], v[94:97], v[190:193], v[58:61]
	v_mfma_f32_16x16x32_bf16 v[46:49], v[86:89], v[198:201], v[46:49]
	v_mfma_f32_16x16x32_bf16 v[42:45], v[94:97], v[198:201], v[42:45]
	v_mfma_f32_16x16x32_bf16 v[30:33], v[86:89], v[206:209], v[30:33]
	v_mfma_f32_16x16x32_bf16 v[26:29], v[94:97], v[206:209], v[26:29]
	v_mfma_f32_16x16x32_bf16 v[14:17], v[86:89], v[216:219], v[14:17]
	v_mfma_f32_16x16x32_bf16 v[10:13], v[94:97], v[216:219], v[10:13]
	v_mfma_f32_16x16x32_bf16 v[54:57], v[162:165], v[186:189], v[54:57]
	v_mfma_f32_16x16x32_bf16 v[50:53], v[178:181], v[186:189], v[50:53]
	v_mfma_f32_16x16x32_bf16 v[38:41], v[162:165], v[194:197], v[38:41]
	v_mfma_f32_16x16x32_bf16 v[34:37], v[178:181], v[194:197], v[34:37]
	v_mfma_f32_16x16x32_bf16 v[22:25], v[162:165], v[202:205], v[22:25]
	v_mfma_f32_16x16x32_bf16 v[18:21], v[178:181], v[202:205], v[18:21]
	v_mfma_f32_16x16x32_bf16 v[6:9], v[162:165], v[212:215], v[6:9]
	v_mfma_f32_16x16x32_bf16 v[2:5], v[178:181], v[212:215], v[2:5]
	v_mfma_f32_16x16x32_bf16 v[54:57], v[174:177], v[190:193], v[54:57]
	v_mfma_f32_16x16x32_bf16 v[50:53], v[182:185], v[190:193], v[50:53]
	v_mfma_f32_16x16x32_bf16 v[38:41], v[174:177], v[198:201], v[38:41]
	v_mfma_f32_16x16x32_bf16 v[34:37], v[182:185], v[198:201], v[34:37]
	v_mfma_f32_16x16x32_bf16 v[22:25], v[174:177], v[206:209], v[22:25]
	v_mfma_f32_16x16x32_bf16 v[18:21], v[182:185], v[206:209], v[18:21]
	v_mfma_f32_16x16x32_bf16 v[6:9], v[174:177], v[216:219], v[6:9]
	v_mfma_f32_16x16x32_bf16 v[2:5], v[182:185], v[216:219], v[2:5]
	s_barrier
	s_add_i32 s75, s75, 2
	s_add_u32 s28, s28, 0x100
	s_addc_u32 s29, s29, 0
	s_add_u32 s73, s73, 0x100
	s_addc_u32 s74, s74, 0
	s_cmp_gt_u32 s75, 41
	s_cbranch_scc0 .LBB0_665
	s_and_b64 vcc, exec, s[18:19]
	s_cbranch_vccz .LBB0_668
	s_barrier

.LBB0_911:
	ds_read_b128 v[156:159], v153
	ds_read_b128 v[160:163], v153 offset:1024
	ds_read_b128 v[164:167], v153 offset:2048
	ds_read_b128 v[168:171], v153 offset:3072
	ds_read_b128 v[172:175], v154
	ds_read_b128 v[176:179], v154 offset:1024
	ds_read_b128 v[180:183], v154 offset:2048
	ds_read_b128 v[184:187], v154 offset:3072
	s_add_u32 s42, s40, 0x100
	s_addc_u32 s43, s41, 0
	s_add_u32 s44, s77, s40
	s_addc_u32 s45, s78, s41
	s_cmp_eq_u32 s79, 4
	s_cselect_b32 s46, s37, s44
	s_cselect_b32 s44, 0, s42
	s_cselect_b32 s47, s31, s45
	s_cselect_b32 s45, 0, s43
	s_add_u32 s44, s6, s44
	s_addc_u32 s45, s7, s45
	v_lshl_add_u64 v[208:209], v[146:147], 0, s[40:41]
	s_add_i32 m0, s29, 0xc000
	ds_read_b128 v[188:191], v155
	ds_read_b128 v[192:195], v155 offset:1024
	ds_read_b128 v[196:199], v155 offset:2048
	ds_read_b128 v[200:203], v155 offset:3072
	ds_read_b128 v[204:207], v155 offset:4096
	ds_read_b128 v[212:215], v155 offset:5120
	ds_read_b128 v[216:219], v155 offset:6144
	ds_read_b128 v[220:223], v155 offset:7168
	global_load_lds_dwordx4 v[208:209], off
	v_lshl_add_u64 v[208:209], v[148:149], 0, s[40:41]
	s_add_i32 m0, s29, 0xe000
	s_nop 0
	global_load_lds_dwordx4 v[208:209], off
	s_waitcnt vmcnt(8)
	s_waitcnt lgkmcnt(0)
	s_barrier
	s_waitcnt lgkmcnt(0)
	v_mfma_f32_16x16x32_bf16 v[126:129], v[156:159], v[188:191], v[126:129]
	v_mfma_f32_16x16x32_bf16 v[122:125], v[164:167], v[188:191], v[122:125]
	v_mfma_f32_16x16x32_bf16 v[118:121], v[156:159], v[196:199], v[118:121]
	v_mfma_f32_16x16x32_bf16 v[114:117], v[164:167], v[196:199], v[114:117]
	v_mfma_f32_16x16x32_bf16 v[102:105], v[156:159], v[204:207], v[102:105]
	v_mfma_f32_16x16x32_bf16 v[98:101], v[164:167], v[204:207], v[98:101]
	v_mfma_f32_16x16x32_bf16 v[86:89], v[156:159], v[216:219], v[86:89]
	v_mfma_f32_16x16x32_bf16 v[82:85], v[164:167], v[216:219], v[82:85]
	v_mfma_f32_16x16x32_bf16 v[126:129], v[160:163], v[192:195], v[126:129]
	v_mfma_f32_16x16x32_bf16 v[122:125], v[168:171], v[192:195], v[122:125]
	v_mfma_f32_16x16x32_bf16 v[118:121], v[160:163], v[200:203], v[118:121]
	v_mfma_f32_16x16x32_bf16 v[114:117], v[168:171], v[200:203], v[114:117]
	v_mfma_f32_16x16x32_bf16 v[102:105], v[160:163], v[212:215], v[102:105]
	v_mfma_f32_16x16x32_bf16 v[98:101], v[168:171], v[212:215], v[98:101]
	v_mfma_f32_16x16x32_bf16 v[86:89], v[160:163], v[220:223], v[86:89]
	v_mfma_f32_16x16x32_bf16 v[82:85], v[168:171], v[220:223], v[82:85]
	v_mfma_f32_16x16x32_bf16 v[110:113], v[172:175], v[188:191], v[110:113]
	v_mfma_f32_16x16x32_bf16 v[106:109], v[180:183], v[188:191], v[106:109]
	v_mfma_f32_16x16x32_bf16 v[94:97], v[172:175], v[196:199], v[94:97]
	v_mfma_f32_16x16x32_bf16 v[90:93], v[180:183], v[196:199], v[90:93]
	v_mfma_f32_16x16x32_bf16 v[78:81], v[172:175], v[204:207], v[78:81]
	v_mfma_f32_16x16x32_bf16 v[74:77], v[180:183], v[204:207], v[74:77]
	v_mfma_f32_16x16x32_bf16 v[70:73], v[172:175], v[216:219], v[70:73]
	v_mfma_f32_16x16x32_bf16 v[66:69], v[180:183], v[216:219], v[66:69]
	v_mfma_f32_16x16x32_bf16 v[110:113], v[176:179], v[192:195], v[110:113]
	v_mfma_f32_16x16x32_bf16 v[106:109], v[184:187], v[192:195], v[106:109]
	v_mfma_f32_16x16x32_bf16 v[94:97], v[176:179], v[200:203], v[94:97]
	v_mfma_f32_16x16x32_bf16 v[90:93], v[184:187], v[200:203], v[90:93]
	v_mfma_f32_16x16x32_bf16 v[78:81], v[176:179], v[212:215], v[78:81]
	v_mfma_f32_16x16x32_bf16 v[74:77], v[184:187], v[212:215], v[74:77]
	v_mfma_f32_16x16x32_bf16 v[70:73], v[176:179], v[220:223], v[70:73]
	v_mfma_f32_16x16x32_bf16 v[66:69], v[184:187], v[220:223], v[66:69]
	s_barrier
	s_add_i32 s40, s70, s62
	v_lshl_add_u64 v[208:209], s[44:45], 0, v[132:133]
	s_mov_b32 m0, s40
	ds_read_b128 v[188:191], v155 offset:16384
	ds_read_b128 v[192:195], v155 offset:17408
	ds_read_b128 v[196:199], v155 offset:18432
	ds_read_b128 v[200:203], v155 offset:19456
	ds_read_b128 v[204:207], v155 offset:20480
	ds_read_b128 v[212:215], v155 offset:21504
	ds_read_b128 v[216:219], v155 offset:22528
	ds_read_b128 v[220:223], v155 offset:23552
	global_load_lds_dwordx4 v[208:209], off
	s_add_i32 m0, s40, 0x2000
	s_add_u32 s40, s44, 0x20000
	v_lshl_add_u64 v[224:225], s[44:45], 0, v[136:137]
	s_addc_u32 s41, s45, 0
	s_add_i32 s60, s71, s62
	global_load_lds_dwordx4 v[224:225], off
	v_lshl_add_u64 v[226:227], s[40:41], 0, v[132:133]
	s_mov_b32 m0, s60
	v_lshl_add_u64 v[228:229], s[46:47], 0, v[134:135]
	global_load_lds_dwordx4 v[226:227], off
	v_lshl_add_u64 v[226:227], s[40:41], 0, v[136:137]
	s_add_i32 m0, s60, 0x2000
	s_nop 0
	global_load_lds_dwordx4 v[226:227], off
	v_lshl_add_u64 v[226:227], s[46:47], 0, v[130:131]
	s_mov_b32 m0, s29
	s_nop 0
	global_load_lds_dwordx4 v[226:227], off
	s_mov_b32 m0, s63
	s_nop 0
	global_load_lds_dwordx4 v[228:229], off
	s_waitcnt vmcnt(8)
	s_waitcnt lgkmcnt(0)
	s_barrier
	s_waitcnt lgkmcnt(0)
	v_mfma_f32_16x16x32_bf16 v[62:65], v[156:159], v[188:191], v[62:65]
	v_mfma_f32_16x16x32_bf16 v[58:61], v[164:167], v[188:191], v[58:61]
	v_mfma_f32_16x16x32_bf16 v[54:57], v[156:159], v[196:199], v[54:57]
	v_mfma_f32_16x16x32_bf16 v[50:53], v[164:167], v[196:199], v[50:53]
	v_mfma_f32_16x16x32_bf16 v[38:41], v[156:159], v[204:207], v[38:41]
	v_mfma_f32_16x16x32_bf16 v[34:37], v[164:167], v[204:207], v[34:37]
	v_mfma_f32_16x16x32_bf16 v[22:25], v[156:159], v[216:219], v[22:25]
	v_mfma_f32_16x16x32_bf16 v[18:21], v[164:167], v[216:219], v[18:21]
	v_mfma_f32_16x16x32_bf16 v[62:65], v[160:163], v[192:195], v[62:65]
	v_mfma_f32_16x16x32_bf16 v[58:61], v[168:171], v[192:195], v[58:61]
	v_mfma_f32_16x16x32_bf16 v[54:57], v[160:163], v[200:203], v[54:57]
	v_mfma_f32_16x16x32_bf16 v[50:53], v[168:171], v[200:203], v[50:53]
	v_mfma_f32_16x16x32_bf16 v[38:41], v[160:163], v[212:215], v[38:41]
	v_mfma_f32_16x16x32_bf16 v[34:37], v[168:171], v[212:215], v[34:37]
	v_mfma_f32_16x16x32_bf16 v[22:25], v[160:163], v[220:223], v[22:25]
	v_mfma_f32_16x16x32_bf16 v[18:21], v[168:171], v[220:223], v[18:21]
	v_mfma_f32_16x16x32_bf16 v[46:49], v[172:175], v[188:191], v[46:49]
	v_mfma_f32_16x16x32_bf16 v[42:45], v[180:183], v[188:191], v[42:45]
	v_mfma_f32_16x16x32_bf16 v[30:33], v[172:175], v[196:199], v[30:33]
	v_mfma_f32_16x16x32_bf16 v[26:29], v[180:183], v[196:199], v[26:29]
	v_mfma_f32_16x16x32_bf16 v[14:17], v[172:175], v[204:207], v[14:17]
	v_mfma_f32_16x16x32_bf16 v[10:13], v[180:183], v[204:207], v[10:13]
	v_mfma_f32_16x16x32_bf16 v[6:9], v[172:175], v[216:219], v[6:9]
	v_mfma_f32_16x16x32_bf16 v[2:5], v[180:183], v[216:219], v[2:5]
	v_mfma_f32_16x16x32_bf16 v[46:49], v[176:179], v[192:195], v[46:49]
	v_mfma_f32_16x16x32_bf16 v[42:45], v[184:187], v[192:195], v[42:45]
	v_mfma_f32_16x16x32_bf16 v[30:33], v[176:179], v[200:203], v[30:33]
	v_mfma_f32_16x16x32_bf16 v[26:29], v[184:187], v[200:203], v[26:29]
	v_mfma_f32_16x16x32_bf16 v[14:17], v[176:179], v[212:215], v[14:17]
	v_mfma_f32_16x16x32_bf16 v[10:13], v[184:187], v[212:215], v[10:13]
	v_mfma_f32_16x16x32_bf16 v[6:9], v[176:179], v[220:223], v[6:9]
	v_mfma_f32_16x16x32_bf16 v[2:5], v[184:187], v[220:223], v[2:5]
	s_barrier
	s_add_i32 s60, 0, 0x18000
	s_add_i32 s61, 0, 0x1c000
	v_add_u32_e32 v168, s60, v151
	v_add_u32_e32 v184, s61, v151
	ds_read_b128 v[156:159], v168
	ds_read_b128 v[160:163], v168 offset:1024
	ds_read_b128 v[164:167], v168 offset:2048
	ds_read_b128 v[168:171], v168 offset:3072
	ds_read_b128 v[172:175], v184
	ds_read_b128 v[176:179], v184 offset:1024
	ds_read_b128 v[180:183], v184 offset:2048
	ds_read_b128 v[184:187], v184 offset:3072
	s_add_u32 s40, s46, 0x80000
	s_addc_u32 s41, s47, 0
	s_mov_b32 m0, s64
	v_lshl_add_u64 v[230:231], s[40:41], 0, v[130:131]
	ds_read_b128 v[188:191], v155 offset:32768
	ds_read_b128 v[192:195], v155 offset:33792
	ds_read_b128 v[196:199], v155 offset:34816
	ds_read_b128 v[200:203], v155 offset:35840
	ds_read_b128 v[204:207], v155 offset:36864
	ds_read_b128 v[212:215], v155 offset:37888
	ds_read_b128 v[216:219], v155 offset:38912
	ds_read_b128 v[220:223], v155 offset:39936
	global_load_lds_dwordx4 v[230:231], off
	v_lshl_add_u64 v[230:231], s[40:41], 0, v[134:135]
	s_mov_b32 m0, s65
	s_nop 0
	global_load_lds_dwordx4 v[230:231], off
	s_waitcnt vmcnt(8)
	s_waitcnt lgkmcnt(0)
	s_barrier
	s_waitcnt lgkmcnt(0)
	v_mfma_f32_16x16x32_bf16 v[126:129], v[156:159], v[188:191], v[126:129]
	v_mfma_f32_16x16x32_bf16 v[122:125], v[164:167], v[188:191], v[122:125]
	v_mfma_f32_16x16x32_bf16 v[118:121], v[156:159], v[196:199], v[118:121]
	v_mfma_f32_16x16x32_bf16 v[114:117], v[164:167], v[196:199], v[114:117]
	v_mfma_f32_16x16x32_bf16 v[102:105], v[156:159], v[204:207], v[102:105]
	v_mfma_f32_16x16x32_bf16 v[98:101], v[164:167], v[204:207], v[98:101]
	v_mfma_f32_16x16x32_bf16 v[86:89], v[156:159], v[216:219], v[86:89]
	v_mfma_f32_16x16x32_bf16 v[82:85], v[164:167], v[216:219], v[82:85]
	v_mfma_f32_16x16x32_bf16 v[126:129], v[160:163], v[192:195], v[126:129]
	v_mfma_f32_16x16x32_bf16 v[122:125], v[168:171], v[192:195], v[122:125]
	v_mfma_f32_16x16x32_bf16 v[118:121], v[160:163], v[200:203], v[118:121]
	v_mfma_f32_16x16x32_bf16 v[114:117], v[168:171], v[200:203], v[114:117]
	v_mfma_f32_16x16x32_bf16 v[102:105], v[160:163], v[212:215], v[102:105]
	v_mfma_f32_16x16x32_bf16 v[98:101], v[168:171], v[212:215], v[98:101]
	v_mfma_f32_16x16x32_bf16 v[86:89], v[160:163], v[220:223], v[86:89]
	v_mfma_f32_16x16x32_bf16 v[82:85], v[168:171], v[220:223], v[82:85]
	v_mfma_f32_16x16x32_bf16 v[110:113], v[172:175], v[188:191], v[110:113]
	v_mfma_f32_16x16x32_bf16 v[106:109], v[180:183], v[188:191], v[106:109]
	v_mfma_f32_16x16x32_bf16 v[94:97], v[172:175], v[196:199], v[94:97]
	v_mfma_f32_16x16x32_bf16 v[90:93], v[180:183], v[196:199], v[90:93]
	v_mfma_f32_16x16x32_bf16 v[78:81], v[172:175], v[204:207], v[78:81]
	v_mfma_f32_16x16x32_bf16 v[74:77], v[180:183], v[204:207], v[74:77]
	v_mfma_f32_16x16x32_bf16 v[70:73], v[172:175], v[216:219], v[70:73]
	v_mfma_f32_16x16x32_bf16 v[66:69], v[180:183], v[216:219], v[66:69]
	v_mfma_f32_16x16x32_bf16 v[110:113], v[176:179], v[192:195], v[110:113]
	v_mfma_f32_16x16x32_bf16 v[106:109], v[184:187], v[192:195], v[106:109]
	v_mfma_f32_16x16x32_bf16 v[94:97], v[176:179], v[200:203], v[94:97]
	v_mfma_f32_16x16x32_bf16 v[90:93], v[184:187], v[200:203], v[90:93]
	v_mfma_f32_16x16x32_bf16 v[78:81], v[176:179], v[212:215], v[78:81]
	v_mfma_f32_16x16x32_bf16 v[74:77], v[184:187], v[212:215], v[74:77]
	v_mfma_f32_16x16x32_bf16 v[70:73], v[176:179], v[220:223], v[70:73]
	v_mfma_f32_16x16x32_bf16 v[66:69], v[184:187], v[220:223], v[66:69]
	s_barrier
	s_add_i32 s40, s60, s62
	v_lshl_add_u64 v[208:209], v[208:209], 0, s[10:11]
	s_mov_b32 m0, s40
	ds_read_b128 v[188:191], v155 offset:49152
	ds_read_b128 v[192:195], v155 offset:50176
	ds_read_b128 v[196:199], v155 offset:51200
	ds_read_b128 v[200:203], v155 offset:52224
	ds_read_b128 v[204:207], v155 offset:53248
	ds_read_b128 v[212:215], v155 offset:54272
	ds_read_b128 v[216:219], v155 offset:55296
	ds_read_b128 v[220:223], v155 offset:56320
	global_load_lds_dwordx4 v[208:209], off
	s_add_i32 m0, s40, 0x2000
	s_add_u32 s40, s44, 0x20080
	v_lshl_add_u64 v[208:209], v[224:225], 0, s[10:11]
	s_addc_u32 s41, s45, 0
	s_add_i32 s44, s61, s62
	global_load_lds_dwordx4 v[208:209], off
	v_lshl_add_u64 v[208:209], s[40:41], 0, v[132:133]
	s_mov_b32 m0, s44
	s_nop 0
	global_load_lds_dwordx4 v[208:209], off
	v_lshl_add_u64 v[208:209], s[40:41], 0, v[136:137]
	s_add_i32 m0, s44, 0x2000
	s_nop 0
	global_load_lds_dwordx4 v[208:209], off
	v_lshl_add_u64 v[208:209], v[226:227], 0, s[10:11]
	s_mov_b32 m0, s67
	s_nop 0
	global_load_lds_dwordx4 v[208:209], off
	v_lshl_add_u64 v[208:209], v[228:229], 0, s[10:11]
	s_mov_b32 m0, s68
	s_nop 0
	global_load_lds_dwordx4 v[208:209], off
	s_waitcnt vmcnt(8)
	s_waitcnt lgkmcnt(0)
	s_barrier
	s_waitcnt lgkmcnt(0)
	v_mfma_f32_16x16x32_bf16 v[62:65], v[156:159], v[188:191], v[62:65]
	v_mfma_f32_16x16x32_bf16 v[58:61], v[164:167], v[188:191], v[58:61]
	v_mfma_f32_16x16x32_bf16 v[54:57], v[156:159], v[196:199], v[54:57]
	v_mfma_f32_16x16x32_bf16 v[50:53], v[164:167], v[196:199], v[50:53]
	v_mfma_f32_16x16x32_bf16 v[38:41], v[156:159], v[204:207], v[38:41]
	v_mfma_f32_16x16x32_bf16 v[34:37], v[164:167], v[204:207], v[34:37]
	v_mfma_f32_16x16x32_bf16 v[22:25], v[156:159], v[216:219], v[22:25]
	v_mfma_f32_16x16x32_bf16 v[18:21], v[164:167], v[216:219], v[18:21]
	v_mfma_f32_16x16x32_bf16 v[62:65], v[160:163], v[192:195], v[62:65]
	v_mfma_f32_16x16x32_bf16 v[58:61], v[168:171], v[192:195], v[58:61]
	v_mfma_f32_16x16x32_bf16 v[54:57], v[160:163], v[200:203], v[54:57]
	v_mfma_f32_16x16x32_bf16 v[50:53], v[168:171], v[200:203], v[50:53]
	v_mfma_f32_16x16x32_bf16 v[38:41], v[160:163], v[212:215], v[38:41]
	v_mfma_f32_16x16x32_bf16 v[34:37], v[168:171], v[212:215], v[34:37]
	v_mfma_f32_16x16x32_bf16 v[22:25], v[160:163], v[220:223], v[22:25]
	v_mfma_f32_16x16x32_bf16 v[18:21], v[168:171], v[220:223], v[18:21]
	v_mfma_f32_16x16x32_bf16 v[46:49], v[172:175], v[188:191], v[46:49]
	v_mfma_f32_16x16x32_bf16 v[42:45], v[180:183], v[188:191], v[42:45]
	v_mfma_f32_16x16x32_bf16 v[30:33], v[172:175], v[196:199], v[30:33]
	v_mfma_f32_16x16x32_bf16 v[26:29], v[180:183], v[196:199], v[26:29]
	v_mfma_f32_16x16x32_bf16 v[14:17], v[172:175], v[204:207], v[14:17]
	v_mfma_f32_16x16x32_bf16 v[10:13], v[180:183], v[204:207], v[10:13]
	v_mfma_f32_16x16x32_bf16 v[6:9], v[172:175], v[216:219], v[6:9]
	v_mfma_f32_16x16x32_bf16 v[2:5], v[180:183], v[216:219], v[2:5]
	v_mfma_f32_16x16x32_bf16 v[46:49], v[176:179], v[192:195], v[46:49]
	v_mfma_f32_16x16x32_bf16 v[42:45], v[184:187], v[192:195], v[42:45]
	v_mfma_f32_16x16x32_bf16 v[30:33], v[176:179], v[200:203], v[30:33]
	v_mfma_f32_16x16x32_bf16 v[26:29], v[184:187], v[200:203], v[26:29]
	v_mfma_f32_16x16x32_bf16 v[14:17], v[176:179], v[212:215], v[14:17]
	v_mfma_f32_16x16x32_bf16 v[10:13], v[184:187], v[212:215], v[10:13]
	v_mfma_f32_16x16x32_bf16 v[6:9], v[176:179], v[220:223], v[6:9]
	v_mfma_f32_16x16x32_bf16 v[2:5], v[184:187], v[220:223], v[2:5]
	s_barrier
	s_add_i32 s79, s79, 2
	s_cmp_gt_u32 s79, 5
	s_mov_b64 s[40:41], s[42:43]
	s_cbranch_scc0 .LBB0_911
	s_and_b64 vcc, exec, s[12:13]
	s_cbranch_vccz .LBB0_914
	s_barrier

.LBB0_988:
	ds_read_b128 v[66:69], v215
	ds_read_b128 v[70:73], v215 offset:1024
	ds_read_b128 v[74:77], v215 offset:2048
	ds_read_b128 v[78:81], v215 offset:3072
	ds_read_b128 v[82:85], v216
	ds_read_b128 v[86:89], v216 offset:1024
	ds_read_b128 v[90:93], v216 offset:2048
	ds_read_b128 v[94:97], v216 offset:3072
	s_add_u32 s46, s6, 0xfffc0080
	s_addc_u32 s47, s7, -1
	s_cmp_eq_u32 s81, 12
	s_cselect_b32 s49, s39, s47
	s_cselect_b32 s48, s45, s46
	s_cselect_b32 s47, s37, s80
	s_cselect_b32 s46, s78, s79
	v_lshl_add_u64 v[220:221], s[6:7], 0, v[194:195]
	s_add_i32 m0, s64, 0xc000
	ds_read_b128 v[162:165], v217
	ds_read_b128 v[166:169], v217 offset:1024
	ds_read_b128 v[170:173], v217 offset:2048
	ds_read_b128 v[174:177], v217 offset:3072
	ds_read_b128 v[178:181], v217 offset:4096
	ds_read_b128 v[182:185], v217 offset:5120
	ds_read_b128 v[202:205], v217 offset:6144
	ds_read_b128 v[206:209], v217 offset:7168
	global_load_lds_dwordx4 v[220:221], off
	v_lshl_add_u64 v[220:221], s[6:7], 0, v[196:197]
	s_add_i32 m0, s64, 0xe000
	s_nop 0
	global_load_lds_dwordx4 v[220:221], off
	s_waitcnt vmcnt(8)
	s_waitcnt lgkmcnt(0)
	s_barrier
	s_waitcnt lgkmcnt(0)
	v_mfma_f32_16x16x32_bf16 v[158:161], v[66:69], v[162:165], v[158:161]
	v_mfma_f32_16x16x32_bf16 v[154:157], v[74:77], v[162:165], v[154:157]
	v_mfma_f32_16x16x32_bf16 v[142:145], v[66:69], v[170:173], v[142:145]
	v_mfma_f32_16x16x32_bf16 v[138:141], v[74:77], v[170:173], v[138:141]
	v_mfma_f32_16x16x32_bf16 v[126:129], v[66:69], v[178:181], v[126:129]
	v_mfma_f32_16x16x32_bf16 v[122:125], v[74:77], v[178:181], v[122:125]
	v_mfma_f32_16x16x32_bf16 v[110:113], v[66:69], v[202:205], v[110:113]
	v_mfma_f32_16x16x32_bf16 v[106:109], v[74:77], v[202:205], v[106:109]
	v_mfma_f32_16x16x32_bf16 v[158:161], v[70:73], v[166:169], v[158:161]
	v_mfma_f32_16x16x32_bf16 v[154:157], v[78:81], v[166:169], v[154:157]
	v_mfma_f32_16x16x32_bf16 v[142:145], v[70:73], v[174:177], v[142:145]
	v_mfma_f32_16x16x32_bf16 v[138:141], v[78:81], v[174:177], v[138:141]
	v_mfma_f32_16x16x32_bf16 v[126:129], v[70:73], v[182:185], v[126:129]
	v_mfma_f32_16x16x32_bf16 v[122:125], v[78:81], v[182:185], v[122:125]
	v_mfma_f32_16x16x32_bf16 v[110:113], v[70:73], v[206:209], v[110:113]
	v_mfma_f32_16x16x32_bf16 v[106:109], v[78:81], v[206:209], v[106:109]
	v_mfma_f32_16x16x32_bf16 v[150:153], v[82:85], v[162:165], v[150:153]
	v_mfma_f32_16x16x32_bf16 v[146:149], v[90:93], v[162:165], v[146:149]
	v_mfma_f32_16x16x32_bf16 v[134:137], v[82:85], v[170:173], v[134:137]
	v_mfma_f32_16x16x32_bf16 v[130:133], v[90:93], v[170:173], v[130:133]
	v_mfma_f32_16x16x32_bf16 v[118:121], v[82:85], v[178:181], v[118:121]
	v_mfma_f32_16x16x32_bf16 v[114:117], v[90:93], v[178:181], v[114:117]
	v_mfma_f32_16x16x32_bf16 v[102:105], v[82:85], v[202:205], v[102:105]
	v_mfma_f32_16x16x32_bf16 v[98:101], v[90:93], v[202:205], v[98:101]
	v_mfma_f32_16x16x32_bf16 v[150:153], v[86:89], v[166:169], v[150:153]
	v_mfma_f32_16x16x32_bf16 v[146:149], v[94:97], v[166:169], v[146:149]
	v_mfma_f32_16x16x32_bf16 v[134:137], v[86:89], v[174:177], v[134:137]
	v_mfma_f32_16x16x32_bf16 v[130:133], v[94:97], v[174:177], v[130:133]
	v_mfma_f32_16x16x32_bf16 v[118:121], v[86:89], v[182:185], v[118:121]
	v_mfma_f32_16x16x32_bf16 v[114:117], v[94:97], v[182:185], v[114:117]
	v_mfma_f32_16x16x32_bf16 v[102:105], v[86:89], v[206:209], v[102:105]
	v_mfma_f32_16x16x32_bf16 v[98:101], v[94:97], v[206:209], v[98:101]
	s_barrier
	s_add_i32 s60, s75, s63
	v_lshl_add_u64 v[220:221], s[46:47], 0, v[188:189]
	s_mov_b32 m0, s60
	ds_read_b128 v[162:165], v217 offset:16384
	ds_read_b128 v[166:169], v217 offset:17408
	ds_read_b128 v[170:173], v217 offset:18432
	ds_read_b128 v[174:177], v217 offset:19456
	ds_read_b128 v[178:181], v217 offset:20480
	ds_read_b128 v[182:185], v217 offset:21504
	ds_read_b128 v[202:205], v217 offset:22528
	ds_read_b128 v[206:209], v217 offset:23552
	global_load_lds_dwordx4 v[220:221], off
	s_add_i32 m0, s60, 0x2000
	s_add_u32 s60, s46, 0x40000
	v_lshl_add_u64 v[222:223], s[46:47], 0, v[192:193]
	s_addc_u32 s61, s47, 0
	s_add_i32 s82, s76, s63
	global_load_lds_dwordx4 v[222:223], off
	v_lshl_add_u64 v[224:225], s[60:61], 0, v[188:189]
	s_mov_b32 m0, s82
	v_lshl_add_u64 v[226:227], s[48:49], 0, v[190:191]
	global_load_lds_dwordx4 v[224:225], off
	v_lshl_add_u64 v[224:225], s[60:61], 0, v[192:193]
	s_add_i32 m0, s82, 0x2000
	s_nop 0
	global_load_lds_dwordx4 v[224:225], off
	v_lshl_add_u64 v[224:225], s[48:49], 0, v[186:187]
	s_mov_b32 m0, s64
	s_nop 0
	global_load_lds_dwordx4 v[224:225], off
	s_mov_b32 m0, s65
	s_nop 0
	global_load_lds_dwordx4 v[226:227], off
	s_waitcnt vmcnt(8)
	s_waitcnt lgkmcnt(0)
	s_barrier
	s_waitcnt lgkmcnt(0)
	v_mfma_f32_16x16x32_bf16 v[62:65], v[66:69], v[162:165], v[62:65]
	v_mfma_f32_16x16x32_bf16 v[58:61], v[74:77], v[162:165], v[58:61]
	v_mfma_f32_16x16x32_bf16 v[46:49], v[66:69], v[170:173], v[46:49]
	v_mfma_f32_16x16x32_bf16 v[42:45], v[74:77], v[170:173], v[42:45]
	v_mfma_f32_16x16x32_bf16 v[30:33], v[66:69], v[178:181], v[30:33]
	v_mfma_f32_16x16x32_bf16 v[26:29], v[74:77], v[178:181], v[26:29]
	v_mfma_f32_16x16x32_bf16 v[14:17], v[66:69], v[202:205], v[14:17]
	v_mfma_f32_16x16x32_bf16 v[10:13], v[74:77], v[202:205], v[10:13]
	v_mfma_f32_16x16x32_bf16 v[62:65], v[70:73], v[166:169], v[62:65]
	v_mfma_f32_16x16x32_bf16 v[58:61], v[78:81], v[166:169], v[58:61]
	v_mfma_f32_16x16x32_bf16 v[46:49], v[70:73], v[174:177], v[46:49]
	v_mfma_f32_16x16x32_bf16 v[42:45], v[78:81], v[174:177], v[42:45]
	v_mfma_f32_16x16x32_bf16 v[30:33], v[70:73], v[182:185], v[30:33]
	v_mfma_f32_16x16x32_bf16 v[26:29], v[78:81], v[182:185], v[26:29]
	v_mfma_f32_16x16x32_bf16 v[14:17], v[70:73], v[206:209], v[14:17]
	v_mfma_f32_16x16x32_bf16 v[10:13], v[78:81], v[206:209], v[10:13]
	v_mfma_f32_16x16x32_bf16 v[54:57], v[82:85], v[162:165], v[54:57]
	v_mfma_f32_16x16x32_bf16 v[50:53], v[90:93], v[162:165], v[50:53]
	v_mfma_f32_16x16x32_bf16 v[38:41], v[82:85], v[170:173], v[38:41]
	v_mfma_f32_16x16x32_bf16 v[34:37], v[90:93], v[170:173], v[34:37]
	v_mfma_f32_16x16x32_bf16 v[22:25], v[82:85], v[178:181], v[22:25]
	v_mfma_f32_16x16x32_bf16 v[18:21], v[90:93], v[178:181], v[18:21]
	v_mfma_f32_16x16x32_bf16 v[6:9], v[82:85], v[202:205], v[6:9]
	v_mfma_f32_16x16x32_bf16 v[2:5], v[90:93], v[202:205], v[2:5]
	v_mfma_f32_16x16x32_bf16 v[54:57], v[86:89], v[166:169], v[54:57]
	v_mfma_f32_16x16x32_bf16 v[50:53], v[94:97], v[166:169], v[50:53]
	v_mfma_f32_16x16x32_bf16 v[38:41], v[86:89], v[174:177], v[38:41]
	v_mfma_f32_16x16x32_bf16 v[34:37], v[94:97], v[174:177], v[34:37]
	v_mfma_f32_16x16x32_bf16 v[22:25], v[86:89], v[182:185], v[22:25]
	v_mfma_f32_16x16x32_bf16 v[18:21], v[94:97], v[182:185], v[18:21]
	v_mfma_f32_16x16x32_bf16 v[6:9], v[86:89], v[206:209], v[6:9]
	v_mfma_f32_16x16x32_bf16 v[2:5], v[94:97], v[206:209], v[2:5]
	s_barrier
	s_add_i32 s60, 0, 0x18000
	s_add_i32 s61, 0, 0x1c000
	v_add_u32_e32 v78, s60, v213
	v_add_u32_e32 v94, s61, v213
	ds_read_b128 v[66:69], v78
	ds_read_b128 v[70:73], v78 offset:1024
	ds_read_b128 v[74:77], v78 offset:2048
	ds_read_b128 v[78:81], v78 offset:3072
	ds_read_b128 v[82:85], v94
	ds_read_b128 v[86:89], v94 offset:1024
	ds_read_b128 v[90:93], v94 offset:2048
	ds_read_b128 v[94:97], v94 offset:3072
	s_add_u32 s48, s48, 0x40000
	s_addc_u32 s49, s49, 0
	s_mov_b32 m0, s66
	v_lshl_add_u64 v[228:229], s[48:49], 0, v[186:187]
	ds_read_b128 v[162:165], v217 offset:32768
	ds_read_b128 v[166:169], v217 offset:33792
	ds_read_b128 v[170:173], v217 offset:34816
	ds_read_b128 v[174:177], v217 offset:35840
	ds_read_b128 v[178:181], v217 offset:36864
	ds_read_b128 v[182:185], v217 offset:37888
	ds_read_b128 v[202:205], v217 offset:38912
	ds_read_b128 v[206:209], v217 offset:39936
	global_load_lds_dwordx4 v[228:229], off
	v_lshl_add_u64 v[228:229], s[48:49], 0, v[190:191]
	s_mov_b32 m0, s67
	s_nop 0
	global_load_lds_dwordx4 v[228:229], off
	s_waitcnt vmcnt(8)
	s_waitcnt lgkmcnt(0)
	s_barrier
	s_waitcnt lgkmcnt(0)
	v_mfma_f32_16x16x32_bf16 v[158:161], v[66:69], v[162:165], v[158:161]
	v_mfma_f32_16x16x32_bf16 v[154:157], v[74:77], v[162:165], v[154:157]
	v_mfma_f32_16x16x32_bf16 v[142:145], v[66:69], v[170:173], v[142:145]
	v_mfma_f32_16x16x32_bf16 v[138:141], v[74:77], v[170:173], v[138:141]
	v_mfma_f32_16x16x32_bf16 v[126:129], v[66:69], v[178:181], v[126:129]
	v_mfma_f32_16x16x32_bf16 v[122:125], v[74:77], v[178:181], v[122:125]
	v_mfma_f32_16x16x32_bf16 v[110:113], v[66:69], v[202:205], v[110:113]
	v_mfma_f32_16x16x32_bf16 v[106:109], v[74:77], v[202:205], v[106:109]
	v_mfma_f32_16x16x32_bf16 v[158:161], v[70:73], v[166:169], v[158:161]
	v_mfma_f32_16x16x32_bf16 v[154:157], v[78:81], v[166:169], v[154:157]
	v_mfma_f32_16x16x32_bf16 v[142:145], v[70:73], v[174:177], v[142:145]
	v_mfma_f32_16x16x32_bf16 v[138:141], v[78:81], v[174:177], v[138:141]
	v_mfma_f32_16x16x32_bf16 v[126:129], v[70:73], v[182:185], v[126:129]
	v_mfma_f32_16x16x32_bf16 v[122:125], v[78:81], v[182:185], v[122:125]
	v_mfma_f32_16x16x32_bf16 v[110:113], v[70:73], v[206:209], v[110:113]
	v_mfma_f32_16x16x32_bf16 v[106:109], v[78:81], v[206:209], v[106:109]
	v_mfma_f32_16x16x32_bf16 v[150:153], v[82:85], v[162:165], v[150:153]
	v_mfma_f32_16x16x32_bf16 v[146:149], v[90:93], v[162:165], v[146:149]
	v_mfma_f32_16x16x32_bf16 v[134:137], v[82:85], v[170:173], v[134:137]
	v_mfma_f32_16x16x32_bf16 v[130:133], v[90:93], v[170:173], v[130:133]
	v_mfma_f32_16x16x32_bf16 v[118:121], v[82:85], v[178:181], v[118:121]
	v_mfma_f32_16x16x32_bf16 v[114:117], v[90:93], v[178:181], v[114:117]
	v_mfma_f32_16x16x32_bf16 v[102:105], v[82:85], v[202:205], v[102:105]
	v_mfma_f32_16x16x32_bf16 v[98:101], v[90:93], v[202:205], v[98:101]
	v_mfma_f32_16x16x32_bf16 v[150:153], v[86:89], v[166:169], v[150:153]
	v_mfma_f32_16x16x32_bf16 v[146:149], v[94:97], v[166:169], v[146:149]
	v_mfma_f32_16x16x32_bf16 v[134:137], v[86:89], v[174:177], v[134:137]
	v_mfma_f32_16x16x32_bf16 v[130:133], v[94:97], v[174:177], v[130:133]
	v_mfma_f32_16x16x32_bf16 v[118:121], v[86:89], v[182:185], v[118:121]
	v_mfma_f32_16x16x32_bf16 v[114:117], v[94:97], v[182:185], v[114:117]
	v_mfma_f32_16x16x32_bf16 v[102:105], v[86:89], v[206:209], v[102:105]
	v_mfma_f32_16x16x32_bf16 v[98:101], v[94:97], v[206:209], v[98:101]
	s_barrier
	s_add_i32 s48, s60, s63
	v_lshl_add_u64 v[220:221], v[220:221], 0, s[24:25]
	s_mov_b32 m0, s48
	ds_read_b128 v[162:165], v217 offset:49152
	ds_read_b128 v[166:169], v217 offset:50176
	ds_read_b128 v[170:173], v217 offset:51200
	ds_read_b128 v[174:177], v217 offset:52224
	ds_read_b128 v[178:181], v217 offset:53248
	ds_read_b128 v[182:185], v217 offset:54272
	ds_read_b128 v[202:205], v217 offset:55296
	ds_read_b128 v[206:209], v217 offset:56320
	global_load_lds_dwordx4 v[220:221], off
	s_add_i32 m0, s48, 0x2000
	s_add_u32 s46, s46, 0x40080
	v_lshl_add_u64 v[220:221], v[222:223], 0, s[24:25]
	s_addc_u32 s47, s47, 0
	s_add_i32 s48, s61, s63
	global_load_lds_dwordx4 v[220:221], off
	v_lshl_add_u64 v[220:221], s[46:47], 0, v[188:189]
	s_mov_b32 m0, s48
	s_nop 0
	global_load_lds_dwordx4 v[220:221], off
	v_lshl_add_u64 v[220:221], s[46:47], 0, v[192:193]
	s_add_i32 m0, s48, 0x2000
	s_nop 0
	global_load_lds_dwordx4 v[220:221], off
	v_lshl_add_u64 v[220:221], v[224:225], 0, s[24:25]
	s_mov_b32 m0, s72
	s_nop 0
	global_load_lds_dwordx4 v[220:221], off
	v_lshl_add_u64 v[220:221], v[226:227], 0, s[24:25]
	s_mov_b32 m0, s73
	s_nop 0
	global_load_lds_dwordx4 v[220:221], off
	s_waitcnt vmcnt(8)
	s_waitcnt lgkmcnt(0)
	s_barrier
	s_waitcnt lgkmcnt(0)
	v_mfma_f32_16x16x32_bf16 v[62:65], v[66:69], v[162:165], v[62:65]
	v_mfma_f32_16x16x32_bf16 v[58:61], v[74:77], v[162:165], v[58:61]
	v_mfma_f32_16x16x32_bf16 v[46:49], v[66:69], v[170:173], v[46:49]
	v_mfma_f32_16x16x32_bf16 v[42:45], v[74:77], v[170:173], v[42:45]
	v_mfma_f32_16x16x32_bf16 v[30:33], v[66:69], v[178:181], v[30:33]
	v_mfma_f32_16x16x32_bf16 v[26:29], v[74:77], v[178:181], v[26:29]
	v_mfma_f32_16x16x32_bf16 v[14:17], v[66:69], v[202:205], v[14:17]
	v_mfma_f32_16x16x32_bf16 v[10:13], v[74:77], v[202:205], v[10:13]
	v_mfma_f32_16x16x32_bf16 v[62:65], v[70:73], v[166:169], v[62:65]
	v_mfma_f32_16x16x32_bf16 v[58:61], v[78:81], v[166:169], v[58:61]
	v_mfma_f32_16x16x32_bf16 v[46:49], v[70:73], v[174:177], v[46:49]
	v_mfma_f32_16x16x32_bf16 v[42:45], v[78:81], v[174:177], v[42:45]
	v_mfma_f32_16x16x32_bf16 v[30:33], v[70:73], v[182:185], v[30:33]
	v_mfma_f32_16x16x32_bf16 v[26:29], v[78:81], v[182:185], v[26:29]
	v_mfma_f32_16x16x32_bf16 v[14:17], v[70:73], v[206:209], v[14:17]
	v_mfma_f32_16x16x32_bf16 v[10:13], v[78:81], v[206:209], v[10:13]
	v_mfma_f32_16x16x32_bf16 v[54:57], v[82:85], v[162:165], v[54:57]
	v_mfma_f32_16x16x32_bf16 v[50:53], v[90:93], v[162:165], v[50:53]
	v_mfma_f32_16x16x32_bf16 v[38:41], v[82:85], v[170:173], v[38:41]
	v_mfma_f32_16x16x32_bf16 v[34:37], v[90:93], v[170:173], v[34:37]
	v_mfma_f32_16x16x32_bf16 v[22:25], v[82:85], v[178:181], v[22:25]
	v_mfma_f32_16x16x32_bf16 v[18:21], v[90:93], v[178:181], v[18:21]
	v_mfma_f32_16x16x32_bf16 v[6:9], v[82:85], v[202:205], v[6:9]
	v_mfma_f32_16x16x32_bf16 v[2:5], v[90:93], v[202:205], v[2:5]
	v_mfma_f32_16x16x32_bf16 v[54:57], v[86:89], v[166:169], v[54:57]
	v_mfma_f32_16x16x32_bf16 v[50:53], v[94:97], v[166:169], v[50:53]
	v_mfma_f32_16x16x32_bf16 v[38:41], v[86:89], v[174:177], v[38:41]
	v_mfma_f32_16x16x32_bf16 v[34:37], v[94:97], v[174:177], v[34:37]
	v_mfma_f32_16x16x32_bf16 v[22:25], v[86:89], v[182:185], v[22:25]
	v_mfma_f32_16x16x32_bf16 v[18:21], v[94:97], v[182:185], v[18:21]
	v_mfma_f32_16x16x32_bf16 v[6:9], v[86:89], v[206:209], v[6:9]
	v_mfma_f32_16x16x32_bf16 v[2:5], v[94:97], v[206:209], v[2:5]
	s_barrier
	s_add_i32 s81, s81, 2
	s_add_u32 s6, s6, 0x100
	s_addc_u32 s7, s7, 0
	s_add_u32 s79, s79, 0x100
	s_addc_u32 s80, s80, 0
	s_cmp_gt_u32 s81, 13
	s_cbranch_scc0 .LBB0_988
	s_and_b64 vcc, exec, s[28:29]
	s_cbranch_vccz .LBB0_991
	s_barrier

.LBB0_1087:
	ds_read_b128 v[130:133], v165
	ds_read_b128 v[134:137], v165 offset:1024
	ds_read_b128 v[138:141], v165 offset:2048
	ds_read_b128 v[142:145], v165 offset:3072
	ds_read_b128 v[168:171], v166
	ds_read_b128 v[172:175], v166 offset:1024
	ds_read_b128 v[176:179], v166 offset:2048
	ds_read_b128 v[180:183], v166 offset:3072
	s_add_u32 s28, s26, 0xfffc0080
	s_addc_u32 s29, s27, -1
	s_cmp_eq_u32 s69, 12
	s_cselect_b32 s31, s17, s29
	s_cselect_b32 s30, s65, s28
	s_cselect_b32 s29, s15, s68
	s_cselect_b32 s28, s66, s67
	v_lshl_add_u64 v[216:217], s[26:27], 0, v[154:155]
	s_add_i32 m0, s25, 0xc000
	ds_read_b128 v[184:187], v167
	ds_read_b128 v[188:191], v167 offset:1024
	ds_read_b128 v[192:195], v167 offset:2048
	ds_read_b128 v[196:199], v167 offset:3072
	ds_read_b128 v[200:203], v167 offset:4096
	ds_read_b128 v[204:207], v167 offset:5120
	ds_read_b128 v[208:211], v167 offset:6144
	ds_read_b128 v[212:215], v167 offset:7168
	global_load_lds_dwordx4 v[216:217], off
	v_lshl_add_u64 v[216:217], s[26:27], 0, v[156:157]
	s_add_i32 m0, s25, 0xe000
	s_nop 0
	global_load_lds_dwordx4 v[216:217], off
	s_waitcnt vmcnt(8)
	s_waitcnt lgkmcnt(0)
	s_barrier
	s_waitcnt lgkmcnt(0)
	v_mfma_f32_16x16x32_bf16 v[126:129], v[130:133], v[184:187], v[126:129]
	v_mfma_f32_16x16x32_bf16 v[122:125], v[138:141], v[184:187], v[122:125]
	v_mfma_f32_16x16x32_bf16 v[110:113], v[130:133], v[192:195], v[110:113]
	v_mfma_f32_16x16x32_bf16 v[106:109], v[138:141], v[192:195], v[106:109]
	v_mfma_f32_16x16x32_bf16 v[94:97], v[130:133], v[200:203], v[94:97]
	v_mfma_f32_16x16x32_bf16 v[90:93], v[138:141], v[200:203], v[90:93]
	v_mfma_f32_16x16x32_bf16 v[78:81], v[130:133], v[208:211], v[78:81]
	v_mfma_f32_16x16x32_bf16 v[74:77], v[138:141], v[208:211], v[74:77]
	v_mfma_f32_16x16x32_bf16 v[126:129], v[134:137], v[188:191], v[126:129]
	v_mfma_f32_16x16x32_bf16 v[122:125], v[142:145], v[188:191], v[122:125]
	v_mfma_f32_16x16x32_bf16 v[110:113], v[134:137], v[196:199], v[110:113]
	v_mfma_f32_16x16x32_bf16 v[106:109], v[142:145], v[196:199], v[106:109]
	v_mfma_f32_16x16x32_bf16 v[94:97], v[134:137], v[204:207], v[94:97]
	v_mfma_f32_16x16x32_bf16 v[90:93], v[142:145], v[204:207], v[90:93]
	v_mfma_f32_16x16x32_bf16 v[78:81], v[134:137], v[212:215], v[78:81]
	v_mfma_f32_16x16x32_bf16 v[74:77], v[142:145], v[212:215], v[74:77]
	v_mfma_f32_16x16x32_bf16 v[118:121], v[168:171], v[184:187], v[118:121]
	v_mfma_f32_16x16x32_bf16 v[114:117], v[176:179], v[184:187], v[114:117]
	v_mfma_f32_16x16x32_bf16 v[102:105], v[168:171], v[192:195], v[102:105]
	v_mfma_f32_16x16x32_bf16 v[98:101], v[176:179], v[192:195], v[98:101]
	v_mfma_f32_16x16x32_bf16 v[86:89], v[168:171], v[200:203], v[86:89]
	v_mfma_f32_16x16x32_bf16 v[82:85], v[176:179], v[200:203], v[82:85]
	v_mfma_f32_16x16x32_bf16 v[70:73], v[168:171], v[208:211], v[70:73]
	v_mfma_f32_16x16x32_bf16 v[66:69], v[176:179], v[208:211], v[66:69]
	v_mfma_f32_16x16x32_bf16 v[118:121], v[172:175], v[188:191], v[118:121]
	v_mfma_f32_16x16x32_bf16 v[114:117], v[180:183], v[188:191], v[114:117]
	v_mfma_f32_16x16x32_bf16 v[102:105], v[172:175], v[196:199], v[102:105]
	v_mfma_f32_16x16x32_bf16 v[98:101], v[180:183], v[196:199], v[98:101]
	v_mfma_f32_16x16x32_bf16 v[86:89], v[172:175], v[204:207], v[86:89]
	v_mfma_f32_16x16x32_bf16 v[82:85], v[180:183], v[204:207], v[82:85]
	v_mfma_f32_16x16x32_bf16 v[70:73], v[172:175], v[212:215], v[70:73]
	v_mfma_f32_16x16x32_bf16 v[66:69], v[180:183], v[212:215], v[66:69]
	s_barrier
	s_add_i32 s60, s49, s37
	v_lshl_add_u64 v[216:217], s[28:29], 0, v[150:151]
	s_mov_b32 m0, s60
	ds_read_b128 v[184:187], v167 offset:16384
	ds_read_b128 v[188:191], v167 offset:17408
	ds_read_b128 v[192:195], v167 offset:18432
	ds_read_b128 v[196:199], v167 offset:19456
	ds_read_b128 v[200:203], v167 offset:20480
	ds_read_b128 v[204:207], v167 offset:21504
	ds_read_b128 v[208:211], v167 offset:22528
	ds_read_b128 v[212:215], v167 offset:23552
	global_load_lds_dwordx4 v[216:217], off
	s_add_i32 m0, s60, 0x2000
	s_add_u32 s60, s28, 0x40000
	v_lshl_add_u64 v[218:219], s[28:29], 0, v[146:147]
	s_addc_u32 s61, s29, 0
	s_add_i32 s70, s50, s37
	global_load_lds_dwordx4 v[218:219], off
	v_lshl_add_u64 v[220:221], s[60:61], 0, v[150:151]
	s_mov_b32 m0, s70
	v_lshl_add_u64 v[222:223], s[30:31], 0, v[148:149]
	global_load_lds_dwordx4 v[220:221], off
	v_lshl_add_u64 v[220:221], s[60:61], 0, v[146:147]
	s_add_i32 m0, s70, 0x2000
	s_nop 0
	global_load_lds_dwordx4 v[220:221], off
	v_lshl_add_u64 v[220:221], s[30:31], 0, v[152:153]
	s_mov_b32 m0, s25
	s_nop 0
	global_load_lds_dwordx4 v[220:221], off
	s_mov_b32 m0, s43
	s_nop 0
	global_load_lds_dwordx4 v[222:223], off
	s_waitcnt vmcnt(8)
	s_waitcnt lgkmcnt(0)
	s_barrier
	s_waitcnt lgkmcnt(0)
	v_mfma_f32_16x16x32_bf16 v[62:65], v[130:133], v[184:187], v[62:65]
	v_mfma_f32_16x16x32_bf16 v[58:61], v[138:141], v[184:187], v[58:61]
	v_mfma_f32_16x16x32_bf16 v[46:49], v[130:133], v[192:195], v[46:49]
	v_mfma_f32_16x16x32_bf16 v[42:45], v[138:141], v[192:195], v[42:45]
	v_mfma_f32_16x16x32_bf16 v[30:33], v[130:133], v[200:203], v[30:33]
	v_mfma_f32_16x16x32_bf16 v[26:29], v[138:141], v[200:203], v[26:29]
	v_mfma_f32_16x16x32_bf16 v[14:17], v[130:133], v[208:211], v[14:17]
	v_mfma_f32_16x16x32_bf16 v[10:13], v[138:141], v[208:211], v[10:13]
	v_mfma_f32_16x16x32_bf16 v[62:65], v[134:137], v[188:191], v[62:65]
	v_mfma_f32_16x16x32_bf16 v[58:61], v[142:145], v[188:191], v[58:61]
	v_mfma_f32_16x16x32_bf16 v[46:49], v[134:137], v[196:199], v[46:49]
	v_mfma_f32_16x16x32_bf16 v[42:45], v[142:145], v[196:199], v[42:45]
	v_mfma_f32_16x16x32_bf16 v[30:33], v[134:137], v[204:207], v[30:33]
	v_mfma_f32_16x16x32_bf16 v[26:29], v[142:145], v[204:207], v[26:29]
	v_mfma_f32_16x16x32_bf16 v[14:17], v[134:137], v[212:215], v[14:17]
	v_mfma_f32_16x16x32_bf16 v[10:13], v[142:145], v[212:215], v[10:13]
	v_mfma_f32_16x16x32_bf16 v[54:57], v[168:171], v[184:187], v[54:57]
	v_mfma_f32_16x16x32_bf16 v[50:53], v[176:179], v[184:187], v[50:53]
	v_mfma_f32_16x16x32_bf16 v[38:41], v[168:171], v[192:195], v[38:41]
	v_mfma_f32_16x16x32_bf16 v[34:37], v[176:179], v[192:195], v[34:37]
	v_mfma_f32_16x16x32_bf16 v[22:25], v[168:171], v[200:203], v[22:25]
	v_mfma_f32_16x16x32_bf16 v[18:21], v[176:179], v[200:203], v[18:21]
	v_mfma_f32_16x16x32_bf16 v[6:9], v[168:171], v[208:211], v[6:9]
	v_mfma_f32_16x16x32_bf16 v[2:5], v[176:179], v[208:211], v[2:5]
	v_mfma_f32_16x16x32_bf16 v[54:57], v[172:175], v[188:191], v[54:57]
	v_mfma_f32_16x16x32_bf16 v[50:53], v[180:183], v[188:191], v[50:53]
	v_mfma_f32_16x16x32_bf16 v[38:41], v[172:175], v[196:199], v[38:41]
	v_mfma_f32_16x16x32_bf16 v[34:37], v[180:183], v[196:199], v[34:37]
	v_mfma_f32_16x16x32_bf16 v[22:25], v[172:175], v[204:207], v[22:25]
	v_mfma_f32_16x16x32_bf16 v[18:21], v[180:183], v[204:207], v[18:21]
	v_mfma_f32_16x16x32_bf16 v[6:9], v[172:175], v[212:215], v[6:9]
	v_mfma_f32_16x16x32_bf16 v[2:5], v[180:183], v[212:215], v[2:5]
	s_barrier
	s_add_i32 s60, 0, 0x18000
	s_add_i32 s61, 0, 0x1c000
	v_add_u32_e32 v142, s60, v163
	v_add_u32_e32 v180, s61, v163
	ds_read_b128 v[130:133], v142
	ds_read_b128 v[134:137], v142 offset:1024
	ds_read_b128 v[138:141], v142 offset:2048
	ds_read_b128 v[142:145], v142 offset:3072
	ds_read_b128 v[168:171], v180
	ds_read_b128 v[172:175], v180 offset:1024
	ds_read_b128 v[176:179], v180 offset:2048
	ds_read_b128 v[180:183], v180 offset:3072
	s_add_u32 s30, s30, 0x40000
	s_addc_u32 s31, s31, 0
	s_mov_b32 m0, s44
	v_lshl_add_u64 v[224:225], s[30:31], 0, v[152:153]
	ds_read_b128 v[184:187], v167 offset:32768
	ds_read_b128 v[188:191], v167 offset:33792
	ds_read_b128 v[192:195], v167 offset:34816
	ds_read_b128 v[196:199], v167 offset:35840
	ds_read_b128 v[200:203], v167 offset:36864
	ds_read_b128 v[204:207], v167 offset:37888
	ds_read_b128 v[208:211], v167 offset:38912
	ds_read_b128 v[212:215], v167 offset:39936
	global_load_lds_dwordx4 v[224:225], off
	v_lshl_add_u64 v[224:225], s[30:31], 0, v[148:149]
	s_mov_b32 m0, s45
	s_nop 0
	global_load_lds_dwordx4 v[224:225], off
	s_waitcnt vmcnt(8)
	s_waitcnt lgkmcnt(0)
	s_barrier
	s_waitcnt lgkmcnt(0)
	v_mfma_f32_16x16x32_bf16 v[126:129], v[130:133], v[184:187], v[126:129]
	v_mfma_f32_16x16x32_bf16 v[122:125], v[138:141], v[184:187], v[122:125]
	v_mfma_f32_16x16x32_bf16 v[110:113], v[130:133], v[192:195], v[110:113]
	v_mfma_f32_16x16x32_bf16 v[106:109], v[138:141], v[192:195], v[106:109]
	v_mfma_f32_16x16x32_bf16 v[94:97], v[130:133], v[200:203], v[94:97]
	v_mfma_f32_16x16x32_bf16 v[90:93], v[138:141], v[200:203], v[90:93]
	v_mfma_f32_16x16x32_bf16 v[78:81], v[130:133], v[208:211], v[78:81]
	v_mfma_f32_16x16x32_bf16 v[74:77], v[138:141], v[208:211], v[74:77]
	v_mfma_f32_16x16x32_bf16 v[126:129], v[134:137], v[188:191], v[126:129]
	v_mfma_f32_16x16x32_bf16 v[122:125], v[142:145], v[188:191], v[122:125]
	v_mfma_f32_16x16x32_bf16 v[110:113], v[134:137], v[196:199], v[110:113]
	v_mfma_f32_16x16x32_bf16 v[106:109], v[142:145], v[196:199], v[106:109]
	v_mfma_f32_16x16x32_bf16 v[94:97], v[134:137], v[204:207], v[94:97]
	v_mfma_f32_16x16x32_bf16 v[90:93], v[142:145], v[204:207], v[90:93]
	v_mfma_f32_16x16x32_bf16 v[78:81], v[134:137], v[212:215], v[78:81]
	v_mfma_f32_16x16x32_bf16 v[74:77], v[142:145], v[212:215], v[74:77]
	v_mfma_f32_16x16x32_bf16 v[118:121], v[168:171], v[184:187], v[118:121]
	v_mfma_f32_16x16x32_bf16 v[114:117], v[176:179], v[184:187], v[114:117]
	v_mfma_f32_16x16x32_bf16 v[102:105], v[168:171], v[192:195], v[102:105]
	v_mfma_f32_16x16x32_bf16 v[98:101], v[176:179], v[192:195], v[98:101]
	v_mfma_f32_16x16x32_bf16 v[86:89], v[168:171], v[200:203], v[86:89]
	v_mfma_f32_16x16x32_bf16 v[82:85], v[176:179], v[200:203], v[82:85]
	v_mfma_f32_16x16x32_bf16 v[70:73], v[168:171], v[208:211], v[70:73]
	v_mfma_f32_16x16x32_bf16 v[66:69], v[176:179], v[208:211], v[66:69]
	v_mfma_f32_16x16x32_bf16 v[118:121], v[172:175], v[188:191], v[118:121]
	v_mfma_f32_16x16x32_bf16 v[114:117], v[180:183], v[188:191], v[114:117]
	v_mfma_f32_16x16x32_bf16 v[102:105], v[172:175], v[196:199], v[102:105]
	v_mfma_f32_16x16x32_bf16 v[98:101], v[180:183], v[196:199], v[98:101]
	v_mfma_f32_16x16x32_bf16 v[86:89], v[172:175], v[204:207], v[86:89]
	v_mfma_f32_16x16x32_bf16 v[82:85], v[180:183], v[204:207], v[82:85]
	v_mfma_f32_16x16x32_bf16 v[70:73], v[172:175], v[212:215], v[70:73]
	v_mfma_f32_16x16x32_bf16 v[66:69], v[180:183], v[212:215], v[66:69]
	s_barrier
	s_add_i32 s30, s60, s37
	v_lshl_add_u64 v[216:217], v[216:217], 0, s[10:11]
	s_mov_b32 m0, s30
	ds_read_b128 v[184:187], v167 offset:49152
	ds_read_b128 v[188:191], v167 offset:50176
	ds_read_b128 v[192:195], v167 offset:51200
	ds_read_b128 v[196:199], v167 offset:52224
	ds_read_b128 v[200:203], v167 offset:53248
	ds_read_b128 v[204:207], v167 offset:54272
	ds_read_b128 v[208:211], v167 offset:55296
	ds_read_b128 v[212:215], v167 offset:56320
	global_load_lds_dwordx4 v[216:217], off
	s_add_i32 m0, s30, 0x2000
	s_add_u32 s28, s28, 0x40080
	v_lshl_add_u64 v[216:217], v[218:219], 0, s[10:11]
	s_addc_u32 s29, s29, 0
	s_add_i32 s30, s61, s37
	global_load_lds_dwordx4 v[216:217], off
	v_lshl_add_u64 v[216:217], s[28:29], 0, v[150:151]
	s_mov_b32 m0, s30
	s_nop 0
	global_load_lds_dwordx4 v[216:217], off
	v_lshl_add_u64 v[216:217], s[28:29], 0, v[146:147]
	s_add_i32 m0, s30, 0x2000
	s_nop 0
	global_load_lds_dwordx4 v[216:217], off
	v_lshl_add_u64 v[216:217], v[220:221], 0, s[10:11]
	s_mov_b32 m0, s47
	s_nop 0
	global_load_lds_dwordx4 v[216:217], off
	v_lshl_add_u64 v[216:217], v[222:223], 0, s[10:11]
	s_mov_b32 m0, s48
	s_nop 0
	global_load_lds_dwordx4 v[216:217], off
	s_waitcnt vmcnt(8)
	s_waitcnt lgkmcnt(0)
	s_barrier
	s_waitcnt lgkmcnt(0)
	v_mfma_f32_16x16x32_bf16 v[62:65], v[130:133], v[184:187], v[62:65]
	v_mfma_f32_16x16x32_bf16 v[58:61], v[138:141], v[184:187], v[58:61]
	v_mfma_f32_16x16x32_bf16 v[46:49], v[130:133], v[192:195], v[46:49]
	v_mfma_f32_16x16x32_bf16 v[42:45], v[138:141], v[192:195], v[42:45]
	v_mfma_f32_16x16x32_bf16 v[30:33], v[130:133], v[200:203], v[30:33]
	v_mfma_f32_16x16x32_bf16 v[26:29], v[138:141], v[200:203], v[26:29]
	v_mfma_f32_16x16x32_bf16 v[14:17], v[130:133], v[208:211], v[14:17]
	v_mfma_f32_16x16x32_bf16 v[10:13], v[138:141], v[208:211], v[10:13]
	v_mfma_f32_16x16x32_bf16 v[62:65], v[134:137], v[188:191], v[62:65]
	v_mfma_f32_16x16x32_bf16 v[58:61], v[142:145], v[188:191], v[58:61]
	v_mfma_f32_16x16x32_bf16 v[46:49], v[134:137], v[196:199], v[46:49]
	v_mfma_f32_16x16x32_bf16 v[42:45], v[142:145], v[196:199], v[42:45]
	v_mfma_f32_16x16x32_bf16 v[30:33], v[134:137], v[204:207], v[30:33]
	v_mfma_f32_16x16x32_bf16 v[26:29], v[142:145], v[204:207], v[26:29]
	v_mfma_f32_16x16x32_bf16 v[14:17], v[134:137], v[212:215], v[14:17]
	v_mfma_f32_16x16x32_bf16 v[10:13], v[142:145], v[212:215], v[10:13]
	v_mfma_f32_16x16x32_bf16 v[54:57], v[168:171], v[184:187], v[54:57]
	v_mfma_f32_16x16x32_bf16 v[50:53], v[176:179], v[184:187], v[50:53]
	v_mfma_f32_16x16x32_bf16 v[38:41], v[168:171], v[192:195], v[38:41]
	v_mfma_f32_16x16x32_bf16 v[34:37], v[176:179], v[192:195], v[34:37]
	v_mfma_f32_16x16x32_bf16 v[22:25], v[168:171], v[200:203], v[22:25]
	v_mfma_f32_16x16x32_bf16 v[18:21], v[176:179], v[200:203], v[18:21]
	v_mfma_f32_16x16x32_bf16 v[6:9], v[168:171], v[208:211], v[6:9]
	v_mfma_f32_16x16x32_bf16 v[2:5], v[176:179], v[208:211], v[2:5]
	v_mfma_f32_16x16x32_bf16 v[54:57], v[172:175], v[188:191], v[54:57]
	v_mfma_f32_16x16x32_bf16 v[50:53], v[180:183], v[188:191], v[50:53]
	v_mfma_f32_16x16x32_bf16 v[38:41], v[172:175], v[196:199], v[38:41]
	v_mfma_f32_16x16x32_bf16 v[34:37], v[180:183], v[196:199], v[34:37]
	v_mfma_f32_16x16x32_bf16 v[22:25], v[172:175], v[204:207], v[22:25]
	v_mfma_f32_16x16x32_bf16 v[18:21], v[180:183], v[204:207], v[18:21]
	v_mfma_f32_16x16x32_bf16 v[6:9], v[172:175], v[212:215], v[6:9]
	v_mfma_f32_16x16x32_bf16 v[2:5], v[180:183], v[212:215], v[2:5]
	s_barrier
	s_add_i32 s69, s69, 2
	s_add_u32 s26, s26, 0x100
	s_addc_u32 s27, s27, 0
	s_add_u32 s67, s67, 0x100
	s_addc_u32 s68, s68, 0
	s_cmp_gt_u32 s69, 13
	s_cbranch_scc0 .LBB0_1087
	s_and_b64 vcc, exec, s[12:13]
	s_cbranch_vccz .LBB0_1090
	s_barrier

.LBB0_1168:
	ds_read_b128 v[104:107], v201
	ds_read_b128 v[108:111], v201 offset:1024
	ds_read_b128 v[116:119], v201 offset:2048
	ds_read_b128 v[124:127], v201 offset:3072
	ds_read_b128 v[162:165], v202
	ds_read_b128 v[166:169], v202 offset:1024
	ds_read_b128 v[170:173], v202 offset:2048
	ds_read_b128 v[174:177], v202 offset:3072
	s_add_u32 s28, s26, 0xfff50080
	s_addc_u32 s29, s27, -1
	s_cmp_eq_u32 s59, 40
	s_cselect_b32 s31, s11, s29
	s_cselect_b32 s30, s10, s28
	s_cselect_b32 s29, s19, s25
	s_cselect_b32 s28, s18, s23
	v_lshl_add_u64 v[244:245], s[26:27], 0, v[154:155]
	s_add_i32 m0, s38, 0xc000
	ds_read_b128 v[178:181], v203
	ds_read_b128 v[216:219], v203 offset:1024
	ds_read_b128 v[220:223], v203 offset:2048
	ds_read_b128 v[224:227], v203 offset:3072
	ds_read_b128 v[228:231], v203 offset:4096
	ds_read_b128 v[232:235], v203 offset:5120
	ds_read_b128 v[236:239], v203 offset:6144
	ds_read_b128 v[240:243], v203 offset:7168
	global_load_lds_dwordx4 v[244:245], off
	v_lshl_add_u64 v[244:245], s[26:27], 0, v[156:157]
	s_add_i32 m0, s38, 0xe000
	s_nop 0
	global_load_lds_dwordx4 v[244:245], off
	s_waitcnt vmcnt(8)
	s_waitcnt lgkmcnt(0)
	s_barrier
	s_waitcnt lgkmcnt(0)
	v_mfma_f32_16x16x32_bf16 v[140:143], v[104:107], v[178:181], v[140:143]
	v_mfma_f32_16x16x32_bf16 v[136:139], v[116:119], v[178:181], v[136:139]
	v_mfma_f32_16x16x32_bf16 v[120:123], v[104:107], v[220:223], v[120:123]
	v_mfma_f32_16x16x32_bf16 v[112:115], v[116:119], v[220:223], v[112:115]
	v_mfma_f32_16x16x32_bf16 v[92:95], v[104:107], v[228:231], v[92:95]
	v_mfma_f32_16x16x32_bf16 v[88:91], v[116:119], v[228:231], v[88:91]
	v_mfma_f32_16x16x32_bf16 v[76:79], v[104:107], v[236:239], v[76:79]
	v_mfma_f32_16x16x32_bf16 v[72:75], v[116:119], v[236:239], v[72:75]
	v_mfma_f32_16x16x32_bf16 v[140:143], v[108:111], v[216:219], v[140:143]
	v_mfma_f32_16x16x32_bf16 v[136:139], v[124:127], v[216:219], v[136:139]
	v_mfma_f32_16x16x32_bf16 v[120:123], v[108:111], v[224:227], v[120:123]
	v_mfma_f32_16x16x32_bf16 v[112:115], v[124:127], v[224:227], v[112:115]
	v_mfma_f32_16x16x32_bf16 v[92:95], v[108:111], v[232:235], v[92:95]
	v_mfma_f32_16x16x32_bf16 v[88:91], v[124:127], v[232:235], v[88:91]
	v_mfma_f32_16x16x32_bf16 v[76:79], v[108:111], v[240:243], v[76:79]
	v_mfma_f32_16x16x32_bf16 v[72:75], v[124:127], v[240:243], v[72:75]
	v_mfma_f32_16x16x32_bf16 v[132:135], v[162:165], v[178:181], v[132:135]
	v_mfma_f32_16x16x32_bf16 v[128:131], v[170:173], v[178:181], v[128:131]
	v_mfma_f32_16x16x32_bf16 v[100:103], v[162:165], v[220:223], v[100:103]
	v_mfma_f32_16x16x32_bf16 v[96:99], v[170:173], v[220:223], v[96:99]
	v_mfma_f32_16x16x32_bf16 v[84:87], v[162:165], v[228:231], v[84:87]
	v_mfma_f32_16x16x32_bf16 v[80:83], v[170:173], v[228:231], v[80:83]
	v_mfma_f32_16x16x32_bf16 v[68:71], v[162:165], v[236:239], v[68:71]
	v_mfma_f32_16x16x32_bf16 v[64:67], v[170:173], v[236:239], v[64:67]
	v_mfma_f32_16x16x32_bf16 v[132:135], v[166:169], v[216:219], v[132:135]
	v_mfma_f32_16x16x32_bf16 v[128:131], v[174:177], v[216:219], v[128:131]
	v_mfma_f32_16x16x32_bf16 v[100:103], v[166:169], v[224:227], v[100:103]
	v_mfma_f32_16x16x32_bf16 v[96:99], v[174:177], v[224:227], v[96:99]
	v_mfma_f32_16x16x32_bf16 v[84:87], v[166:169], v[232:235], v[84:87]
	v_mfma_f32_16x16x32_bf16 v[80:83], v[174:177], v[232:235], v[80:83]
	v_mfma_f32_16x16x32_bf16 v[68:71], v[166:169], v[240:243], v[68:71]
	v_mfma_f32_16x16x32_bf16 v[64:67], v[174:177], v[240:243], v[64:67]
	s_barrier
	s_add_i32 s60, s51, s37
	v_lshl_add_u64 v[244:245], s[28:29], 0, v[146:147]
	s_mov_b32 m0, s60
	ds_read_b128 v[178:181], v203 offset:16384
	ds_read_b128 v[216:219], v203 offset:17408
	ds_read_b128 v[220:223], v203 offset:18432
	ds_read_b128 v[224:227], v203 offset:19456
	ds_read_b128 v[228:231], v203 offset:20480
	ds_read_b128 v[232:235], v203 offset:21504
	ds_read_b128 v[236:239], v203 offset:22528
	ds_read_b128 v[240:243], v203 offset:23552
	global_load_lds_dwordx4 v[244:245], off
	s_add_i32 m0, s60, 0x2000
	s_add_u32 s60, s28, 0xb0000
	v_lshl_add_u64 v[246:247], s[28:29], 0, v[150:151]
	s_addc_u32 s61, s29, 0
	s_add_i32 s62, s56, s37
	global_load_lds_dwordx4 v[246:247], off
	v_lshl_add_u64 v[248:249], s[60:61], 0, v[146:147]
	s_mov_b32 m0, s62
	v_lshl_add_u64 v[250:251], s[30:31], 0, v[148:149]
	global_load_lds_dwordx4 v[248:249], off
	v_lshl_add_u64 v[248:249], s[60:61], 0, v[150:151]
	s_add_i32 m0, s62, 0x2000
	s_nop 0
	global_load_lds_dwordx4 v[248:249], off
	v_lshl_add_u64 v[248:249], s[30:31], 0, v[144:145]
	s_mov_b32 m0, s38
	s_nop 0
	global_load_lds_dwordx4 v[248:249], off
	s_mov_b32 m0, s39
	s_nop 0
	global_load_lds_dwordx4 v[250:251], off
	s_waitcnt vmcnt(8)
	s_waitcnt lgkmcnt(0)
	s_barrier
	s_waitcnt lgkmcnt(0)
	v_mfma_f32_16x16x32_bf16 v[60:63], v[104:107], v[178:181], v[60:63]
	v_mfma_f32_16x16x32_bf16 v[56:59], v[116:119], v[178:181], v[56:59]
	v_mfma_f32_16x16x32_bf16 v[44:47], v[104:107], v[220:223], v[44:47]
	v_mfma_f32_16x16x32_bf16 v[40:43], v[116:119], v[220:223], v[40:43]
	v_mfma_f32_16x16x32_bf16 v[28:31], v[104:107], v[228:231], v[28:31]
	v_mfma_f32_16x16x32_bf16 v[24:27], v[116:119], v[228:231], v[24:27]
	v_mfma_f32_16x16x32_bf16 v[12:15], v[104:107], v[236:239], v[12:15]
	v_mfma_f32_16x16x32_bf16 v[8:11], v[116:119], v[236:239], v[8:11]
	v_mfma_f32_16x16x32_bf16 v[60:63], v[108:111], v[216:219], v[60:63]
	v_mfma_f32_16x16x32_bf16 v[56:59], v[124:127], v[216:219], v[56:59]
	v_mfma_f32_16x16x32_bf16 v[44:47], v[108:111], v[224:227], v[44:47]
	v_mfma_f32_16x16x32_bf16 v[40:43], v[124:127], v[224:227], v[40:43]
	v_mfma_f32_16x16x32_bf16 v[28:31], v[108:111], v[232:235], v[28:31]
	v_mfma_f32_16x16x32_bf16 v[24:27], v[124:127], v[232:235], v[24:27]
	v_mfma_f32_16x16x32_bf16 v[12:15], v[108:111], v[240:243], v[12:15]
	v_mfma_f32_16x16x32_bf16 v[8:11], v[124:127], v[240:243], v[8:11]
	v_mfma_f32_16x16x32_bf16 v[52:55], v[162:165], v[178:181], v[52:55]
	v_mfma_f32_16x16x32_bf16 v[48:51], v[170:173], v[178:181], v[48:51]
	v_mfma_f32_16x16x32_bf16 v[36:39], v[162:165], v[220:223], v[36:39]
	v_mfma_f32_16x16x32_bf16 v[32:35], v[170:173], v[220:223], v[32:35]
	v_mfma_f32_16x16x32_bf16 v[20:23], v[162:165], v[228:231], v[20:23]
	v_mfma_f32_16x16x32_bf16 v[16:19], v[170:173], v[228:231], v[16:19]
	v_mfma_f32_16x16x32_bf16 v[4:7], v[162:165], v[236:239], v[4:7]
	v_mfma_f32_16x16x32_bf16 v[0:3], v[170:173], v[236:239], v[0:3]
	v_mfma_f32_16x16x32_bf16 v[52:55], v[166:169], v[216:219], v[52:55]
	v_mfma_f32_16x16x32_bf16 v[48:51], v[174:177], v[216:219], v[48:51]
	v_mfma_f32_16x16x32_bf16 v[36:39], v[166:169], v[224:227], v[36:39]
	v_mfma_f32_16x16x32_bf16 v[32:35], v[174:177], v[224:227], v[32:35]
	v_mfma_f32_16x16x32_bf16 v[20:23], v[166:169], v[232:235], v[20:23]
	v_mfma_f32_16x16x32_bf16 v[16:19], v[174:177], v[232:235], v[16:19]
	v_mfma_f32_16x16x32_bf16 v[4:7], v[166:169], v[240:243], v[4:7]
	v_mfma_f32_16x16x32_bf16 v[0:3], v[174:177], v[240:243], v[0:3]
	s_barrier
	s_add_i32 s60, 0, 0x18000
	s_add_i32 s61, 0, 0x1c000
	v_add_u32_e32 v124, s60, v183
	v_add_u32_e32 v174, s61, v183
	ds_read_b128 v[104:107], v124
	ds_read_b128 v[108:111], v124 offset:1024
	ds_read_b128 v[116:119], v124 offset:2048
	ds_read_b128 v[124:127], v124 offset:3072
	ds_read_b128 v[162:165], v174
	ds_read_b128 v[166:169], v174 offset:1024
	ds_read_b128 v[170:173], v174 offset:2048
	ds_read_b128 v[174:177], v174 offset:3072
	s_add_u32 s30, s30, 0xb0000
	s_addc_u32 s31, s31, 0
	s_mov_b32 m0, s40
	v_lshl_add_u64 v[252:253], s[30:31], 0, v[144:145]
	ds_read_b128 v[178:181], v203 offset:32768
	ds_read_b128 v[216:219], v203 offset:33792
	ds_read_b128 v[220:223], v203 offset:34816
	ds_read_b128 v[224:227], v203 offset:35840
	ds_read_b128 v[228:231], v203 offset:36864
	ds_read_b128 v[232:235], v203 offset:37888
	ds_read_b128 v[236:239], v203 offset:38912
	ds_read_b128 v[240:243], v203 offset:39936
	global_load_lds_dwordx4 v[252:253], off
	v_lshl_add_u64 v[252:253], s[30:31], 0, v[148:149]
	s_mov_b32 m0, s41
	s_nop 0
	global_load_lds_dwordx4 v[252:253], off
	s_waitcnt vmcnt(8)
	s_waitcnt lgkmcnt(0)
	s_barrier
	s_waitcnt lgkmcnt(0)
	v_mfma_f32_16x16x32_bf16 v[140:143], v[104:107], v[178:181], v[140:143]
	v_mfma_f32_16x16x32_bf16 v[136:139], v[116:119], v[178:181], v[136:139]
	v_mfma_f32_16x16x32_bf16 v[120:123], v[104:107], v[220:223], v[120:123]
	v_mfma_f32_16x16x32_bf16 v[112:115], v[116:119], v[220:223], v[112:115]
	v_mfma_f32_16x16x32_bf16 v[92:95], v[104:107], v[228:231], v[92:95]
	v_mfma_f32_16x16x32_bf16 v[88:91], v[116:119], v[228:231], v[88:91]
	v_mfma_f32_16x16x32_bf16 v[76:79], v[104:107], v[236:239], v[76:79]
	v_mfma_f32_16x16x32_bf16 v[72:75], v[116:119], v[236:239], v[72:75]
	v_mfma_f32_16x16x32_bf16 v[140:143], v[108:111], v[216:219], v[140:143]
	v_mfma_f32_16x16x32_bf16 v[136:139], v[124:127], v[216:219], v[136:139]
	v_mfma_f32_16x16x32_bf16 v[120:123], v[108:111], v[224:227], v[120:123]
	v_mfma_f32_16x16x32_bf16 v[112:115], v[124:127], v[224:227], v[112:115]
	v_mfma_f32_16x16x32_bf16 v[92:95], v[108:111], v[232:235], v[92:95]
	v_mfma_f32_16x16x32_bf16 v[88:91], v[124:127], v[232:235], v[88:91]
	v_mfma_f32_16x16x32_bf16 v[76:79], v[108:111], v[240:243], v[76:79]
	v_mfma_f32_16x16x32_bf16 v[72:75], v[124:127], v[240:243], v[72:75]
	v_mfma_f32_16x16x32_bf16 v[132:135], v[162:165], v[178:181], v[132:135]
	v_mfma_f32_16x16x32_bf16 v[128:131], v[170:173], v[178:181], v[128:131]
	v_mfma_f32_16x16x32_bf16 v[100:103], v[162:165], v[220:223], v[100:103]
	v_mfma_f32_16x16x32_bf16 v[96:99], v[170:173], v[220:223], v[96:99]
	v_mfma_f32_16x16x32_bf16 v[84:87], v[162:165], v[228:231], v[84:87]
	v_mfma_f32_16x16x32_bf16 v[80:83], v[170:173], v[228:231], v[80:83]
	v_mfma_f32_16x16x32_bf16 v[68:71], v[162:165], v[236:239], v[68:71]
	v_mfma_f32_16x16x32_bf16 v[64:67], v[170:173], v[236:239], v[64:67]
	v_mfma_f32_16x16x32_bf16 v[132:135], v[166:169], v[216:219], v[132:135]
	v_mfma_f32_16x16x32_bf16 v[128:131], v[174:177], v[216:219], v[128:131]
	v_mfma_f32_16x16x32_bf16 v[100:103], v[166:169], v[224:227], v[100:103]
	v_mfma_f32_16x16x32_bf16 v[96:99], v[174:177], v[224:227], v[96:99]
	v_mfma_f32_16x16x32_bf16 v[84:87], v[166:169], v[232:235], v[84:87]
	v_mfma_f32_16x16x32_bf16 v[80:83], v[174:177], v[232:235], v[80:83]
	v_mfma_f32_16x16x32_bf16 v[68:71], v[166:169], v[240:243], v[68:71]
	v_mfma_f32_16x16x32_bf16 v[64:67], v[174:177], v[240:243], v[64:67]
	s_barrier
	s_add_i32 s30, s60, s37
	v_lshl_add_u64 v[244:245], v[244:245], 0, s[14:15]
	s_mov_b32 m0, s30
	ds_read_b128 v[178:181], v203 offset:49152
	ds_read_b128 v[216:219], v203 offset:50176
	ds_read_b128 v[220:223], v203 offset:51200
	ds_read_b128 v[224:227], v203 offset:52224
	ds_read_b128 v[228:231], v203 offset:53248
	ds_read_b128 v[232:235], v203 offset:54272
	ds_read_b128 v[236:239], v203 offset:55296
	ds_read_b128 v[240:243], v203 offset:56320
	global_load_lds_dwordx4 v[244:245], off
	s_add_i32 m0, s30, 0x2000
	s_add_u32 s28, s28, 0xb0080
	v_lshl_add_u64 v[244:245], v[246:247], 0, s[14:15]
	s_addc_u32 s29, s29, 0
	s_add_i32 s30, s61, s37
	global_load_lds_dwordx4 v[244:245], off
	v_lshl_add_u64 v[244:245], s[28:29], 0, v[146:147]
	s_mov_b32 m0, s30
	s_nop 0
	global_load_lds_dwordx4 v[244:245], off
	v_lshl_add_u64 v[244:245], s[28:29], 0, v[150:151]
	s_add_i32 m0, s30, 0x2000
	s_nop 0
	global_load_lds_dwordx4 v[244:245], off
	v_lshl_add_u64 v[244:245], v[248:249], 0, s[14:15]
	s_mov_b32 m0, s48
	s_nop 0
	global_load_lds_dwordx4 v[244:245], off
	v_lshl_add_u64 v[244:245], v[250:251], 0, s[14:15]
	s_mov_b32 m0, s49
	s_nop 0
	global_load_lds_dwordx4 v[244:245], off
	s_waitcnt vmcnt(8)
	s_waitcnt lgkmcnt(0)
	s_barrier
	s_waitcnt lgkmcnt(0)
	v_mfma_f32_16x16x32_bf16 v[60:63], v[104:107], v[178:181], v[60:63]
	v_mfma_f32_16x16x32_bf16 v[56:59], v[116:119], v[178:181], v[56:59]
	v_mfma_f32_16x16x32_bf16 v[44:47], v[104:107], v[220:223], v[44:47]
	v_mfma_f32_16x16x32_bf16 v[40:43], v[116:119], v[220:223], v[40:43]
	v_mfma_f32_16x16x32_bf16 v[28:31], v[104:107], v[228:231], v[28:31]
	v_mfma_f32_16x16x32_bf16 v[24:27], v[116:119], v[228:231], v[24:27]
	v_mfma_f32_16x16x32_bf16 v[12:15], v[104:107], v[236:239], v[12:15]
	v_mfma_f32_16x16x32_bf16 v[8:11], v[116:119], v[236:239], v[8:11]
	v_mfma_f32_16x16x32_bf16 v[60:63], v[108:111], v[216:219], v[60:63]
	v_mfma_f32_16x16x32_bf16 v[56:59], v[124:127], v[216:219], v[56:59]
	v_mfma_f32_16x16x32_bf16 v[44:47], v[108:111], v[224:227], v[44:47]
	v_mfma_f32_16x16x32_bf16 v[40:43], v[124:127], v[224:227], v[40:43]
	v_mfma_f32_16x16x32_bf16 v[28:31], v[108:111], v[232:235], v[28:31]
	v_mfma_f32_16x16x32_bf16 v[24:27], v[124:127], v[232:235], v[24:27]
	v_mfma_f32_16x16x32_bf16 v[12:15], v[108:111], v[240:243], v[12:15]
	v_mfma_f32_16x16x32_bf16 v[8:11], v[124:127], v[240:243], v[8:11]
	v_mfma_f32_16x16x32_bf16 v[52:55], v[162:165], v[178:181], v[52:55]
	v_mfma_f32_16x16x32_bf16 v[48:51], v[170:173], v[178:181], v[48:51]
	v_mfma_f32_16x16x32_bf16 v[36:39], v[162:165], v[220:223], v[36:39]
	v_mfma_f32_16x16x32_bf16 v[32:35], v[170:173], v[220:223], v[32:35]
	v_mfma_f32_16x16x32_bf16 v[20:23], v[162:165], v[228:231], v[20:23]
	v_mfma_f32_16x16x32_bf16 v[16:19], v[170:173], v[228:231], v[16:19]
	v_mfma_f32_16x16x32_bf16 v[4:7], v[162:165], v[236:239], v[4:7]
	v_mfma_f32_16x16x32_bf16 v[0:3], v[170:173], v[236:239], v[0:3]
	v_mfma_f32_16x16x32_bf16 v[52:55], v[166:169], v[216:219], v[52:55]
	v_mfma_f32_16x16x32_bf16 v[48:51], v[174:177], v[216:219], v[48:51]
	v_mfma_f32_16x16x32_bf16 v[36:39], v[166:169], v[224:227], v[36:39]
	v_mfma_f32_16x16x32_bf16 v[32:35], v[174:177], v[224:227], v[32:35]
	v_mfma_f32_16x16x32_bf16 v[20:23], v[166:169], v[232:235], v[20:23]
	v_mfma_f32_16x16x32_bf16 v[16:19], v[174:177], v[232:235], v[16:19]
	v_mfma_f32_16x16x32_bf16 v[4:7], v[166:169], v[240:243], v[4:7]
	v_mfma_f32_16x16x32_bf16 v[0:3], v[174:177], v[240:243], v[0:3]
	s_barrier
	s_add_i32 s59, s59, 2
	s_add_u32 s26, s26, 0x100
	s_addc_u32 s27, s27, 0
	s_add_u32 s23, s23, 0x100
	s_addc_u32 s25, s25, 0
	s_cmp_gt_u32 s59, 41
	s_cbranch_scc0 .LBB0_1168
	s_and_b64 vcc, exec, s[16:17]
	s_cbranch_vccz .LBB0_1171
	s_barrier
